# stack of neutral edits plus one static priority raise for the leading wave half in the K-loops
# speedup vs baseline: 1.0023x; 1.0023x over previous
.LBB0_165:
	s_add_u32 s16, s14, 0xfff80080
	s_addc_u32 s17, s15, -1
	s_cmp_eq_u32 s64, 28
	s_cselect_b32 s19, s1, s17
	s_cselect_b32 s18, s4, s16
	s_cselect_b32 s17, s11, s21
	s_cselect_b32 s16, s13, s20
	s_and_b64 vcc, exec, s[36:37]
	s_cbranch_vccz .Lk64_trail_p1
	s_setprio 1
	s_sub_u32 vcc_lo, s20, 0x80
	s_subb_u32 vcc_hi, s21, 0
	s_add_i32 m0, s23, 0x18000
	s_nop 0
	global_load_lds_dwordx4 v130, vcc
	s_add_i32 m0, s23, 0x1a000
	s_nop 0
	global_load_lds_dwordx4 v134, vcc
	s_add_u32 vcc_lo, vcc_lo, 0x20000
	s_addc_u32 vcc_hi, vcc_hi, 0
	s_add_i32 m0, s23, 0x19000
	s_nop 0
	global_load_lds_dwordx4 v130, vcc
	s_add_i32 m0, s23, 0x1b000
	s_nop 0
	global_load_lds_dwordx4 v134, vcc
	s_add_u32 vcc_lo, vcc_lo, 0x60000
	s_addc_u32 vcc_hi, vcc_hi, 0
	s_add_i32 m0, s23, 0x1c000
	s_nop 0
	global_load_lds_dwordx4 v130, vcc
	s_add_i32 m0, s23, 0x1e000
	s_nop 0
	global_load_lds_dwordx4 v134, vcc
	s_add_u32 vcc_lo, vcc_lo, 0x20000
	s_addc_u32 vcc_hi, vcc_hi, 0
	s_add_i32 m0, s23, 0x1d000
	s_nop 0
	global_load_lds_dwordx4 v130, vcc
	s_add_i32 m0, s23, 0x1f000
	s_nop 0
	global_load_lds_dwordx4 v134, vcc
	ds_read_b128 v[148:151], v168 offset:0
	ds_read_b128 v[152:155], v168 offset:1024
	ds_read_b128 v[156:159], v168 offset:2048
	ds_read_b128 v[172:175], v168 offset:3072
	ds_read_b128 v[176:179], v169 offset:0
	ds_read_b128 v[180:183], v169 offset:1024
	ds_read_b128 v[184:187], v169 offset:2048
	ds_read_b128 v[188:191], v169 offset:3072
	ds_read_b128 v[192:195], v170 offset:0
	ds_read_b128 v[196:199], v170 offset:1024
	ds_read_b128 v[200:203], v170 offset:2048
	ds_read_b128 v[204:207], v170 offset:3072
	ds_read_b128 v[208:211], v170 offset:4096
	ds_read_b128 v[212:215], v170 offset:5120
	ds_read_b128 v[216:219], v170 offset:6144
	ds_read_b128 v[220:223], v170 offset:7168
	ds_read_b128 v[142:145], v170 offset:16384
	ds_read_b128 v[224:227], v170 offset:17408
	ds_read_b128 v[228:231], v170 offset:18432
	ds_read_b128 v[232:235], v170 offset:19456
	ds_read_b128 v[236:239], v170 offset:20480
	ds_read_b128 v[240:243], v170 offset:21504
	ds_read_b128 v[244:247], v170 offset:22528
	ds_read_b128 v[248:251], v170 offset:23552
	s_waitcnt lgkmcnt(0)
	s_barrier
	v_mfma_f32_16x16x32_bf16 v[124:127], v[148:151], v[192:195], v[124:127]
	v_mfma_f32_16x16x32_bf16 v[120:123], v[156:159], v[192:195], v[120:123]
	v_mfma_f32_16x16x32_bf16 v[116:119], v[148:151], v[200:203], v[116:119]
	v_mfma_f32_16x16x32_bf16 v[112:115], v[156:159], v[200:203], v[112:115]
	v_mfma_f32_16x16x32_bf16 v[100:103], v[148:151], v[208:211], v[100:103]
	v_mfma_f32_16x16x32_bf16 v[96:99], v[156:159], v[208:211], v[96:99]
	v_mfma_f32_16x16x32_bf16 v[84:87], v[148:151], v[216:219], v[84:87]
	v_mfma_f32_16x16x32_bf16 v[80:83], v[156:159], v[216:219], v[80:83]
	v_mfma_f32_16x16x32_bf16 v[124:127], v[152:155], v[196:199], v[124:127]
	v_mfma_f32_16x16x32_bf16 v[120:123], v[172:175], v[196:199], v[120:123]
	v_mfma_f32_16x16x32_bf16 v[116:119], v[152:155], v[204:207], v[116:119]
	v_mfma_f32_16x16x32_bf16 v[112:115], v[172:175], v[204:207], v[112:115]
	v_mfma_f32_16x16x32_bf16 v[100:103], v[152:155], v[212:215], v[100:103]
	v_mfma_f32_16x16x32_bf16 v[96:99], v[172:175], v[212:215], v[96:99]
	v_mfma_f32_16x16x32_bf16 v[84:87], v[152:155], v[220:223], v[84:87]
	v_mfma_f32_16x16x32_bf16 v[80:83], v[172:175], v[220:223], v[80:83]
	v_mfma_f32_16x16x32_bf16 v[108:111], v[176:179], v[192:195], v[108:111]
	v_mfma_f32_16x16x32_bf16 v[104:107], v[184:187], v[192:195], v[104:107]
	v_mfma_f32_16x16x32_bf16 v[92:95], v[176:179], v[200:203], v[92:95]
	v_mfma_f32_16x16x32_bf16 v[88:91], v[184:187], v[200:203], v[88:91]
	v_mfma_f32_16x16x32_bf16 v[76:79], v[176:179], v[208:211], v[76:79]
	v_mfma_f32_16x16x32_bf16 v[72:75], v[184:187], v[208:211], v[72:75]
	v_mfma_f32_16x16x32_bf16 v[68:71], v[176:179], v[216:219], v[68:71]
	v_mfma_f32_16x16x32_bf16 v[64:67], v[184:187], v[216:219], v[64:67]
	v_mfma_f32_16x16x32_bf16 v[108:111], v[180:183], v[196:199], v[108:111]
	v_mfma_f32_16x16x32_bf16 v[104:107], v[188:191], v[196:199], v[104:107]
	v_mfma_f32_16x16x32_bf16 v[92:95], v[180:183], v[204:207], v[92:95]
	v_mfma_f32_16x16x32_bf16 v[88:91], v[188:191], v[204:207], v[88:91]
	v_mfma_f32_16x16x32_bf16 v[76:79], v[180:183], v[212:215], v[76:79]
	v_mfma_f32_16x16x32_bf16 v[72:75], v[188:191], v[212:215], v[72:75]
	v_mfma_f32_16x16x32_bf16 v[68:71], v[180:183], v[220:223], v[68:71]
	v_mfma_f32_16x16x32_bf16 v[64:67], v[188:191], v[220:223], v[64:67]
	v_mfma_f32_16x16x32_bf16 v[60:63], v[148:151], v[142:145], v[60:63]
	v_mfma_f32_16x16x32_bf16 v[56:59], v[156:159], v[142:145], v[56:59]
	v_mfma_f32_16x16x32_bf16 v[52:55], v[148:151], v[228:231], v[52:55]
	v_mfma_f32_16x16x32_bf16 v[48:51], v[156:159], v[228:231], v[48:51]
	v_mfma_f32_16x16x32_bf16 v[36:39], v[148:151], v[236:239], v[36:39]
	v_mfma_f32_16x16x32_bf16 v[32:35], v[156:159], v[236:239], v[32:35]
	v_mfma_f32_16x16x32_bf16 v[20:23], v[148:151], v[244:247], v[20:23]
	v_mfma_f32_16x16x32_bf16 v[16:19], v[156:159], v[244:247], v[16:19]
	v_mfma_f32_16x16x32_bf16 v[60:63], v[152:155], v[224:227], v[60:63]
	v_mfma_f32_16x16x32_bf16 v[56:59], v[172:175], v[224:227], v[56:59]
	v_mfma_f32_16x16x32_bf16 v[52:55], v[152:155], v[232:235], v[52:55]
	v_mfma_f32_16x16x32_bf16 v[48:51], v[172:175], v[232:235], v[48:51]
	v_mfma_f32_16x16x32_bf16 v[36:39], v[152:155], v[240:243], v[36:39]
	v_mfma_f32_16x16x32_bf16 v[32:35], v[172:175], v[240:243], v[32:35]
	v_mfma_f32_16x16x32_bf16 v[20:23], v[152:155], v[248:251], v[20:23]
	v_mfma_f32_16x16x32_bf16 v[16:19], v[172:175], v[248:251], v[16:19]
	v_mfma_f32_16x16x32_bf16 v[44:47], v[176:179], v[142:145], v[44:47]
	v_mfma_f32_16x16x32_bf16 v[40:43], v[184:187], v[142:145], v[40:43]
	v_mfma_f32_16x16x32_bf16 v[28:31], v[176:179], v[228:231], v[28:31]
	v_mfma_f32_16x16x32_bf16 v[24:27], v[184:187], v[228:231], v[24:27]
	v_mfma_f32_16x16x32_bf16 v[12:15], v[176:179], v[236:239], v[12:15]
	v_mfma_f32_16x16x32_bf16 v[8:11], v[184:187], v[236:239], v[8:11]
	v_mfma_f32_16x16x32_bf16 v[4:7], v[176:179], v[244:247], v[4:7]
	v_mfma_f32_16x16x32_bf16 v[0:3], v[184:187], v[244:247], v[0:3]
	v_mfma_f32_16x16x32_bf16 v[44:47], v[180:183], v[224:227], v[44:47]
	v_mfma_f32_16x16x32_bf16 v[40:43], v[188:191], v[224:227], v[40:43]
	v_mfma_f32_16x16x32_bf16 v[28:31], v[180:183], v[232:235], v[28:31]
	v_mfma_f32_16x16x32_bf16 v[24:27], v[188:191], v[232:235], v[24:27]
	v_mfma_f32_16x16x32_bf16 v[12:15], v[180:183], v[240:243], v[12:15]
	v_mfma_f32_16x16x32_bf16 v[8:11], v[188:191], v[240:243], v[8:11]
	v_mfma_f32_16x16x32_bf16 v[4:7], v[180:183], v[248:251], v[4:7]
	v_mfma_f32_16x16x32_bf16 v[0:3], v[188:191], v[248:251], v[0:3]
	s_waitcnt vmcnt(0)
	s_barrier
	s_add_u32 vcc_lo, s16, 0x0
	s_addc_u32 vcc_hi, s17, 0
	s_add_i32 m0, s23, 0x10000
	s_nop 0
	global_load_lds_dwordx4 v130, vcc
	s_add_i32 m0, s23, 0x12000
	s_nop 0
	global_load_lds_dwordx4 v134, vcc
	s_add_u32 vcc_lo, vcc_lo, 0x20000
	s_addc_u32 vcc_hi, vcc_hi, 0
	s_add_i32 m0, s23, 0x11000
	s_nop 0
	global_load_lds_dwordx4 v130, vcc
	s_add_i32 m0, s23, 0x13000
	s_nop 0
	global_load_lds_dwordx4 v134, vcc
	s_add_u32 vcc_lo, vcc_lo, 0x60000
	s_addc_u32 vcc_hi, vcc_hi, 0
	s_add_i32 m0, s23, 0x14000
	s_nop 0
	global_load_lds_dwordx4 v130, vcc
	s_add_i32 m0, s23, 0x16000
	s_nop 0
	global_load_lds_dwordx4 v134, vcc
	s_add_u32 vcc_lo, vcc_lo, 0x20000
	s_addc_u32 vcc_hi, vcc_hi, 0
	s_add_i32 m0, s23, 0x15000
	s_nop 0
	global_load_lds_dwordx4 v130, vcc
	s_add_i32 m0, s23, 0x17000
	s_nop 0
	global_load_lds_dwordx4 v134, vcc
	ds_read_b128 v[148:151], v168 offset:32768
	ds_read_b128 v[152:155], v168 offset:33792
	ds_read_b128 v[156:159], v168 offset:34816
	ds_read_b128 v[172:175], v168 offset:35840
	ds_read_b128 v[176:179], v169 offset:32768
	ds_read_b128 v[180:183], v169 offset:33792
	ds_read_b128 v[184:187], v169 offset:34816
	ds_read_b128 v[188:191], v169 offset:35840
	ds_read_b128 v[192:195], v170 offset:32768
	ds_read_b128 v[196:199], v170 offset:33792
	ds_read_b128 v[200:203], v170 offset:34816
	ds_read_b128 v[204:207], v170 offset:35840
	ds_read_b128 v[208:211], v170 offset:36864
	ds_read_b128 v[212:215], v170 offset:37888
	ds_read_b128 v[216:219], v170 offset:38912
	ds_read_b128 v[220:223], v170 offset:39936
	ds_read_b128 v[142:145], v170 offset:49152
	ds_read_b128 v[224:227], v170 offset:50176
	ds_read_b128 v[228:231], v170 offset:51200
	ds_read_b128 v[232:235], v170 offset:52224
	ds_read_b128 v[236:239], v170 offset:53248
	ds_read_b128 v[240:243], v170 offset:54272
	ds_read_b128 v[244:247], v170 offset:55296
	ds_read_b128 v[248:251], v170 offset:56320
	s_waitcnt lgkmcnt(0)
	s_barrier
	v_mfma_f32_16x16x32_bf16 v[124:127], v[148:151], v[192:195], v[124:127]
	v_mfma_f32_16x16x32_bf16 v[120:123], v[156:159], v[192:195], v[120:123]
	v_mfma_f32_16x16x32_bf16 v[116:119], v[148:151], v[200:203], v[116:119]
	v_mfma_f32_16x16x32_bf16 v[112:115], v[156:159], v[200:203], v[112:115]
	v_mfma_f32_16x16x32_bf16 v[100:103], v[148:151], v[208:211], v[100:103]
	v_mfma_f32_16x16x32_bf16 v[96:99], v[156:159], v[208:211], v[96:99]
	v_mfma_f32_16x16x32_bf16 v[84:87], v[148:151], v[216:219], v[84:87]
	v_mfma_f32_16x16x32_bf16 v[80:83], v[156:159], v[216:219], v[80:83]
	v_mfma_f32_16x16x32_bf16 v[124:127], v[152:155], v[196:199], v[124:127]
	v_mfma_f32_16x16x32_bf16 v[120:123], v[172:175], v[196:199], v[120:123]
	v_mfma_f32_16x16x32_bf16 v[116:119], v[152:155], v[204:207], v[116:119]
	v_mfma_f32_16x16x32_bf16 v[112:115], v[172:175], v[204:207], v[112:115]
	v_mfma_f32_16x16x32_bf16 v[100:103], v[152:155], v[212:215], v[100:103]
	v_mfma_f32_16x16x32_bf16 v[96:99], v[172:175], v[212:215], v[96:99]
	v_mfma_f32_16x16x32_bf16 v[84:87], v[152:155], v[220:223], v[84:87]
	v_mfma_f32_16x16x32_bf16 v[80:83], v[172:175], v[220:223], v[80:83]
	v_mfma_f32_16x16x32_bf16 v[108:111], v[176:179], v[192:195], v[108:111]
	v_mfma_f32_16x16x32_bf16 v[104:107], v[184:187], v[192:195], v[104:107]
	v_mfma_f32_16x16x32_bf16 v[92:95], v[176:179], v[200:203], v[92:95]
	v_mfma_f32_16x16x32_bf16 v[88:91], v[184:187], v[200:203], v[88:91]
	v_mfma_f32_16x16x32_bf16 v[76:79], v[176:179], v[208:211], v[76:79]
	v_mfma_f32_16x16x32_bf16 v[72:75], v[184:187], v[208:211], v[72:75]
	v_mfma_f32_16x16x32_bf16 v[68:71], v[176:179], v[216:219], v[68:71]
	v_mfma_f32_16x16x32_bf16 v[64:67], v[184:187], v[216:219], v[64:67]
	v_mfma_f32_16x16x32_bf16 v[108:111], v[180:183], v[196:199], v[108:111]
	v_mfma_f32_16x16x32_bf16 v[104:107], v[188:191], v[196:199], v[104:107]
	v_mfma_f32_16x16x32_bf16 v[92:95], v[180:183], v[204:207], v[92:95]
	v_mfma_f32_16x16x32_bf16 v[88:91], v[188:191], v[204:207], v[88:91]
	v_mfma_f32_16x16x32_bf16 v[76:79], v[180:183], v[212:215], v[76:79]
	v_mfma_f32_16x16x32_bf16 v[72:75], v[188:191], v[212:215], v[72:75]
	v_mfma_f32_16x16x32_bf16 v[68:71], v[180:183], v[220:223], v[68:71]
	v_mfma_f32_16x16x32_bf16 v[64:67], v[188:191], v[220:223], v[64:67]
	v_mfma_f32_16x16x32_bf16 v[60:63], v[148:151], v[142:145], v[60:63]
	v_mfma_f32_16x16x32_bf16 v[56:59], v[156:159], v[142:145], v[56:59]
	v_mfma_f32_16x16x32_bf16 v[52:55], v[148:151], v[228:231], v[52:55]
	v_mfma_f32_16x16x32_bf16 v[48:51], v[156:159], v[228:231], v[48:51]
	v_mfma_f32_16x16x32_bf16 v[36:39], v[148:151], v[236:239], v[36:39]
	v_mfma_f32_16x16x32_bf16 v[32:35], v[156:159], v[236:239], v[32:35]
	v_mfma_f32_16x16x32_bf16 v[20:23], v[148:151], v[244:247], v[20:23]
	v_mfma_f32_16x16x32_bf16 v[16:19], v[156:159], v[244:247], v[16:19]
	v_mfma_f32_16x16x32_bf16 v[60:63], v[152:155], v[224:227], v[60:63]
	v_mfma_f32_16x16x32_bf16 v[56:59], v[172:175], v[224:227], v[56:59]
	v_mfma_f32_16x16x32_bf16 v[52:55], v[152:155], v[232:235], v[52:55]
	v_mfma_f32_16x16x32_bf16 v[48:51], v[172:175], v[232:235], v[48:51]
	v_mfma_f32_16x16x32_bf16 v[36:39], v[152:155], v[240:243], v[36:39]
	v_mfma_f32_16x16x32_bf16 v[32:35], v[172:175], v[240:243], v[32:35]
	v_mfma_f32_16x16x32_bf16 v[20:23], v[152:155], v[248:251], v[20:23]
	v_mfma_f32_16x16x32_bf16 v[16:19], v[172:175], v[248:251], v[16:19]
	v_mfma_f32_16x16x32_bf16 v[44:47], v[176:179], v[142:145], v[44:47]
	v_mfma_f32_16x16x32_bf16 v[40:43], v[184:187], v[142:145], v[40:43]
	v_mfma_f32_16x16x32_bf16 v[28:31], v[176:179], v[228:231], v[28:31]
	v_mfma_f32_16x16x32_bf16 v[24:27], v[184:187], v[228:231], v[24:27]
	v_mfma_f32_16x16x32_bf16 v[12:15], v[176:179], v[236:239], v[12:15]
	v_mfma_f32_16x16x32_bf16 v[8:11], v[184:187], v[236:239], v[8:11]
	v_mfma_f32_16x16x32_bf16 v[4:7], v[176:179], v[244:247], v[4:7]
	v_mfma_f32_16x16x32_bf16 v[0:3], v[184:187], v[244:247], v[0:3]
	v_mfma_f32_16x16x32_bf16 v[44:47], v[180:183], v[224:227], v[44:47]
	v_mfma_f32_16x16x32_bf16 v[40:43], v[188:191], v[224:227], v[40:43]
	v_mfma_f32_16x16x32_bf16 v[28:31], v[180:183], v[232:235], v[28:31]
	v_mfma_f32_16x16x32_bf16 v[24:27], v[188:191], v[232:235], v[24:27]
	v_mfma_f32_16x16x32_bf16 v[12:15], v[180:183], v[240:243], v[12:15]
	v_mfma_f32_16x16x32_bf16 v[8:11], v[188:191], v[240:243], v[8:11]
	v_mfma_f32_16x16x32_bf16 v[4:7], v[180:183], v[248:251], v[4:7]
	v_mfma_f32_16x16x32_bf16 v[0:3], v[188:191], v[248:251], v[0:3]
	s_waitcnt vmcnt(0)
	s_barrier
	s_add_i32 s64, s64, 2
	s_add_u32 s14, s14, 0x100
	s_addc_u32 s15, s15, 0
	s_add_u32 s20, s20, 0x100
	s_addc_u32 s21, s21, 0
	s_cmp_gt_u32 s64, 29
	s_cbranch_scc0 .LBB0_165
	s_branch .Lk64_done_p1
.Lk64_trail_p1:
	s_sub_u32 vcc_lo, s14, 0x80000
	s_subb_u32 vcc_hi, s15, 0
	s_add_i32 m0, s23, 0xa000
	s_nop 0
	global_load_lds_dwordx4 v132, vcc
	s_add_u32 vcc_lo, vcc_lo, 0x20000
	s_addc_u32 vcc_hi, vcc_hi, 0
	s_add_i32 m0, s23, 0x9000
	s_nop 0
	global_load_lds_dwordx4 v128, vcc
	s_add_u32 vcc_lo, vcc_lo, 0x60000
	s_addc_u32 vcc_hi, vcc_hi, 0
	s_add_i32 m0, s23, 0xe000
	s_nop 0
	global_load_lds_dwordx4 v132, vcc
	s_add_u32 vcc_lo, vcc_lo, 0x20000
	s_addc_u32 vcc_hi, vcc_hi, 0
	s_add_i32 m0, s23, 0xd000
	s_nop 0
	global_load_lds_dwordx4 v128, vcc
	s_add_u32 vcc_lo, s18, 0x0
	s_addc_u32 vcc_hi, s19, 0
	s_mov_b32 m0, s23
	s_nop 0
	global_load_lds_dwordx4 v128, vcc
	s_sub_u32 vcc_lo, vcc_lo, 0x20000
	s_subb_u32 vcc_hi, vcc_hi, 0
	s_sub_i32 m0, s23, 0x1000
	s_nop 0
	global_load_lds_dwordx4 v128, vcc
	s_add_u32 vcc_lo, vcc_lo, 0xa0000
	s_addc_u32 vcc_hi, vcc_hi, 0
	s_add_i32 m0, s23, 0x4000
	s_nop 0
	global_load_lds_dwordx4 v128, vcc
	s_sub_u32 vcc_lo, vcc_lo, 0x20000
	s_subb_u32 vcc_hi, vcc_hi, 0
	s_add_i32 m0, s23, 0x3000
	s_nop 0
	global_load_lds_dwordx4 v128, vcc
	ds_read_b128 v[148:151], v168 offset:0
	ds_read_b128 v[152:155], v168 offset:1024
	ds_read_b128 v[156:159], v168 offset:2048
	ds_read_b128 v[172:175], v168 offset:3072
	ds_read_b128 v[176:179], v169 offset:0
	ds_read_b128 v[180:183], v169 offset:1024
	ds_read_b128 v[184:187], v169 offset:2048
	ds_read_b128 v[188:191], v169 offset:3072
	ds_read_b128 v[192:195], v170 offset:0
	ds_read_b128 v[196:199], v170 offset:1024
	ds_read_b128 v[200:203], v170 offset:2048
	ds_read_b128 v[204:207], v170 offset:3072
	ds_read_b128 v[208:211], v170 offset:4096
	ds_read_b128 v[212:215], v170 offset:5120
	ds_read_b128 v[216:219], v170 offset:6144
	ds_read_b128 v[220:223], v170 offset:7168
	ds_read_b128 v[142:145], v170 offset:16384
	ds_read_b128 v[224:227], v170 offset:17408
	ds_read_b128 v[228:231], v170 offset:18432
	ds_read_b128 v[232:235], v170 offset:19456
	ds_read_b128 v[236:239], v170 offset:20480
	ds_read_b128 v[240:243], v170 offset:21504
	ds_read_b128 v[244:247], v170 offset:22528
	ds_read_b128 v[248:251], v170 offset:23552
	s_waitcnt lgkmcnt(0)
	s_barrier
	v_mfma_f32_16x16x32_bf16 v[124:127], v[148:151], v[192:195], v[124:127]
	v_mfma_f32_16x16x32_bf16 v[120:123], v[156:159], v[192:195], v[120:123]
	v_mfma_f32_16x16x32_bf16 v[116:119], v[148:151], v[200:203], v[116:119]
	v_mfma_f32_16x16x32_bf16 v[112:115], v[156:159], v[200:203], v[112:115]
	v_mfma_f32_16x16x32_bf16 v[100:103], v[148:151], v[208:211], v[100:103]
	v_mfma_f32_16x16x32_bf16 v[96:99], v[156:159], v[208:211], v[96:99]
	v_mfma_f32_16x16x32_bf16 v[84:87], v[148:151], v[216:219], v[84:87]
	v_mfma_f32_16x16x32_bf16 v[80:83], v[156:159], v[216:219], v[80:83]
	v_mfma_f32_16x16x32_bf16 v[124:127], v[152:155], v[196:199], v[124:127]
	v_mfma_f32_16x16x32_bf16 v[120:123], v[172:175], v[196:199], v[120:123]
	v_mfma_f32_16x16x32_bf16 v[116:119], v[152:155], v[204:207], v[116:119]
	v_mfma_f32_16x16x32_bf16 v[112:115], v[172:175], v[204:207], v[112:115]
	v_mfma_f32_16x16x32_bf16 v[100:103], v[152:155], v[212:215], v[100:103]
	v_mfma_f32_16x16x32_bf16 v[96:99], v[172:175], v[212:215], v[96:99]
	v_mfma_f32_16x16x32_bf16 v[84:87], v[152:155], v[220:223], v[84:87]
	v_mfma_f32_16x16x32_bf16 v[80:83], v[172:175], v[220:223], v[80:83]
	v_mfma_f32_16x16x32_bf16 v[108:111], v[176:179], v[192:195], v[108:111]
	v_mfma_f32_16x16x32_bf16 v[104:107], v[184:187], v[192:195], v[104:107]
	v_mfma_f32_16x16x32_bf16 v[92:95], v[176:179], v[200:203], v[92:95]
	v_mfma_f32_16x16x32_bf16 v[88:91], v[184:187], v[200:203], v[88:91]
	v_mfma_f32_16x16x32_bf16 v[76:79], v[176:179], v[208:211], v[76:79]
	v_mfma_f32_16x16x32_bf16 v[72:75], v[184:187], v[208:211], v[72:75]
	v_mfma_f32_16x16x32_bf16 v[68:71], v[176:179], v[216:219], v[68:71]
	v_mfma_f32_16x16x32_bf16 v[64:67], v[184:187], v[216:219], v[64:67]
	v_mfma_f32_16x16x32_bf16 v[108:111], v[180:183], v[196:199], v[108:111]
	v_mfma_f32_16x16x32_bf16 v[104:107], v[188:191], v[196:199], v[104:107]
	v_mfma_f32_16x16x32_bf16 v[92:95], v[180:183], v[204:207], v[92:95]
	v_mfma_f32_16x16x32_bf16 v[88:91], v[188:191], v[204:207], v[88:91]
	v_mfma_f32_16x16x32_bf16 v[76:79], v[180:183], v[212:215], v[76:79]
	v_mfma_f32_16x16x32_bf16 v[72:75], v[188:191], v[212:215], v[72:75]
	v_mfma_f32_16x16x32_bf16 v[68:71], v[180:183], v[220:223], v[68:71]
	v_mfma_f32_16x16x32_bf16 v[64:67], v[188:191], v[220:223], v[64:67]
	v_mfma_f32_16x16x32_bf16 v[60:63], v[148:151], v[142:145], v[60:63]
	v_mfma_f32_16x16x32_bf16 v[56:59], v[156:159], v[142:145], v[56:59]
	v_mfma_f32_16x16x32_bf16 v[52:55], v[148:151], v[228:231], v[52:55]
	v_mfma_f32_16x16x32_bf16 v[48:51], v[156:159], v[228:231], v[48:51]
	v_mfma_f32_16x16x32_bf16 v[36:39], v[148:151], v[236:239], v[36:39]
	v_mfma_f32_16x16x32_bf16 v[32:35], v[156:159], v[236:239], v[32:35]
	v_mfma_f32_16x16x32_bf16 v[20:23], v[148:151], v[244:247], v[20:23]
	v_mfma_f32_16x16x32_bf16 v[16:19], v[156:159], v[244:247], v[16:19]
	v_mfma_f32_16x16x32_bf16 v[60:63], v[152:155], v[224:227], v[60:63]
	v_mfma_f32_16x16x32_bf16 v[56:59], v[172:175], v[224:227], v[56:59]
	v_mfma_f32_16x16x32_bf16 v[52:55], v[152:155], v[232:235], v[52:55]
	v_mfma_f32_16x16x32_bf16 v[48:51], v[172:175], v[232:235], v[48:51]
	v_mfma_f32_16x16x32_bf16 v[36:39], v[152:155], v[240:243], v[36:39]
	v_mfma_f32_16x16x32_bf16 v[32:35], v[172:175], v[240:243], v[32:35]
	v_mfma_f32_16x16x32_bf16 v[20:23], v[152:155], v[248:251], v[20:23]
	v_mfma_f32_16x16x32_bf16 v[16:19], v[172:175], v[248:251], v[16:19]
	v_mfma_f32_16x16x32_bf16 v[44:47], v[176:179], v[142:145], v[44:47]
	v_mfma_f32_16x16x32_bf16 v[40:43], v[184:187], v[142:145], v[40:43]
	v_mfma_f32_16x16x32_bf16 v[28:31], v[176:179], v[228:231], v[28:31]
	v_mfma_f32_16x16x32_bf16 v[24:27], v[184:187], v[228:231], v[24:27]
	v_mfma_f32_16x16x32_bf16 v[12:15], v[176:179], v[236:239], v[12:15]
	v_mfma_f32_16x16x32_bf16 v[8:11], v[184:187], v[236:239], v[8:11]
	v_mfma_f32_16x16x32_bf16 v[4:7], v[176:179], v[244:247], v[4:7]
	v_mfma_f32_16x16x32_bf16 v[0:3], v[184:187], v[244:247], v[0:3]
	v_mfma_f32_16x16x32_bf16 v[44:47], v[180:183], v[224:227], v[44:47]
	v_mfma_f32_16x16x32_bf16 v[40:43], v[188:191], v[224:227], v[40:43]
	v_mfma_f32_16x16x32_bf16 v[28:31], v[180:183], v[232:235], v[28:31]
	v_mfma_f32_16x16x32_bf16 v[24:27], v[188:191], v[232:235], v[24:27]
	v_mfma_f32_16x16x32_bf16 v[12:15], v[180:183], v[240:243], v[12:15]
	v_mfma_f32_16x16x32_bf16 v[8:11], v[188:191], v[240:243], v[8:11]
	v_mfma_f32_16x16x32_bf16 v[4:7], v[180:183], v[248:251], v[4:7]
	v_mfma_f32_16x16x32_bf16 v[0:3], v[188:191], v[248:251], v[0:3]
	s_waitcnt vmcnt(0)
	s_barrier
	s_add_u32 vcc_lo, s18, 0x0
	s_addc_u32 vcc_hi, s19, 0
	s_add_i32 m0, s23, 0x2000
	s_nop 0
	global_load_lds_dwordx4 v132, vcc
	s_add_u32 vcc_lo, vcc_lo, 0x20000
	s_addc_u32 vcc_hi, vcc_hi, 0
	s_add_i32 m0, s23, 0x1000
	s_nop 0
	global_load_lds_dwordx4 v128, vcc
	s_add_u32 vcc_lo, vcc_lo, 0x60000
	s_addc_u32 vcc_hi, vcc_hi, 0
	s_add_i32 m0, s23, 0x6000
	s_nop 0
	global_load_lds_dwordx4 v132, vcc
	s_add_u32 vcc_lo, vcc_lo, 0x20000
	s_addc_u32 vcc_hi, vcc_hi, 0
	s_add_i32 m0, s23, 0x5000
	s_nop 0
	global_load_lds_dwordx4 v128, vcc
	s_add_u32 vcc_lo, s18, 0x80
	s_addc_u32 vcc_hi, s19, 0
	s_add_i32 m0, s23, 0x8000
	s_nop 0
	global_load_lds_dwordx4 v128, vcc
	s_sub_u32 vcc_lo, vcc_lo, 0x20000
	s_subb_u32 vcc_hi, vcc_hi, 0
	s_add_i32 m0, s23, 0x7000
	s_nop 0
	global_load_lds_dwordx4 v128, vcc
	s_add_u32 vcc_lo, vcc_lo, 0xa0000
	s_addc_u32 vcc_hi, vcc_hi, 0
	s_add_i32 m0, s23, 0xc000
	s_nop 0
	global_load_lds_dwordx4 v128, vcc
	s_sub_u32 vcc_lo, vcc_lo, 0x20000
	s_subb_u32 vcc_hi, vcc_hi, 0
	s_add_i32 m0, s23, 0xb000
	s_nop 0
	global_load_lds_dwordx4 v128, vcc
	ds_read_b128 v[148:151], v168 offset:32768
	ds_read_b128 v[152:155], v168 offset:33792
	ds_read_b128 v[156:159], v168 offset:34816
	ds_read_b128 v[172:175], v168 offset:35840
	ds_read_b128 v[176:179], v169 offset:32768
	ds_read_b128 v[180:183], v169 offset:33792
	ds_read_b128 v[184:187], v169 offset:34816
	ds_read_b128 v[188:191], v169 offset:35840
	ds_read_b128 v[192:195], v170 offset:32768
	ds_read_b128 v[196:199], v170 offset:33792
	ds_read_b128 v[200:203], v170 offset:34816
	ds_read_b128 v[204:207], v170 offset:35840
	ds_read_b128 v[208:211], v170 offset:36864
	ds_read_b128 v[212:215], v170 offset:37888
	ds_read_b128 v[216:219], v170 offset:38912
	ds_read_b128 v[220:223], v170 offset:39936
	ds_read_b128 v[142:145], v170 offset:49152
	ds_read_b128 v[224:227], v170 offset:50176
	ds_read_b128 v[228:231], v170 offset:51200
	ds_read_b128 v[232:235], v170 offset:52224
	ds_read_b128 v[236:239], v170 offset:53248
	ds_read_b128 v[240:243], v170 offset:54272
	ds_read_b128 v[244:247], v170 offset:55296
	ds_read_b128 v[248:251], v170 offset:56320
	s_waitcnt lgkmcnt(0)
	s_barrier
	v_mfma_f32_16x16x32_bf16 v[124:127], v[148:151], v[192:195], v[124:127]
	v_mfma_f32_16x16x32_bf16 v[120:123], v[156:159], v[192:195], v[120:123]
	v_mfma_f32_16x16x32_bf16 v[116:119], v[148:151], v[200:203], v[116:119]
	v_mfma_f32_16x16x32_bf16 v[112:115], v[156:159], v[200:203], v[112:115]
	v_mfma_f32_16x16x32_bf16 v[100:103], v[148:151], v[208:211], v[100:103]
	v_mfma_f32_16x16x32_bf16 v[96:99], v[156:159], v[208:211], v[96:99]
	v_mfma_f32_16x16x32_bf16 v[84:87], v[148:151], v[216:219], v[84:87]
	v_mfma_f32_16x16x32_bf16 v[80:83], v[156:159], v[216:219], v[80:83]
	v_mfma_f32_16x16x32_bf16 v[124:127], v[152:155], v[196:199], v[124:127]
	v_mfma_f32_16x16x32_bf16 v[120:123], v[172:175], v[196:199], v[120:123]
	v_mfma_f32_16x16x32_bf16 v[116:119], v[152:155], v[204:207], v[116:119]
	v_mfma_f32_16x16x32_bf16 v[112:115], v[172:175], v[204:207], v[112:115]
	v_mfma_f32_16x16x32_bf16 v[100:103], v[152:155], v[212:215], v[100:103]
	v_mfma_f32_16x16x32_bf16 v[96:99], v[172:175], v[212:215], v[96:99]
	v_mfma_f32_16x16x32_bf16 v[84:87], v[152:155], v[220:223], v[84:87]
	v_mfma_f32_16x16x32_bf16 v[80:83], v[172:175], v[220:223], v[80:83]
	v_mfma_f32_16x16x32_bf16 v[108:111], v[176:179], v[192:195], v[108:111]
	v_mfma_f32_16x16x32_bf16 v[104:107], v[184:187], v[192:195], v[104:107]
	v_mfma_f32_16x16x32_bf16 v[92:95], v[176:179], v[200:203], v[92:95]
	v_mfma_f32_16x16x32_bf16 v[88:91], v[184:187], v[200:203], v[88:91]
	v_mfma_f32_16x16x32_bf16 v[76:79], v[176:179], v[208:211], v[76:79]
	v_mfma_f32_16x16x32_bf16 v[72:75], v[184:187], v[208:211], v[72:75]
	v_mfma_f32_16x16x32_bf16 v[68:71], v[176:179], v[216:219], v[68:71]
	v_mfma_f32_16x16x32_bf16 v[64:67], v[184:187], v[216:219], v[64:67]
	v_mfma_f32_16x16x32_bf16 v[108:111], v[180:183], v[196:199], v[108:111]
	v_mfma_f32_16x16x32_bf16 v[104:107], v[188:191], v[196:199], v[104:107]
	v_mfma_f32_16x16x32_bf16 v[92:95], v[180:183], v[204:207], v[92:95]
	v_mfma_f32_16x16x32_bf16 v[88:91], v[188:191], v[204:207], v[88:91]
	v_mfma_f32_16x16x32_bf16 v[76:79], v[180:183], v[212:215], v[76:79]
	v_mfma_f32_16x16x32_bf16 v[72:75], v[188:191], v[212:215], v[72:75]
	v_mfma_f32_16x16x32_bf16 v[68:71], v[180:183], v[220:223], v[68:71]
	v_mfma_f32_16x16x32_bf16 v[64:67], v[188:191], v[220:223], v[64:67]
	v_mfma_f32_16x16x32_bf16 v[60:63], v[148:151], v[142:145], v[60:63]
	v_mfma_f32_16x16x32_bf16 v[56:59], v[156:159], v[142:145], v[56:59]
	v_mfma_f32_16x16x32_bf16 v[52:55], v[148:151], v[228:231], v[52:55]
	v_mfma_f32_16x16x32_bf16 v[48:51], v[156:159], v[228:231], v[48:51]
	v_mfma_f32_16x16x32_bf16 v[36:39], v[148:151], v[236:239], v[36:39]
	v_mfma_f32_16x16x32_bf16 v[32:35], v[156:159], v[236:239], v[32:35]
	v_mfma_f32_16x16x32_bf16 v[20:23], v[148:151], v[244:247], v[20:23]
	v_mfma_f32_16x16x32_bf16 v[16:19], v[156:159], v[244:247], v[16:19]
	v_mfma_f32_16x16x32_bf16 v[60:63], v[152:155], v[224:227], v[60:63]
	v_mfma_f32_16x16x32_bf16 v[56:59], v[172:175], v[224:227], v[56:59]
	v_mfma_f32_16x16x32_bf16 v[52:55], v[152:155], v[232:235], v[52:55]
	v_mfma_f32_16x16x32_bf16 v[48:51], v[172:175], v[232:235], v[48:51]
	v_mfma_f32_16x16x32_bf16 v[36:39], v[152:155], v[240:243], v[36:39]
	v_mfma_f32_16x16x32_bf16 v[32:35], v[172:175], v[240:243], v[32:35]
	v_mfma_f32_16x16x32_bf16 v[20:23], v[152:155], v[248:251], v[20:23]
	v_mfma_f32_16x16x32_bf16 v[16:19], v[172:175], v[248:251], v[16:19]
	v_mfma_f32_16x16x32_bf16 v[44:47], v[176:179], v[142:145], v[44:47]
	v_mfma_f32_16x16x32_bf16 v[40:43], v[184:187], v[142:145], v[40:43]
	v_mfma_f32_16x16x32_bf16 v[28:31], v[176:179], v[228:231], v[28:31]
	v_mfma_f32_16x16x32_bf16 v[24:27], v[184:187], v[228:231], v[24:27]
	v_mfma_f32_16x16x32_bf16 v[12:15], v[176:179], v[236:239], v[12:15]
	v_mfma_f32_16x16x32_bf16 v[8:11], v[184:187], v[236:239], v[8:11]
	v_mfma_f32_16x16x32_bf16 v[4:7], v[176:179], v[244:247], v[4:7]
	v_mfma_f32_16x16x32_bf16 v[0:3], v[184:187], v[244:247], v[0:3]
	v_mfma_f32_16x16x32_bf16 v[44:47], v[180:183], v[224:227], v[44:47]
	v_mfma_f32_16x16x32_bf16 v[40:43], v[188:191], v[224:227], v[40:43]
	v_mfma_f32_16x16x32_bf16 v[28:31], v[180:183], v[232:235], v[28:31]
	v_mfma_f32_16x16x32_bf16 v[24:27], v[188:191], v[232:235], v[24:27]
	v_mfma_f32_16x16x32_bf16 v[12:15], v[180:183], v[240:243], v[12:15]
	v_mfma_f32_16x16x32_bf16 v[8:11], v[188:191], v[240:243], v[8:11]
	v_mfma_f32_16x16x32_bf16 v[4:7], v[180:183], v[248:251], v[4:7]
	v_mfma_f32_16x16x32_bf16 v[0:3], v[188:191], v[248:251], v[0:3]
	s_waitcnt vmcnt(0)
	s_barrier
	s_add_i32 s64, s64, 2
	s_add_u32 s14, s14, 0x100
	s_addc_u32 s15, s15, 0
	s_add_u32 s20, s20, 0x100
	s_addc_u32 s21, s21, 0
	s_cmp_gt_u32 s64, 29
	s_cbranch_scc0 .LBB0_165

.LBB0_613:
	s_add_u32 s24, s22, 0xfffc0080
	s_addc_u32 s25, s23, -1
	s_cmp_eq_u32 s49, 12
	s_cselect_b32 s27, s13, s25
	s_cselect_b32 s26, s41, s24
	s_cselect_b32 s25, s11, s48
	s_cselect_b32 s24, s46, s47
	s_and_b64 vcc, exec, s[6:7]
	s_cbranch_vccz .Lk64_trail_glu
	s_setprio 1
	s_sub_u32 vcc_lo, s47, 0x80
	s_subb_u32 vcc_hi, s48, 0
	s_add_i32 m0, s28, 0x18000
	s_nop 0
	global_load_lds_dwordx4 v132, vcc
	s_add_i32 m0, s28, 0x1a000
	s_nop 0
	global_load_lds_dwordx4 v128, vcc
	s_add_u32 vcc_lo, vcc_lo, 0x10000
	s_addc_u32 vcc_hi, vcc_hi, 0
	s_add_i32 m0, s28, 0x19000
	s_nop 0
	global_load_lds_dwordx4 v132, vcc
	s_add_i32 m0, s28, 0x1b000
	s_nop 0
	global_load_lds_dwordx4 v128, vcc
	s_add_u32 vcc_lo, vcc_lo, 0x30000
	s_addc_u32 vcc_hi, vcc_hi, 0
	s_add_i32 m0, s28, 0x1c000
	s_nop 0
	global_load_lds_dwordx4 v132, vcc
	s_add_i32 m0, s28, 0x1e000
	s_nop 0
	global_load_lds_dwordx4 v128, vcc
	s_add_u32 vcc_lo, vcc_lo, 0x10000
	s_addc_u32 vcc_hi, vcc_hi, 0
	s_add_i32 m0, s28, 0x1d000
	s_nop 0
	global_load_lds_dwordx4 v132, vcc
	s_add_i32 m0, s28, 0x1f000
	s_nop 0
	global_load_lds_dwordx4 v128, vcc
	ds_read_b128 v[144:147], v151 offset:0
	ds_read_b128 v[154:157], v151 offset:1024
	ds_read_b128 v[158:161], v151 offset:2048
	ds_read_b128 v[162:165], v151 offset:3072
	ds_read_b128 v[166:169], v152 offset:0
	ds_read_b128 v[170:173], v152 offset:1024
	ds_read_b128 v[174:177], v152 offset:2048
	ds_read_b128 v[178:181], v152 offset:3072
	ds_read_b128 v[182:185], v153 offset:0
	ds_read_b128 v[186:189], v153 offset:1024
	ds_read_b128 v[190:193], v153 offset:2048
	ds_read_b128 v[194:197], v153 offset:3072
	ds_read_b128 v[198:201], v153 offset:4096
	ds_read_b128 v[202:205], v153 offset:5120
	ds_read_b128 v[206:209], v153 offset:6144
	ds_read_b128 v[210:213], v153 offset:7168
	ds_read_b128 v[220:223], v153 offset:16384
	ds_read_b128 v[224:227], v153 offset:17408
	ds_read_b128 v[228:231], v153 offset:18432
	ds_read_b128 v[232:235], v153 offset:19456
	ds_read_b128 v[236:239], v153 offset:20480
	ds_read_b128 v[240:243], v153 offset:21504
	ds_read_b128 v[244:247], v153 offset:22528
	ds_read_b128 v[248:251], v153 offset:23552
	s_waitcnt lgkmcnt(0)
	s_barrier
	v_mfma_f32_16x16x32_bf16 v[124:127], v[144:147], v[182:185], v[124:127]
	v_mfma_f32_16x16x32_bf16 v[120:123], v[158:161], v[182:185], v[120:123]
	v_mfma_f32_16x16x32_bf16 v[108:111], v[144:147], v[190:193], v[108:111]
	v_mfma_f32_16x16x32_bf16 v[104:107], v[158:161], v[190:193], v[104:107]
	v_mfma_f32_16x16x32_bf16 v[92:95], v[144:147], v[198:201], v[92:95]
	v_mfma_f32_16x16x32_bf16 v[88:91], v[158:161], v[198:201], v[88:91]
	v_mfma_f32_16x16x32_bf16 v[76:79], v[144:147], v[206:209], v[76:79]
	v_mfma_f32_16x16x32_bf16 v[72:75], v[158:161], v[206:209], v[72:75]
	v_mfma_f32_16x16x32_bf16 v[124:127], v[154:157], v[186:189], v[124:127]
	v_mfma_f32_16x16x32_bf16 v[120:123], v[162:165], v[186:189], v[120:123]
	v_mfma_f32_16x16x32_bf16 v[108:111], v[154:157], v[194:197], v[108:111]
	v_mfma_f32_16x16x32_bf16 v[104:107], v[162:165], v[194:197], v[104:107]
	v_mfma_f32_16x16x32_bf16 v[92:95], v[154:157], v[202:205], v[92:95]
	v_mfma_f32_16x16x32_bf16 v[88:91], v[162:165], v[202:205], v[88:91]
	v_mfma_f32_16x16x32_bf16 v[76:79], v[154:157], v[210:213], v[76:79]
	v_mfma_f32_16x16x32_bf16 v[72:75], v[162:165], v[210:213], v[72:75]
	v_mfma_f32_16x16x32_bf16 v[116:119], v[166:169], v[182:185], v[116:119]
	v_mfma_f32_16x16x32_bf16 v[112:115], v[174:177], v[182:185], v[112:115]
	v_mfma_f32_16x16x32_bf16 v[100:103], v[166:169], v[190:193], v[100:103]
	v_mfma_f32_16x16x32_bf16 v[96:99], v[174:177], v[190:193], v[96:99]
	v_mfma_f32_16x16x32_bf16 v[84:87], v[166:169], v[198:201], v[84:87]
	v_mfma_f32_16x16x32_bf16 v[80:83], v[174:177], v[198:201], v[80:83]
	v_mfma_f32_16x16x32_bf16 v[68:71], v[166:169], v[206:209], v[68:71]
	v_mfma_f32_16x16x32_bf16 v[64:67], v[174:177], v[206:209], v[64:67]
	v_mfma_f32_16x16x32_bf16 v[116:119], v[170:173], v[186:189], v[116:119]
	v_mfma_f32_16x16x32_bf16 v[112:115], v[178:181], v[186:189], v[112:115]
	v_mfma_f32_16x16x32_bf16 v[100:103], v[170:173], v[194:197], v[100:103]
	v_mfma_f32_16x16x32_bf16 v[96:99], v[178:181], v[194:197], v[96:99]
	v_mfma_f32_16x16x32_bf16 v[84:87], v[170:173], v[202:205], v[84:87]
	v_mfma_f32_16x16x32_bf16 v[80:83], v[178:181], v[202:205], v[80:83]
	v_mfma_f32_16x16x32_bf16 v[68:71], v[170:173], v[210:213], v[68:71]
	v_mfma_f32_16x16x32_bf16 v[64:67], v[178:181], v[210:213], v[64:67]
	v_mfma_f32_16x16x32_bf16 v[60:63], v[144:147], v[220:223], v[60:63]
	v_mfma_f32_16x16x32_bf16 v[56:59], v[158:161], v[220:223], v[56:59]
	v_mfma_f32_16x16x32_bf16 v[44:47], v[144:147], v[228:231], v[44:47]
	v_mfma_f32_16x16x32_bf16 v[40:43], v[158:161], v[228:231], v[40:43]
	v_mfma_f32_16x16x32_bf16 v[28:31], v[144:147], v[236:239], v[28:31]
	v_mfma_f32_16x16x32_bf16 v[24:27], v[158:161], v[236:239], v[24:27]
	v_mfma_f32_16x16x32_bf16 v[12:15], v[144:147], v[244:247], v[12:15]
	v_mfma_f32_16x16x32_bf16 v[8:11], v[158:161], v[244:247], v[8:11]
	v_mfma_f32_16x16x32_bf16 v[60:63], v[154:157], v[224:227], v[60:63]
	v_mfma_f32_16x16x32_bf16 v[56:59], v[162:165], v[224:227], v[56:59]
	v_mfma_f32_16x16x32_bf16 v[44:47], v[154:157], v[232:235], v[44:47]
	v_mfma_f32_16x16x32_bf16 v[40:43], v[162:165], v[232:235], v[40:43]
	v_mfma_f32_16x16x32_bf16 v[28:31], v[154:157], v[240:243], v[28:31]
	v_mfma_f32_16x16x32_bf16 v[24:27], v[162:165], v[240:243], v[24:27]
	v_mfma_f32_16x16x32_bf16 v[12:15], v[154:157], v[248:251], v[12:15]
	v_mfma_f32_16x16x32_bf16 v[8:11], v[162:165], v[248:251], v[8:11]
	v_mfma_f32_16x16x32_bf16 v[52:55], v[166:169], v[220:223], v[52:55]
	v_mfma_f32_16x16x32_bf16 v[48:51], v[174:177], v[220:223], v[48:51]
	v_mfma_f32_16x16x32_bf16 v[36:39], v[166:169], v[228:231], v[36:39]
	v_mfma_f32_16x16x32_bf16 v[32:35], v[174:177], v[228:231], v[32:35]
	v_mfma_f32_16x16x32_bf16 v[20:23], v[166:169], v[236:239], v[20:23]
	v_mfma_f32_16x16x32_bf16 v[16:19], v[174:177], v[236:239], v[16:19]
	v_mfma_f32_16x16x32_bf16 v[4:7], v[166:169], v[244:247], v[4:7]
	v_mfma_f32_16x16x32_bf16 v[0:3], v[174:177], v[244:247], v[0:3]
	v_mfma_f32_16x16x32_bf16 v[52:55], v[170:173], v[224:227], v[52:55]
	v_mfma_f32_16x16x32_bf16 v[48:51], v[178:181], v[224:227], v[48:51]
	v_mfma_f32_16x16x32_bf16 v[36:39], v[170:173], v[232:235], v[36:39]
	v_mfma_f32_16x16x32_bf16 v[32:35], v[178:181], v[232:235], v[32:35]
	v_mfma_f32_16x16x32_bf16 v[20:23], v[170:173], v[240:243], v[20:23]
	v_mfma_f32_16x16x32_bf16 v[16:19], v[178:181], v[240:243], v[16:19]
	v_mfma_f32_16x16x32_bf16 v[4:7], v[170:173], v[248:251], v[4:7]
	v_mfma_f32_16x16x32_bf16 v[0:3], v[178:181], v[248:251], v[0:3]
	s_waitcnt vmcnt(0)
	s_barrier
	s_add_u32 vcc_lo, s24, 0x0
	s_addc_u32 vcc_hi, s25, 0
	s_add_i32 m0, s28, 0x10000
	s_nop 0
	global_load_lds_dwordx4 v132, vcc
	s_add_i32 m0, s28, 0x12000
	s_nop 0
	global_load_lds_dwordx4 v128, vcc
	s_add_u32 vcc_lo, vcc_lo, 0x10000
	s_addc_u32 vcc_hi, vcc_hi, 0
	s_add_i32 m0, s28, 0x11000
	s_nop 0
	global_load_lds_dwordx4 v132, vcc
	s_add_i32 m0, s28, 0x13000
	s_nop 0
	global_load_lds_dwordx4 v128, vcc
	s_add_u32 vcc_lo, vcc_lo, 0x30000
	s_addc_u32 vcc_hi, vcc_hi, 0
	s_add_i32 m0, s28, 0x14000
	s_nop 0
	global_load_lds_dwordx4 v132, vcc
	s_add_i32 m0, s28, 0x16000
	s_nop 0
	global_load_lds_dwordx4 v128, vcc
	s_add_u32 vcc_lo, vcc_lo, 0x10000
	s_addc_u32 vcc_hi, vcc_hi, 0
	s_add_i32 m0, s28, 0x15000
	s_nop 0
	global_load_lds_dwordx4 v132, vcc
	s_add_i32 m0, s28, 0x17000
	s_nop 0
	global_load_lds_dwordx4 v128, vcc
	ds_read_b128 v[144:147], v151 offset:32768
	ds_read_b128 v[154:157], v151 offset:33792
	ds_read_b128 v[158:161], v151 offset:34816
	ds_read_b128 v[162:165], v151 offset:35840
	ds_read_b128 v[166:169], v152 offset:32768
	ds_read_b128 v[170:173], v152 offset:33792
	ds_read_b128 v[174:177], v152 offset:34816
	ds_read_b128 v[178:181], v152 offset:35840
	ds_read_b128 v[182:185], v153 offset:32768
	ds_read_b128 v[186:189], v153 offset:33792
	ds_read_b128 v[190:193], v153 offset:34816
	ds_read_b128 v[194:197], v153 offset:35840
	ds_read_b128 v[198:201], v153 offset:36864
	ds_read_b128 v[202:205], v153 offset:37888
	ds_read_b128 v[206:209], v153 offset:38912
	ds_read_b128 v[210:213], v153 offset:39936
	ds_read_b128 v[220:223], v153 offset:49152
	ds_read_b128 v[224:227], v153 offset:50176
	ds_read_b128 v[228:231], v153 offset:51200
	ds_read_b128 v[232:235], v153 offset:52224
	ds_read_b128 v[236:239], v153 offset:53248
	ds_read_b128 v[240:243], v153 offset:54272
	ds_read_b128 v[244:247], v153 offset:55296
	ds_read_b128 v[248:251], v153 offset:56320
	s_waitcnt lgkmcnt(0)
	s_barrier
	v_mfma_f32_16x16x32_bf16 v[124:127], v[144:147], v[182:185], v[124:127]
	v_mfma_f32_16x16x32_bf16 v[120:123], v[158:161], v[182:185], v[120:123]
	v_mfma_f32_16x16x32_bf16 v[108:111], v[144:147], v[190:193], v[108:111]
	v_mfma_f32_16x16x32_bf16 v[104:107], v[158:161], v[190:193], v[104:107]
	v_mfma_f32_16x16x32_bf16 v[92:95], v[144:147], v[198:201], v[92:95]
	v_mfma_f32_16x16x32_bf16 v[88:91], v[158:161], v[198:201], v[88:91]
	v_mfma_f32_16x16x32_bf16 v[76:79], v[144:147], v[206:209], v[76:79]
	v_mfma_f32_16x16x32_bf16 v[72:75], v[158:161], v[206:209], v[72:75]
	v_mfma_f32_16x16x32_bf16 v[124:127], v[154:157], v[186:189], v[124:127]
	v_mfma_f32_16x16x32_bf16 v[120:123], v[162:165], v[186:189], v[120:123]
	v_mfma_f32_16x16x32_bf16 v[108:111], v[154:157], v[194:197], v[108:111]
	v_mfma_f32_16x16x32_bf16 v[104:107], v[162:165], v[194:197], v[104:107]
	v_mfma_f32_16x16x32_bf16 v[92:95], v[154:157], v[202:205], v[92:95]
	v_mfma_f32_16x16x32_bf16 v[88:91], v[162:165], v[202:205], v[88:91]
	v_mfma_f32_16x16x32_bf16 v[76:79], v[154:157], v[210:213], v[76:79]
	v_mfma_f32_16x16x32_bf16 v[72:75], v[162:165], v[210:213], v[72:75]
	v_mfma_f32_16x16x32_bf16 v[116:119], v[166:169], v[182:185], v[116:119]
	v_mfma_f32_16x16x32_bf16 v[112:115], v[174:177], v[182:185], v[112:115]
	v_mfma_f32_16x16x32_bf16 v[100:103], v[166:169], v[190:193], v[100:103]
	v_mfma_f32_16x16x32_bf16 v[96:99], v[174:177], v[190:193], v[96:99]
	v_mfma_f32_16x16x32_bf16 v[84:87], v[166:169], v[198:201], v[84:87]
	v_mfma_f32_16x16x32_bf16 v[80:83], v[174:177], v[198:201], v[80:83]
	v_mfma_f32_16x16x32_bf16 v[68:71], v[166:169], v[206:209], v[68:71]
	v_mfma_f32_16x16x32_bf16 v[64:67], v[174:177], v[206:209], v[64:67]
	v_mfma_f32_16x16x32_bf16 v[116:119], v[170:173], v[186:189], v[116:119]
	v_mfma_f32_16x16x32_bf16 v[112:115], v[178:181], v[186:189], v[112:115]
	v_mfma_f32_16x16x32_bf16 v[100:103], v[170:173], v[194:197], v[100:103]
	v_mfma_f32_16x16x32_bf16 v[96:99], v[178:181], v[194:197], v[96:99]
	v_mfma_f32_16x16x32_bf16 v[84:87], v[170:173], v[202:205], v[84:87]
	v_mfma_f32_16x16x32_bf16 v[80:83], v[178:181], v[202:205], v[80:83]
	v_mfma_f32_16x16x32_bf16 v[68:71], v[170:173], v[210:213], v[68:71]
	v_mfma_f32_16x16x32_bf16 v[64:67], v[178:181], v[210:213], v[64:67]
	v_mfma_f32_16x16x32_bf16 v[60:63], v[144:147], v[220:223], v[60:63]
	v_mfma_f32_16x16x32_bf16 v[56:59], v[158:161], v[220:223], v[56:59]
	v_mfma_f32_16x16x32_bf16 v[44:47], v[144:147], v[228:231], v[44:47]
	v_mfma_f32_16x16x32_bf16 v[40:43], v[158:161], v[228:231], v[40:43]
	v_mfma_f32_16x16x32_bf16 v[28:31], v[144:147], v[236:239], v[28:31]
	v_mfma_f32_16x16x32_bf16 v[24:27], v[158:161], v[236:239], v[24:27]
	v_mfma_f32_16x16x32_bf16 v[12:15], v[144:147], v[244:247], v[12:15]
	v_mfma_f32_16x16x32_bf16 v[8:11], v[158:161], v[244:247], v[8:11]
	v_mfma_f32_16x16x32_bf16 v[60:63], v[154:157], v[224:227], v[60:63]
	v_mfma_f32_16x16x32_bf16 v[56:59], v[162:165], v[224:227], v[56:59]
	v_mfma_f32_16x16x32_bf16 v[44:47], v[154:157], v[232:235], v[44:47]
	v_mfma_f32_16x16x32_bf16 v[40:43], v[162:165], v[232:235], v[40:43]
	v_mfma_f32_16x16x32_bf16 v[28:31], v[154:157], v[240:243], v[28:31]
	v_mfma_f32_16x16x32_bf16 v[24:27], v[162:165], v[240:243], v[24:27]
	v_mfma_f32_16x16x32_bf16 v[12:15], v[154:157], v[248:251], v[12:15]
	v_mfma_f32_16x16x32_bf16 v[8:11], v[162:165], v[248:251], v[8:11]
	v_mfma_f32_16x16x32_bf16 v[52:55], v[166:169], v[220:223], v[52:55]
	v_mfma_f32_16x16x32_bf16 v[48:51], v[174:177], v[220:223], v[48:51]
	v_mfma_f32_16x16x32_bf16 v[36:39], v[166:169], v[228:231], v[36:39]
	v_mfma_f32_16x16x32_bf16 v[32:35], v[174:177], v[228:231], v[32:35]
	v_mfma_f32_16x16x32_bf16 v[20:23], v[166:169], v[236:239], v[20:23]
	v_mfma_f32_16x16x32_bf16 v[16:19], v[174:177], v[236:239], v[16:19]
	v_mfma_f32_16x16x32_bf16 v[4:7], v[166:169], v[244:247], v[4:7]
	v_mfma_f32_16x16x32_bf16 v[0:3], v[174:177], v[244:247], v[0:3]
	v_mfma_f32_16x16x32_bf16 v[52:55], v[170:173], v[224:227], v[52:55]
	v_mfma_f32_16x16x32_bf16 v[48:51], v[178:181], v[224:227], v[48:51]
	v_mfma_f32_16x16x32_bf16 v[36:39], v[170:173], v[232:235], v[36:39]
	v_mfma_f32_16x16x32_bf16 v[32:35], v[178:181], v[232:235], v[32:35]
	v_mfma_f32_16x16x32_bf16 v[20:23], v[170:173], v[240:243], v[20:23]
	v_mfma_f32_16x16x32_bf16 v[16:19], v[178:181], v[240:243], v[16:19]
	v_mfma_f32_16x16x32_bf16 v[4:7], v[170:173], v[248:251], v[4:7]
	v_mfma_f32_16x16x32_bf16 v[0:3], v[178:181], v[248:251], v[0:3]
	s_waitcnt vmcnt(0)
	s_barrier
	s_add_i32 s49, s49, 2
	s_add_u32 s22, s22, 0x100
	s_addc_u32 s23, s23, 0
	s_add_u32 s47, s47, 0x100
	s_addc_u32 s48, s48, 0
	s_cmp_gt_u32 s49, 13
	s_cbranch_scc0 .LBB0_613
	s_branch .Lk64_done_glu
.Lk64_trail_glu:
	s_sub_u32 vcc_lo, s22, 0x40000
	s_subb_u32 vcc_hi, s23, 0
	s_add_i32 m0, s28, 0xa000
	s_nop 0
	global_load_lds_dwordx4 v130, vcc
	s_add_u32 vcc_lo, vcc_lo, 0x10000
	s_addc_u32 vcc_hi, vcc_hi, 0
	s_add_i32 m0, s28, 0x9000
	s_nop 0
	global_load_lds_dwordx4 v134, vcc
	s_add_u32 vcc_lo, vcc_lo, 0x30000
	s_addc_u32 vcc_hi, vcc_hi, 0
	s_add_i32 m0, s28, 0xe000
	s_nop 0
	global_load_lds_dwordx4 v130, vcc
	s_add_u32 vcc_lo, vcc_lo, 0x10000
	s_addc_u32 vcc_hi, vcc_hi, 0
	s_add_i32 m0, s28, 0xd000
	s_nop 0
	global_load_lds_dwordx4 v134, vcc
	s_add_u32 vcc_lo, s26, 0x0
	s_addc_u32 vcc_hi, s27, 0
	s_mov_b32 m0, s28
	s_nop 0
	global_load_lds_dwordx4 v134, vcc
	s_sub_u32 vcc_lo, vcc_lo, 0x10000
	s_subb_u32 vcc_hi, vcc_hi, 0
	s_sub_i32 m0, s28, 0x1000
	s_nop 0
	global_load_lds_dwordx4 v134, vcc
	s_add_u32 vcc_lo, vcc_lo, 0x50000
	s_addc_u32 vcc_hi, vcc_hi, 0
	s_add_i32 m0, s28, 0x4000
	s_nop 0
	global_load_lds_dwordx4 v134, vcc
	s_sub_u32 vcc_lo, vcc_lo, 0x10000
	s_subb_u32 vcc_hi, vcc_hi, 0
	s_add_i32 m0, s28, 0x3000
	s_nop 0
	global_load_lds_dwordx4 v134, vcc
	ds_read_b128 v[144:147], v151 offset:0
	ds_read_b128 v[154:157], v151 offset:1024
	ds_read_b128 v[158:161], v151 offset:2048
	ds_read_b128 v[162:165], v151 offset:3072
	ds_read_b128 v[166:169], v152 offset:0
	ds_read_b128 v[170:173], v152 offset:1024
	ds_read_b128 v[174:177], v152 offset:2048
	ds_read_b128 v[178:181], v152 offset:3072
	ds_read_b128 v[182:185], v153 offset:0
	ds_read_b128 v[186:189], v153 offset:1024
	ds_read_b128 v[190:193], v153 offset:2048
	ds_read_b128 v[194:197], v153 offset:3072
	ds_read_b128 v[198:201], v153 offset:4096
	ds_read_b128 v[202:205], v153 offset:5120
	ds_read_b128 v[206:209], v153 offset:6144
	ds_read_b128 v[210:213], v153 offset:7168
	ds_read_b128 v[220:223], v153 offset:16384
	ds_read_b128 v[224:227], v153 offset:17408
	ds_read_b128 v[228:231], v153 offset:18432
	ds_read_b128 v[232:235], v153 offset:19456
	ds_read_b128 v[236:239], v153 offset:20480
	ds_read_b128 v[240:243], v153 offset:21504
	ds_read_b128 v[244:247], v153 offset:22528
	ds_read_b128 v[248:251], v153 offset:23552
	s_waitcnt lgkmcnt(0)
	s_barrier
	v_mfma_f32_16x16x32_bf16 v[124:127], v[144:147], v[182:185], v[124:127]
	v_mfma_f32_16x16x32_bf16 v[120:123], v[158:161], v[182:185], v[120:123]
	v_mfma_f32_16x16x32_bf16 v[108:111], v[144:147], v[190:193], v[108:111]
	v_mfma_f32_16x16x32_bf16 v[104:107], v[158:161], v[190:193], v[104:107]
	v_mfma_f32_16x16x32_bf16 v[92:95], v[144:147], v[198:201], v[92:95]
	v_mfma_f32_16x16x32_bf16 v[88:91], v[158:161], v[198:201], v[88:91]
	v_mfma_f32_16x16x32_bf16 v[76:79], v[144:147], v[206:209], v[76:79]
	v_mfma_f32_16x16x32_bf16 v[72:75], v[158:161], v[206:209], v[72:75]
	v_mfma_f32_16x16x32_bf16 v[124:127], v[154:157], v[186:189], v[124:127]
	v_mfma_f32_16x16x32_bf16 v[120:123], v[162:165], v[186:189], v[120:123]
	v_mfma_f32_16x16x32_bf16 v[108:111], v[154:157], v[194:197], v[108:111]
	v_mfma_f32_16x16x32_bf16 v[104:107], v[162:165], v[194:197], v[104:107]
	v_mfma_f32_16x16x32_bf16 v[92:95], v[154:157], v[202:205], v[92:95]
	v_mfma_f32_16x16x32_bf16 v[88:91], v[162:165], v[202:205], v[88:91]
	v_mfma_f32_16x16x32_bf16 v[76:79], v[154:157], v[210:213], v[76:79]
	v_mfma_f32_16x16x32_bf16 v[72:75], v[162:165], v[210:213], v[72:75]
	v_mfma_f32_16x16x32_bf16 v[116:119], v[166:169], v[182:185], v[116:119]
	v_mfma_f32_16x16x32_bf16 v[112:115], v[174:177], v[182:185], v[112:115]
	v_mfma_f32_16x16x32_bf16 v[100:103], v[166:169], v[190:193], v[100:103]
	v_mfma_f32_16x16x32_bf16 v[96:99], v[174:177], v[190:193], v[96:99]
	v_mfma_f32_16x16x32_bf16 v[84:87], v[166:169], v[198:201], v[84:87]
	v_mfma_f32_16x16x32_bf16 v[80:83], v[174:177], v[198:201], v[80:83]
	v_mfma_f32_16x16x32_bf16 v[68:71], v[166:169], v[206:209], v[68:71]
	v_mfma_f32_16x16x32_bf16 v[64:67], v[174:177], v[206:209], v[64:67]
	v_mfma_f32_16x16x32_bf16 v[116:119], v[170:173], v[186:189], v[116:119]
	v_mfma_f32_16x16x32_bf16 v[112:115], v[178:181], v[186:189], v[112:115]
	v_mfma_f32_16x16x32_bf16 v[100:103], v[170:173], v[194:197], v[100:103]
	v_mfma_f32_16x16x32_bf16 v[96:99], v[178:181], v[194:197], v[96:99]
	v_mfma_f32_16x16x32_bf16 v[84:87], v[170:173], v[202:205], v[84:87]
	v_mfma_f32_16x16x32_bf16 v[80:83], v[178:181], v[202:205], v[80:83]
	v_mfma_f32_16x16x32_bf16 v[68:71], v[170:173], v[210:213], v[68:71]
	v_mfma_f32_16x16x32_bf16 v[64:67], v[178:181], v[210:213], v[64:67]
	v_mfma_f32_16x16x32_bf16 v[60:63], v[144:147], v[220:223], v[60:63]
	v_mfma_f32_16x16x32_bf16 v[56:59], v[158:161], v[220:223], v[56:59]
	v_mfma_f32_16x16x32_bf16 v[44:47], v[144:147], v[228:231], v[44:47]
	v_mfma_f32_16x16x32_bf16 v[40:43], v[158:161], v[228:231], v[40:43]
	v_mfma_f32_16x16x32_bf16 v[28:31], v[144:147], v[236:239], v[28:31]
	v_mfma_f32_16x16x32_bf16 v[24:27], v[158:161], v[236:239], v[24:27]
	v_mfma_f32_16x16x32_bf16 v[12:15], v[144:147], v[244:247], v[12:15]
	v_mfma_f32_16x16x32_bf16 v[8:11], v[158:161], v[244:247], v[8:11]
	v_mfma_f32_16x16x32_bf16 v[60:63], v[154:157], v[224:227], v[60:63]
	v_mfma_f32_16x16x32_bf16 v[56:59], v[162:165], v[224:227], v[56:59]
	v_mfma_f32_16x16x32_bf16 v[44:47], v[154:157], v[232:235], v[44:47]
	v_mfma_f32_16x16x32_bf16 v[40:43], v[162:165], v[232:235], v[40:43]
	v_mfma_f32_16x16x32_bf16 v[28:31], v[154:157], v[240:243], v[28:31]
	v_mfma_f32_16x16x32_bf16 v[24:27], v[162:165], v[240:243], v[24:27]
	v_mfma_f32_16x16x32_bf16 v[12:15], v[154:157], v[248:251], v[12:15]
	v_mfma_f32_16x16x32_bf16 v[8:11], v[162:165], v[248:251], v[8:11]
	v_mfma_f32_16x16x32_bf16 v[52:55], v[166:169], v[220:223], v[52:55]
	v_mfma_f32_16x16x32_bf16 v[48:51], v[174:177], v[220:223], v[48:51]
	v_mfma_f32_16x16x32_bf16 v[36:39], v[166:169], v[228:231], v[36:39]
	v_mfma_f32_16x16x32_bf16 v[32:35], v[174:177], v[228:231], v[32:35]
	v_mfma_f32_16x16x32_bf16 v[20:23], v[166:169], v[236:239], v[20:23]
	v_mfma_f32_16x16x32_bf16 v[16:19], v[174:177], v[236:239], v[16:19]
	v_mfma_f32_16x16x32_bf16 v[4:7], v[166:169], v[244:247], v[4:7]
	v_mfma_f32_16x16x32_bf16 v[0:3], v[174:177], v[244:247], v[0:3]
	v_mfma_f32_16x16x32_bf16 v[52:55], v[170:173], v[224:227], v[52:55]
	v_mfma_f32_16x16x32_bf16 v[48:51], v[178:181], v[224:227], v[48:51]
	v_mfma_f32_16x16x32_bf16 v[36:39], v[170:173], v[232:235], v[36:39]
	v_mfma_f32_16x16x32_bf16 v[32:35], v[178:181], v[232:235], v[32:35]
	v_mfma_f32_16x16x32_bf16 v[20:23], v[170:173], v[240:243], v[20:23]
	v_mfma_f32_16x16x32_bf16 v[16:19], v[178:181], v[240:243], v[16:19]
	v_mfma_f32_16x16x32_bf16 v[4:7], v[170:173], v[248:251], v[4:7]
	v_mfma_f32_16x16x32_bf16 v[0:3], v[178:181], v[248:251], v[0:3]
	s_waitcnt vmcnt(0)
	s_barrier
	s_add_u32 vcc_lo, s26, 0x0
	s_addc_u32 vcc_hi, s27, 0
	s_add_i32 m0, s28, 0x2000
	s_nop 0
	global_load_lds_dwordx4 v130, vcc
	s_add_u32 vcc_lo, vcc_lo, 0x10000
	s_addc_u32 vcc_hi, vcc_hi, 0
	s_add_i32 m0, s28, 0x1000
	s_nop 0
	global_load_lds_dwordx4 v134, vcc
	s_add_u32 vcc_lo, vcc_lo, 0x30000
	s_addc_u32 vcc_hi, vcc_hi, 0
	s_add_i32 m0, s28, 0x6000
	s_nop 0
	global_load_lds_dwordx4 v130, vcc
	s_add_u32 vcc_lo, vcc_lo, 0x10000
	s_addc_u32 vcc_hi, vcc_hi, 0
	s_add_i32 m0, s28, 0x5000
	s_nop 0
	global_load_lds_dwordx4 v134, vcc
	s_add_u32 vcc_lo, s26, 0x80
	s_addc_u32 vcc_hi, s27, 0
	s_add_i32 m0, s28, 0x8000
	s_nop 0
	global_load_lds_dwordx4 v134, vcc
	s_sub_u32 vcc_lo, vcc_lo, 0x10000
	s_subb_u32 vcc_hi, vcc_hi, 0
	s_add_i32 m0, s28, 0x7000
	s_nop 0
	global_load_lds_dwordx4 v134, vcc
	s_add_u32 vcc_lo, vcc_lo, 0x50000
	s_addc_u32 vcc_hi, vcc_hi, 0
	s_add_i32 m0, s28, 0xc000
	s_nop 0
	global_load_lds_dwordx4 v134, vcc
	s_sub_u32 vcc_lo, vcc_lo, 0x10000
	s_subb_u32 vcc_hi, vcc_hi, 0
	s_add_i32 m0, s28, 0xb000
	s_nop 0
	global_load_lds_dwordx4 v134, vcc
	ds_read_b128 v[144:147], v151 offset:32768
	ds_read_b128 v[154:157], v151 offset:33792
	ds_read_b128 v[158:161], v151 offset:34816
	ds_read_b128 v[162:165], v151 offset:35840
	ds_read_b128 v[166:169], v152 offset:32768
	ds_read_b128 v[170:173], v152 offset:33792
	ds_read_b128 v[174:177], v152 offset:34816
	ds_read_b128 v[178:181], v152 offset:35840
	ds_read_b128 v[182:185], v153 offset:32768
	ds_read_b128 v[186:189], v153 offset:33792
	ds_read_b128 v[190:193], v153 offset:34816
	ds_read_b128 v[194:197], v153 offset:35840
	ds_read_b128 v[198:201], v153 offset:36864
	ds_read_b128 v[202:205], v153 offset:37888
	ds_read_b128 v[206:209], v153 offset:38912
	ds_read_b128 v[210:213], v153 offset:39936
	ds_read_b128 v[220:223], v153 offset:49152
	ds_read_b128 v[224:227], v153 offset:50176
	ds_read_b128 v[228:231], v153 offset:51200
	ds_read_b128 v[232:235], v153 offset:52224
	ds_read_b128 v[236:239], v153 offset:53248
	ds_read_b128 v[240:243], v153 offset:54272
	ds_read_b128 v[244:247], v153 offset:55296
	ds_read_b128 v[248:251], v153 offset:56320
	s_waitcnt lgkmcnt(0)
	s_barrier
	v_mfma_f32_16x16x32_bf16 v[124:127], v[144:147], v[182:185], v[124:127]
	v_mfma_f32_16x16x32_bf16 v[120:123], v[158:161], v[182:185], v[120:123]
	v_mfma_f32_16x16x32_bf16 v[108:111], v[144:147], v[190:193], v[108:111]
	v_mfma_f32_16x16x32_bf16 v[104:107], v[158:161], v[190:193], v[104:107]
	v_mfma_f32_16x16x32_bf16 v[92:95], v[144:147], v[198:201], v[92:95]
	v_mfma_f32_16x16x32_bf16 v[88:91], v[158:161], v[198:201], v[88:91]
	v_mfma_f32_16x16x32_bf16 v[76:79], v[144:147], v[206:209], v[76:79]
	v_mfma_f32_16x16x32_bf16 v[72:75], v[158:161], v[206:209], v[72:75]
	v_mfma_f32_16x16x32_bf16 v[124:127], v[154:157], v[186:189], v[124:127]
	v_mfma_f32_16x16x32_bf16 v[120:123], v[162:165], v[186:189], v[120:123]
	v_mfma_f32_16x16x32_bf16 v[108:111], v[154:157], v[194:197], v[108:111]
	v_mfma_f32_16x16x32_bf16 v[104:107], v[162:165], v[194:197], v[104:107]
	v_mfma_f32_16x16x32_bf16 v[92:95], v[154:157], v[202:205], v[92:95]
	v_mfma_f32_16x16x32_bf16 v[88:91], v[162:165], v[202:205], v[88:91]
	v_mfma_f32_16x16x32_bf16 v[76:79], v[154:157], v[210:213], v[76:79]
	v_mfma_f32_16x16x32_bf16 v[72:75], v[162:165], v[210:213], v[72:75]
	v_mfma_f32_16x16x32_bf16 v[116:119], v[166:169], v[182:185], v[116:119]
	v_mfma_f32_16x16x32_bf16 v[112:115], v[174:177], v[182:185], v[112:115]
	v_mfma_f32_16x16x32_bf16 v[100:103], v[166:169], v[190:193], v[100:103]
	v_mfma_f32_16x16x32_bf16 v[96:99], v[174:177], v[190:193], v[96:99]
	v_mfma_f32_16x16x32_bf16 v[84:87], v[166:169], v[198:201], v[84:87]
	v_mfma_f32_16x16x32_bf16 v[80:83], v[174:177], v[198:201], v[80:83]
	v_mfma_f32_16x16x32_bf16 v[68:71], v[166:169], v[206:209], v[68:71]
	v_mfma_f32_16x16x32_bf16 v[64:67], v[174:177], v[206:209], v[64:67]
	v_mfma_f32_16x16x32_bf16 v[116:119], v[170:173], v[186:189], v[116:119]
	v_mfma_f32_16x16x32_bf16 v[112:115], v[178:181], v[186:189], v[112:115]
	v_mfma_f32_16x16x32_bf16 v[100:103], v[170:173], v[194:197], v[100:103]
	v_mfma_f32_16x16x32_bf16 v[96:99], v[178:181], v[194:197], v[96:99]
	v_mfma_f32_16x16x32_bf16 v[84:87], v[170:173], v[202:205], v[84:87]
	v_mfma_f32_16x16x32_bf16 v[80:83], v[178:181], v[202:205], v[80:83]
	v_mfma_f32_16x16x32_bf16 v[68:71], v[170:173], v[210:213], v[68:71]
	v_mfma_f32_16x16x32_bf16 v[64:67], v[178:181], v[210:213], v[64:67]
	v_mfma_f32_16x16x32_bf16 v[60:63], v[144:147], v[220:223], v[60:63]
	v_mfma_f32_16x16x32_bf16 v[56:59], v[158:161], v[220:223], v[56:59]
	v_mfma_f32_16x16x32_bf16 v[44:47], v[144:147], v[228:231], v[44:47]
	v_mfma_f32_16x16x32_bf16 v[40:43], v[158:161], v[228:231], v[40:43]
	v_mfma_f32_16x16x32_bf16 v[28:31], v[144:147], v[236:239], v[28:31]
	v_mfma_f32_16x16x32_bf16 v[24:27], v[158:161], v[236:239], v[24:27]
	v_mfma_f32_16x16x32_bf16 v[12:15], v[144:147], v[244:247], v[12:15]
	v_mfma_f32_16x16x32_bf16 v[8:11], v[158:161], v[244:247], v[8:11]
	v_mfma_f32_16x16x32_bf16 v[60:63], v[154:157], v[224:227], v[60:63]
	v_mfma_f32_16x16x32_bf16 v[56:59], v[162:165], v[224:227], v[56:59]
	v_mfma_f32_16x16x32_bf16 v[44:47], v[154:157], v[232:235], v[44:47]
	v_mfma_f32_16x16x32_bf16 v[40:43], v[162:165], v[232:235], v[40:43]
	v_mfma_f32_16x16x32_bf16 v[28:31], v[154:157], v[240:243], v[28:31]
	v_mfma_f32_16x16x32_bf16 v[24:27], v[162:165], v[240:243], v[24:27]
	v_mfma_f32_16x16x32_bf16 v[12:15], v[154:157], v[248:251], v[12:15]
	v_mfma_f32_16x16x32_bf16 v[8:11], v[162:165], v[248:251], v[8:11]
	v_mfma_f32_16x16x32_bf16 v[52:55], v[166:169], v[220:223], v[52:55]
	v_mfma_f32_16x16x32_bf16 v[48:51], v[174:177], v[220:223], v[48:51]
	v_mfma_f32_16x16x32_bf16 v[36:39], v[166:169], v[228:231], v[36:39]
	v_mfma_f32_16x16x32_bf16 v[32:35], v[174:177], v[228:231], v[32:35]
	v_mfma_f32_16x16x32_bf16 v[20:23], v[166:169], v[236:239], v[20:23]
	v_mfma_f32_16x16x32_bf16 v[16:19], v[174:177], v[236:239], v[16:19]
	v_mfma_f32_16x16x32_bf16 v[4:7], v[166:169], v[244:247], v[4:7]
	v_mfma_f32_16x16x32_bf16 v[0:3], v[174:177], v[244:247], v[0:3]
	v_mfma_f32_16x16x32_bf16 v[52:55], v[170:173], v[224:227], v[52:55]
	v_mfma_f32_16x16x32_bf16 v[48:51], v[178:181], v[224:227], v[48:51]
	v_mfma_f32_16x16x32_bf16 v[36:39], v[170:173], v[232:235], v[36:39]
	v_mfma_f32_16x16x32_bf16 v[32:35], v[178:181], v[232:235], v[32:35]
	v_mfma_f32_16x16x32_bf16 v[20:23], v[170:173], v[240:243], v[20:23]
	v_mfma_f32_16x16x32_bf16 v[16:19], v[178:181], v[240:243], v[16:19]
	v_mfma_f32_16x16x32_bf16 v[4:7], v[170:173], v[248:251], v[4:7]
	v_mfma_f32_16x16x32_bf16 v[0:3], v[178:181], v[248:251], v[0:3]
	s_waitcnt vmcnt(0)
	s_barrier
	s_add_i32 s49, s49, 2
	s_add_u32 s22, s22, 0x100
	s_addc_u32 s23, s23, 0
	s_add_u32 s47, s47, 0x100
	s_addc_u32 s48, s48, 0
	s_cmp_gt_u32 s49, 13
	s_cbranch_scc0 .LBB0_613

.LBB0_686:
	s_add_u32 s30, s12, 0xfffc0080
	s_addc_u32 s31, s13, -1
	s_cmp_eq_u32 s56, 12
	s_cselect_b32 s35, s25, s31
	s_cselect_b32 s34, s49, s30
	s_cselect_b32 s31, s23, s55
	s_cselect_b32 s30, s51, s54
	s_and_b64 vcc, exec, s[4:5]
	s_cbranch_vccz .Lk64_trail_p4
	s_setprio 1
	s_sub_u32 vcc_lo, s54, 0x80
	s_subb_u32 vcc_hi, s55, 0
	s_add_i32 m0, s36, 0x18000
	s_nop 0
	global_load_lds_dwordx4 v132, vcc
	s_add_i32 m0, s36, 0x1a000
	s_nop 0
	global_load_lds_dwordx4 v128, vcc
	s_add_u32 vcc_lo, vcc_lo, 0x10000
	s_addc_u32 vcc_hi, vcc_hi, 0
	s_add_i32 m0, s36, 0x19000
	s_nop 0
	global_load_lds_dwordx4 v132, vcc
	s_add_i32 m0, s36, 0x1b000
	s_nop 0
	global_load_lds_dwordx4 v128, vcc
	s_add_u32 vcc_lo, vcc_lo, 0x30000
	s_addc_u32 vcc_hi, vcc_hi, 0
	s_add_i32 m0, s36, 0x1c000
	s_nop 0
	global_load_lds_dwordx4 v132, vcc
	s_add_i32 m0, s36, 0x1e000
	s_nop 0
	global_load_lds_dwordx4 v128, vcc
	s_add_u32 vcc_lo, vcc_lo, 0x10000
	s_addc_u32 vcc_hi, vcc_hi, 0
	s_add_i32 m0, s36, 0x1d000
	s_nop 0
	global_load_lds_dwordx4 v132, vcc
	s_add_i32 m0, s36, 0x1f000
	s_nop 0
	global_load_lds_dwordx4 v128, vcc
	ds_read_b128 v[144:147], v151 offset:0
	ds_read_b128 v[154:157], v151 offset:1024
	ds_read_b128 v[158:161], v151 offset:2048
	ds_read_b128 v[162:165], v151 offset:3072
	ds_read_b128 v[166:169], v152 offset:0
	ds_read_b128 v[170:173], v152 offset:1024
	ds_read_b128 v[174:177], v152 offset:2048
	ds_read_b128 v[178:181], v152 offset:3072
	ds_read_b128 v[182:185], v153 offset:0
	ds_read_b128 v[186:189], v153 offset:1024
	ds_read_b128 v[190:193], v153 offset:2048
	ds_read_b128 v[194:197], v153 offset:3072
	ds_read_b128 v[198:201], v153 offset:4096
	ds_read_b128 v[202:205], v153 offset:5120
	ds_read_b128 v[206:209], v153 offset:6144
	ds_read_b128 v[210:213], v153 offset:7168
	ds_read_b128 v[220:223], v153 offset:16384
	ds_read_b128 v[224:227], v153 offset:17408
	ds_read_b128 v[228:231], v153 offset:18432
	ds_read_b128 v[232:235], v153 offset:19456
	ds_read_b128 v[236:239], v153 offset:20480
	ds_read_b128 v[240:243], v153 offset:21504
	ds_read_b128 v[244:247], v153 offset:22528
	ds_read_b128 v[248:251], v153 offset:23552
	s_waitcnt lgkmcnt(0)
	s_barrier
	v_mfma_f32_16x16x32_bf16 v[124:127], v[144:147], v[182:185], v[124:127]
	v_mfma_f32_16x16x32_bf16 v[120:123], v[158:161], v[182:185], v[120:123]
	v_mfma_f32_16x16x32_bf16 v[108:111], v[144:147], v[190:193], v[108:111]
	v_mfma_f32_16x16x32_bf16 v[104:107], v[158:161], v[190:193], v[104:107]
	v_mfma_f32_16x16x32_bf16 v[92:95], v[144:147], v[198:201], v[92:95]
	v_mfma_f32_16x16x32_bf16 v[88:91], v[158:161], v[198:201], v[88:91]
	v_mfma_f32_16x16x32_bf16 v[76:79], v[144:147], v[206:209], v[76:79]
	v_mfma_f32_16x16x32_bf16 v[72:75], v[158:161], v[206:209], v[72:75]
	v_mfma_f32_16x16x32_bf16 v[124:127], v[154:157], v[186:189], v[124:127]
	v_mfma_f32_16x16x32_bf16 v[120:123], v[162:165], v[186:189], v[120:123]
	v_mfma_f32_16x16x32_bf16 v[108:111], v[154:157], v[194:197], v[108:111]
	v_mfma_f32_16x16x32_bf16 v[104:107], v[162:165], v[194:197], v[104:107]
	v_mfma_f32_16x16x32_bf16 v[92:95], v[154:157], v[202:205], v[92:95]
	v_mfma_f32_16x16x32_bf16 v[88:91], v[162:165], v[202:205], v[88:91]
	v_mfma_f32_16x16x32_bf16 v[76:79], v[154:157], v[210:213], v[76:79]
	v_mfma_f32_16x16x32_bf16 v[72:75], v[162:165], v[210:213], v[72:75]
	v_mfma_f32_16x16x32_bf16 v[116:119], v[166:169], v[182:185], v[116:119]
	v_mfma_f32_16x16x32_bf16 v[112:115], v[174:177], v[182:185], v[112:115]
	v_mfma_f32_16x16x32_bf16 v[100:103], v[166:169], v[190:193], v[100:103]
	v_mfma_f32_16x16x32_bf16 v[96:99], v[174:177], v[190:193], v[96:99]
	v_mfma_f32_16x16x32_bf16 v[84:87], v[166:169], v[198:201], v[84:87]
	v_mfma_f32_16x16x32_bf16 v[80:83], v[174:177], v[198:201], v[80:83]
	v_mfma_f32_16x16x32_bf16 v[68:71], v[166:169], v[206:209], v[68:71]
	v_mfma_f32_16x16x32_bf16 v[64:67], v[174:177], v[206:209], v[64:67]
	v_mfma_f32_16x16x32_bf16 v[116:119], v[170:173], v[186:189], v[116:119]
	v_mfma_f32_16x16x32_bf16 v[112:115], v[178:181], v[186:189], v[112:115]
	v_mfma_f32_16x16x32_bf16 v[100:103], v[170:173], v[194:197], v[100:103]
	v_mfma_f32_16x16x32_bf16 v[96:99], v[178:181], v[194:197], v[96:99]
	v_mfma_f32_16x16x32_bf16 v[84:87], v[170:173], v[202:205], v[84:87]
	v_mfma_f32_16x16x32_bf16 v[80:83], v[178:181], v[202:205], v[80:83]
	v_mfma_f32_16x16x32_bf16 v[68:71], v[170:173], v[210:213], v[68:71]
	v_mfma_f32_16x16x32_bf16 v[64:67], v[178:181], v[210:213], v[64:67]
	v_mfma_f32_16x16x32_bf16 v[60:63], v[144:147], v[220:223], v[60:63]
	v_mfma_f32_16x16x32_bf16 v[56:59], v[158:161], v[220:223], v[56:59]
	v_mfma_f32_16x16x32_bf16 v[44:47], v[144:147], v[228:231], v[44:47]
	v_mfma_f32_16x16x32_bf16 v[40:43], v[158:161], v[228:231], v[40:43]
	v_mfma_f32_16x16x32_bf16 v[28:31], v[144:147], v[236:239], v[28:31]
	v_mfma_f32_16x16x32_bf16 v[24:27], v[158:161], v[236:239], v[24:27]
	v_mfma_f32_16x16x32_bf16 v[12:15], v[144:147], v[244:247], v[12:15]
	v_mfma_f32_16x16x32_bf16 v[8:11], v[158:161], v[244:247], v[8:11]
	v_mfma_f32_16x16x32_bf16 v[60:63], v[154:157], v[224:227], v[60:63]
	v_mfma_f32_16x16x32_bf16 v[56:59], v[162:165], v[224:227], v[56:59]
	v_mfma_f32_16x16x32_bf16 v[44:47], v[154:157], v[232:235], v[44:47]
	v_mfma_f32_16x16x32_bf16 v[40:43], v[162:165], v[232:235], v[40:43]
	v_mfma_f32_16x16x32_bf16 v[28:31], v[154:157], v[240:243], v[28:31]
	v_mfma_f32_16x16x32_bf16 v[24:27], v[162:165], v[240:243], v[24:27]
	v_mfma_f32_16x16x32_bf16 v[12:15], v[154:157], v[248:251], v[12:15]
	v_mfma_f32_16x16x32_bf16 v[8:11], v[162:165], v[248:251], v[8:11]
	v_mfma_f32_16x16x32_bf16 v[52:55], v[166:169], v[220:223], v[52:55]
	v_mfma_f32_16x16x32_bf16 v[48:51], v[174:177], v[220:223], v[48:51]
	v_mfma_f32_16x16x32_bf16 v[36:39], v[166:169], v[228:231], v[36:39]
	v_mfma_f32_16x16x32_bf16 v[32:35], v[174:177], v[228:231], v[32:35]
	v_mfma_f32_16x16x32_bf16 v[20:23], v[166:169], v[236:239], v[20:23]
	v_mfma_f32_16x16x32_bf16 v[16:19], v[174:177], v[236:239], v[16:19]
	v_mfma_f32_16x16x32_bf16 v[4:7], v[166:169], v[244:247], v[4:7]
	v_mfma_f32_16x16x32_bf16 v[0:3], v[174:177], v[244:247], v[0:3]
	v_mfma_f32_16x16x32_bf16 v[52:55], v[170:173], v[224:227], v[52:55]
	v_mfma_f32_16x16x32_bf16 v[48:51], v[178:181], v[224:227], v[48:51]
	v_mfma_f32_16x16x32_bf16 v[36:39], v[170:173], v[232:235], v[36:39]
	v_mfma_f32_16x16x32_bf16 v[32:35], v[178:181], v[232:235], v[32:35]
	v_mfma_f32_16x16x32_bf16 v[20:23], v[170:173], v[240:243], v[20:23]
	v_mfma_f32_16x16x32_bf16 v[16:19], v[178:181], v[240:243], v[16:19]
	v_mfma_f32_16x16x32_bf16 v[4:7], v[170:173], v[248:251], v[4:7]
	v_mfma_f32_16x16x32_bf16 v[0:3], v[178:181], v[248:251], v[0:3]
	s_waitcnt vmcnt(0)
	s_barrier
	s_add_u32 vcc_lo, s30, 0x0
	s_addc_u32 vcc_hi, s31, 0
	s_add_i32 m0, s36, 0x10000
	s_nop 0
	global_load_lds_dwordx4 v132, vcc
	s_add_i32 m0, s36, 0x12000
	s_nop 0
	global_load_lds_dwordx4 v128, vcc
	s_add_u32 vcc_lo, vcc_lo, 0x10000
	s_addc_u32 vcc_hi, vcc_hi, 0
	s_add_i32 m0, s36, 0x11000
	s_nop 0
	global_load_lds_dwordx4 v132, vcc
	s_add_i32 m0, s36, 0x13000
	s_nop 0
	global_load_lds_dwordx4 v128, vcc
	s_add_u32 vcc_lo, vcc_lo, 0x30000
	s_addc_u32 vcc_hi, vcc_hi, 0
	s_add_i32 m0, s36, 0x14000
	s_nop 0
	global_load_lds_dwordx4 v132, vcc
	s_add_i32 m0, s36, 0x16000
	s_nop 0
	global_load_lds_dwordx4 v128, vcc
	s_add_u32 vcc_lo, vcc_lo, 0x10000
	s_addc_u32 vcc_hi, vcc_hi, 0
	s_add_i32 m0, s36, 0x15000
	s_nop 0
	global_load_lds_dwordx4 v132, vcc
	s_add_i32 m0, s36, 0x17000
	s_nop 0
	global_load_lds_dwordx4 v128, vcc
	ds_read_b128 v[144:147], v151 offset:32768
	ds_read_b128 v[154:157], v151 offset:33792
	ds_read_b128 v[158:161], v151 offset:34816
	ds_read_b128 v[162:165], v151 offset:35840
	ds_read_b128 v[166:169], v152 offset:32768
	ds_read_b128 v[170:173], v152 offset:33792
	ds_read_b128 v[174:177], v152 offset:34816
	ds_read_b128 v[178:181], v152 offset:35840
	ds_read_b128 v[182:185], v153 offset:32768
	ds_read_b128 v[186:189], v153 offset:33792
	ds_read_b128 v[190:193], v153 offset:34816
	ds_read_b128 v[194:197], v153 offset:35840
	ds_read_b128 v[198:201], v153 offset:36864
	ds_read_b128 v[202:205], v153 offset:37888
	ds_read_b128 v[206:209], v153 offset:38912
	ds_read_b128 v[210:213], v153 offset:39936
	ds_read_b128 v[220:223], v153 offset:49152
	ds_read_b128 v[224:227], v153 offset:50176
	ds_read_b128 v[228:231], v153 offset:51200
	ds_read_b128 v[232:235], v153 offset:52224
	ds_read_b128 v[236:239], v153 offset:53248
	ds_read_b128 v[240:243], v153 offset:54272
	ds_read_b128 v[244:247], v153 offset:55296
	ds_read_b128 v[248:251], v153 offset:56320
	s_waitcnt lgkmcnt(0)
	s_barrier
	v_mfma_f32_16x16x32_bf16 v[124:127], v[144:147], v[182:185], v[124:127]
	v_mfma_f32_16x16x32_bf16 v[120:123], v[158:161], v[182:185], v[120:123]
	v_mfma_f32_16x16x32_bf16 v[108:111], v[144:147], v[190:193], v[108:111]
	v_mfma_f32_16x16x32_bf16 v[104:107], v[158:161], v[190:193], v[104:107]
	v_mfma_f32_16x16x32_bf16 v[92:95], v[144:147], v[198:201], v[92:95]
	v_mfma_f32_16x16x32_bf16 v[88:91], v[158:161], v[198:201], v[88:91]
	v_mfma_f32_16x16x32_bf16 v[76:79], v[144:147], v[206:209], v[76:79]
	v_mfma_f32_16x16x32_bf16 v[72:75], v[158:161], v[206:209], v[72:75]
	v_mfma_f32_16x16x32_bf16 v[124:127], v[154:157], v[186:189], v[124:127]
	v_mfma_f32_16x16x32_bf16 v[120:123], v[162:165], v[186:189], v[120:123]
	v_mfma_f32_16x16x32_bf16 v[108:111], v[154:157], v[194:197], v[108:111]
	v_mfma_f32_16x16x32_bf16 v[104:107], v[162:165], v[194:197], v[104:107]
	v_mfma_f32_16x16x32_bf16 v[92:95], v[154:157], v[202:205], v[92:95]
	v_mfma_f32_16x16x32_bf16 v[88:91], v[162:165], v[202:205], v[88:91]
	v_mfma_f32_16x16x32_bf16 v[76:79], v[154:157], v[210:213], v[76:79]
	v_mfma_f32_16x16x32_bf16 v[72:75], v[162:165], v[210:213], v[72:75]
	v_mfma_f32_16x16x32_bf16 v[116:119], v[166:169], v[182:185], v[116:119]
	v_mfma_f32_16x16x32_bf16 v[112:115], v[174:177], v[182:185], v[112:115]
	v_mfma_f32_16x16x32_bf16 v[100:103], v[166:169], v[190:193], v[100:103]
	v_mfma_f32_16x16x32_bf16 v[96:99], v[174:177], v[190:193], v[96:99]
	v_mfma_f32_16x16x32_bf16 v[84:87], v[166:169], v[198:201], v[84:87]
	v_mfma_f32_16x16x32_bf16 v[80:83], v[174:177], v[198:201], v[80:83]
	v_mfma_f32_16x16x32_bf16 v[68:71], v[166:169], v[206:209], v[68:71]
	v_mfma_f32_16x16x32_bf16 v[64:67], v[174:177], v[206:209], v[64:67]
	v_mfma_f32_16x16x32_bf16 v[116:119], v[170:173], v[186:189], v[116:119]
	v_mfma_f32_16x16x32_bf16 v[112:115], v[178:181], v[186:189], v[112:115]
	v_mfma_f32_16x16x32_bf16 v[100:103], v[170:173], v[194:197], v[100:103]
	v_mfma_f32_16x16x32_bf16 v[96:99], v[178:181], v[194:197], v[96:99]
	v_mfma_f32_16x16x32_bf16 v[84:87], v[170:173], v[202:205], v[84:87]
	v_mfma_f32_16x16x32_bf16 v[80:83], v[178:181], v[202:205], v[80:83]
	v_mfma_f32_16x16x32_bf16 v[68:71], v[170:173], v[210:213], v[68:71]
	v_mfma_f32_16x16x32_bf16 v[64:67], v[178:181], v[210:213], v[64:67]
	v_mfma_f32_16x16x32_bf16 v[60:63], v[144:147], v[220:223], v[60:63]
	v_mfma_f32_16x16x32_bf16 v[56:59], v[158:161], v[220:223], v[56:59]
	v_mfma_f32_16x16x32_bf16 v[44:47], v[144:147], v[228:231], v[44:47]
	v_mfma_f32_16x16x32_bf16 v[40:43], v[158:161], v[228:231], v[40:43]
	v_mfma_f32_16x16x32_bf16 v[28:31], v[144:147], v[236:239], v[28:31]
	v_mfma_f32_16x16x32_bf16 v[24:27], v[158:161], v[236:239], v[24:27]
	v_mfma_f32_16x16x32_bf16 v[12:15], v[144:147], v[244:247], v[12:15]
	v_mfma_f32_16x16x32_bf16 v[8:11], v[158:161], v[244:247], v[8:11]
	v_mfma_f32_16x16x32_bf16 v[60:63], v[154:157], v[224:227], v[60:63]
	v_mfma_f32_16x16x32_bf16 v[56:59], v[162:165], v[224:227], v[56:59]
	v_mfma_f32_16x16x32_bf16 v[44:47], v[154:157], v[232:235], v[44:47]
	v_mfma_f32_16x16x32_bf16 v[40:43], v[162:165], v[232:235], v[40:43]
	v_mfma_f32_16x16x32_bf16 v[28:31], v[154:157], v[240:243], v[28:31]
	v_mfma_f32_16x16x32_bf16 v[24:27], v[162:165], v[240:243], v[24:27]
	v_mfma_f32_16x16x32_bf16 v[12:15], v[154:157], v[248:251], v[12:15]
	v_mfma_f32_16x16x32_bf16 v[8:11], v[162:165], v[248:251], v[8:11]
	v_mfma_f32_16x16x32_bf16 v[52:55], v[166:169], v[220:223], v[52:55]
	v_mfma_f32_16x16x32_bf16 v[48:51], v[174:177], v[220:223], v[48:51]
	v_mfma_f32_16x16x32_bf16 v[36:39], v[166:169], v[228:231], v[36:39]
	v_mfma_f32_16x16x32_bf16 v[32:35], v[174:177], v[228:231], v[32:35]
	v_mfma_f32_16x16x32_bf16 v[20:23], v[166:169], v[236:239], v[20:23]
	v_mfma_f32_16x16x32_bf16 v[16:19], v[174:177], v[236:239], v[16:19]
	v_mfma_f32_16x16x32_bf16 v[4:7], v[166:169], v[244:247], v[4:7]
	v_mfma_f32_16x16x32_bf16 v[0:3], v[174:177], v[244:247], v[0:3]
	v_mfma_f32_16x16x32_bf16 v[52:55], v[170:173], v[224:227], v[52:55]
	v_mfma_f32_16x16x32_bf16 v[48:51], v[178:181], v[224:227], v[48:51]
	v_mfma_f32_16x16x32_bf16 v[36:39], v[170:173], v[232:235], v[36:39]
	v_mfma_f32_16x16x32_bf16 v[32:35], v[178:181], v[232:235], v[32:35]
	v_mfma_f32_16x16x32_bf16 v[20:23], v[170:173], v[240:243], v[20:23]
	v_mfma_f32_16x16x32_bf16 v[16:19], v[178:181], v[240:243], v[16:19]
	v_mfma_f32_16x16x32_bf16 v[4:7], v[170:173], v[248:251], v[4:7]
	v_mfma_f32_16x16x32_bf16 v[0:3], v[178:181], v[248:251], v[0:3]
	s_waitcnt vmcnt(0)
	s_barrier
	s_add_i32 s56, s56, 2
	s_add_u32 s12, s12, 0x100
	s_addc_u32 s13, s13, 0
	s_add_u32 s54, s54, 0x100
	s_addc_u32 s55, s55, 0
	s_cmp_gt_u32 s56, 13
	s_cbranch_scc0 .LBB0_686
	s_branch .Lk64_done_p4
.Lk64_trail_p4:
	s_sub_u32 vcc_lo, s12, 0x40000
	s_subb_u32 vcc_hi, s13, 0
	s_add_i32 m0, s36, 0xa000
	s_nop 0
	global_load_lds_dwordx4 v130, vcc
	s_add_u32 vcc_lo, vcc_lo, 0x10000
	s_addc_u32 vcc_hi, vcc_hi, 0
	s_add_i32 m0, s36, 0x9000
	s_nop 0
	global_load_lds_dwordx4 v134, vcc
	s_add_u32 vcc_lo, vcc_lo, 0x30000
	s_addc_u32 vcc_hi, vcc_hi, 0
	s_add_i32 m0, s36, 0xe000
	s_nop 0
	global_load_lds_dwordx4 v130, vcc
	s_add_u32 vcc_lo, vcc_lo, 0x10000
	s_addc_u32 vcc_hi, vcc_hi, 0
	s_add_i32 m0, s36, 0xd000
	s_nop 0
	global_load_lds_dwordx4 v134, vcc
	s_add_u32 vcc_lo, s34, 0x0
	s_addc_u32 vcc_hi, s35, 0
	s_mov_b32 m0, s36
	s_nop 0
	global_load_lds_dwordx4 v134, vcc
	s_sub_u32 vcc_lo, vcc_lo, 0x10000
	s_subb_u32 vcc_hi, vcc_hi, 0
	s_sub_i32 m0, s36, 0x1000
	s_nop 0
	global_load_lds_dwordx4 v134, vcc
	s_add_u32 vcc_lo, vcc_lo, 0x50000
	s_addc_u32 vcc_hi, vcc_hi, 0
	s_add_i32 m0, s36, 0x4000
	s_nop 0
	global_load_lds_dwordx4 v134, vcc
	s_sub_u32 vcc_lo, vcc_lo, 0x10000
	s_subb_u32 vcc_hi, vcc_hi, 0
	s_add_i32 m0, s36, 0x3000
	s_nop 0
	global_load_lds_dwordx4 v134, vcc
	ds_read_b128 v[144:147], v151 offset:0
	ds_read_b128 v[154:157], v151 offset:1024
	ds_read_b128 v[158:161], v151 offset:2048
	ds_read_b128 v[162:165], v151 offset:3072
	ds_read_b128 v[166:169], v152 offset:0
	ds_read_b128 v[170:173], v152 offset:1024
	ds_read_b128 v[174:177], v152 offset:2048
	ds_read_b128 v[178:181], v152 offset:3072
	ds_read_b128 v[182:185], v153 offset:0
	ds_read_b128 v[186:189], v153 offset:1024
	ds_read_b128 v[190:193], v153 offset:2048
	ds_read_b128 v[194:197], v153 offset:3072
	ds_read_b128 v[198:201], v153 offset:4096
	ds_read_b128 v[202:205], v153 offset:5120
	ds_read_b128 v[206:209], v153 offset:6144
	ds_read_b128 v[210:213], v153 offset:7168
	ds_read_b128 v[220:223], v153 offset:16384
	ds_read_b128 v[224:227], v153 offset:17408
	ds_read_b128 v[228:231], v153 offset:18432
	ds_read_b128 v[232:235], v153 offset:19456
	ds_read_b128 v[236:239], v153 offset:20480
	ds_read_b128 v[240:243], v153 offset:21504
	ds_read_b128 v[244:247], v153 offset:22528
	ds_read_b128 v[248:251], v153 offset:23552
	s_waitcnt lgkmcnt(0)
	s_barrier
	v_mfma_f32_16x16x32_bf16 v[124:127], v[144:147], v[182:185], v[124:127]
	v_mfma_f32_16x16x32_bf16 v[120:123], v[158:161], v[182:185], v[120:123]
	v_mfma_f32_16x16x32_bf16 v[108:111], v[144:147], v[190:193], v[108:111]
	v_mfma_f32_16x16x32_bf16 v[104:107], v[158:161], v[190:193], v[104:107]
	v_mfma_f32_16x16x32_bf16 v[92:95], v[144:147], v[198:201], v[92:95]
	v_mfma_f32_16x16x32_bf16 v[88:91], v[158:161], v[198:201], v[88:91]
	v_mfma_f32_16x16x32_bf16 v[76:79], v[144:147], v[206:209], v[76:79]
	v_mfma_f32_16x16x32_bf16 v[72:75], v[158:161], v[206:209], v[72:75]
	v_mfma_f32_16x16x32_bf16 v[124:127], v[154:157], v[186:189], v[124:127]
	v_mfma_f32_16x16x32_bf16 v[120:123], v[162:165], v[186:189], v[120:123]
	v_mfma_f32_16x16x32_bf16 v[108:111], v[154:157], v[194:197], v[108:111]
	v_mfma_f32_16x16x32_bf16 v[104:107], v[162:165], v[194:197], v[104:107]
	v_mfma_f32_16x16x32_bf16 v[92:95], v[154:157], v[202:205], v[92:95]
	v_mfma_f32_16x16x32_bf16 v[88:91], v[162:165], v[202:205], v[88:91]
	v_mfma_f32_16x16x32_bf16 v[76:79], v[154:157], v[210:213], v[76:79]
	v_mfma_f32_16x16x32_bf16 v[72:75], v[162:165], v[210:213], v[72:75]
	v_mfma_f32_16x16x32_bf16 v[116:119], v[166:169], v[182:185], v[116:119]
	v_mfma_f32_16x16x32_bf16 v[112:115], v[174:177], v[182:185], v[112:115]
	v_mfma_f32_16x16x32_bf16 v[100:103], v[166:169], v[190:193], v[100:103]
	v_mfma_f32_16x16x32_bf16 v[96:99], v[174:177], v[190:193], v[96:99]
	v_mfma_f32_16x16x32_bf16 v[84:87], v[166:169], v[198:201], v[84:87]
	v_mfma_f32_16x16x32_bf16 v[80:83], v[174:177], v[198:201], v[80:83]
	v_mfma_f32_16x16x32_bf16 v[68:71], v[166:169], v[206:209], v[68:71]
	v_mfma_f32_16x16x32_bf16 v[64:67], v[174:177], v[206:209], v[64:67]
	v_mfma_f32_16x16x32_bf16 v[116:119], v[170:173], v[186:189], v[116:119]
	v_mfma_f32_16x16x32_bf16 v[112:115], v[178:181], v[186:189], v[112:115]
	v_mfma_f32_16x16x32_bf16 v[100:103], v[170:173], v[194:197], v[100:103]
	v_mfma_f32_16x16x32_bf16 v[96:99], v[178:181], v[194:197], v[96:99]
	v_mfma_f32_16x16x32_bf16 v[84:87], v[170:173], v[202:205], v[84:87]
	v_mfma_f32_16x16x32_bf16 v[80:83], v[178:181], v[202:205], v[80:83]
	v_mfma_f32_16x16x32_bf16 v[68:71], v[170:173], v[210:213], v[68:71]
	v_mfma_f32_16x16x32_bf16 v[64:67], v[178:181], v[210:213], v[64:67]
	v_mfma_f32_16x16x32_bf16 v[60:63], v[144:147], v[220:223], v[60:63]
	v_mfma_f32_16x16x32_bf16 v[56:59], v[158:161], v[220:223], v[56:59]
	v_mfma_f32_16x16x32_bf16 v[44:47], v[144:147], v[228:231], v[44:47]
	v_mfma_f32_16x16x32_bf16 v[40:43], v[158:161], v[228:231], v[40:43]
	v_mfma_f32_16x16x32_bf16 v[28:31], v[144:147], v[236:239], v[28:31]
	v_mfma_f32_16x16x32_bf16 v[24:27], v[158:161], v[236:239], v[24:27]
	v_mfma_f32_16x16x32_bf16 v[12:15], v[144:147], v[244:247], v[12:15]
	v_mfma_f32_16x16x32_bf16 v[8:11], v[158:161], v[244:247], v[8:11]
	v_mfma_f32_16x16x32_bf16 v[60:63], v[154:157], v[224:227], v[60:63]
	v_mfma_f32_16x16x32_bf16 v[56:59], v[162:165], v[224:227], v[56:59]
	v_mfma_f32_16x16x32_bf16 v[44:47], v[154:157], v[232:235], v[44:47]
	v_mfma_f32_16x16x32_bf16 v[40:43], v[162:165], v[232:235], v[40:43]
	v_mfma_f32_16x16x32_bf16 v[28:31], v[154:157], v[240:243], v[28:31]
	v_mfma_f32_16x16x32_bf16 v[24:27], v[162:165], v[240:243], v[24:27]
	v_mfma_f32_16x16x32_bf16 v[12:15], v[154:157], v[248:251], v[12:15]
	v_mfma_f32_16x16x32_bf16 v[8:11], v[162:165], v[248:251], v[8:11]
	v_mfma_f32_16x16x32_bf16 v[52:55], v[166:169], v[220:223], v[52:55]
	v_mfma_f32_16x16x32_bf16 v[48:51], v[174:177], v[220:223], v[48:51]
	v_mfma_f32_16x16x32_bf16 v[36:39], v[166:169], v[228:231], v[36:39]
	v_mfma_f32_16x16x32_bf16 v[32:35], v[174:177], v[228:231], v[32:35]
	v_mfma_f32_16x16x32_bf16 v[20:23], v[166:169], v[236:239], v[20:23]
	v_mfma_f32_16x16x32_bf16 v[16:19], v[174:177], v[236:239], v[16:19]
	v_mfma_f32_16x16x32_bf16 v[4:7], v[166:169], v[244:247], v[4:7]
	v_mfma_f32_16x16x32_bf16 v[0:3], v[174:177], v[244:247], v[0:3]
	v_mfma_f32_16x16x32_bf16 v[52:55], v[170:173], v[224:227], v[52:55]
	v_mfma_f32_16x16x32_bf16 v[48:51], v[178:181], v[224:227], v[48:51]
	v_mfma_f32_16x16x32_bf16 v[36:39], v[170:173], v[232:235], v[36:39]
	v_mfma_f32_16x16x32_bf16 v[32:35], v[178:181], v[232:235], v[32:35]
	v_mfma_f32_16x16x32_bf16 v[20:23], v[170:173], v[240:243], v[20:23]
	v_mfma_f32_16x16x32_bf16 v[16:19], v[178:181], v[240:243], v[16:19]
	v_mfma_f32_16x16x32_bf16 v[4:7], v[170:173], v[248:251], v[4:7]
	v_mfma_f32_16x16x32_bf16 v[0:3], v[178:181], v[248:251], v[0:3]
	s_waitcnt vmcnt(0)
	s_barrier
	s_add_u32 vcc_lo, s34, 0x0
	s_addc_u32 vcc_hi, s35, 0
	s_add_i32 m0, s36, 0x2000
	s_nop 0
	global_load_lds_dwordx4 v130, vcc
	s_add_u32 vcc_lo, vcc_lo, 0x10000
	s_addc_u32 vcc_hi, vcc_hi, 0
	s_add_i32 m0, s36, 0x1000
	s_nop 0
	global_load_lds_dwordx4 v134, vcc
	s_add_u32 vcc_lo, vcc_lo, 0x30000
	s_addc_u32 vcc_hi, vcc_hi, 0
	s_add_i32 m0, s36, 0x6000
	s_nop 0
	global_load_lds_dwordx4 v130, vcc
	s_add_u32 vcc_lo, vcc_lo, 0x10000
	s_addc_u32 vcc_hi, vcc_hi, 0
	s_add_i32 m0, s36, 0x5000
	s_nop 0
	global_load_lds_dwordx4 v134, vcc
	s_add_u32 vcc_lo, s34, 0x80
	s_addc_u32 vcc_hi, s35, 0
	s_add_i32 m0, s36, 0x8000
	s_nop 0
	global_load_lds_dwordx4 v134, vcc
	s_sub_u32 vcc_lo, vcc_lo, 0x10000
	s_subb_u32 vcc_hi, vcc_hi, 0
	s_add_i32 m0, s36, 0x7000
	s_nop 0
	global_load_lds_dwordx4 v134, vcc
	s_add_u32 vcc_lo, vcc_lo, 0x50000
	s_addc_u32 vcc_hi, vcc_hi, 0
	s_add_i32 m0, s36, 0xc000
	s_nop 0
	global_load_lds_dwordx4 v134, vcc
	s_sub_u32 vcc_lo, vcc_lo, 0x10000
	s_subb_u32 vcc_hi, vcc_hi, 0
	s_add_i32 m0, s36, 0xb000
	s_nop 0
	global_load_lds_dwordx4 v134, vcc
	ds_read_b128 v[144:147], v151 offset:32768
	ds_read_b128 v[154:157], v151 offset:33792
	ds_read_b128 v[158:161], v151 offset:34816
	ds_read_b128 v[162:165], v151 offset:35840
	ds_read_b128 v[166:169], v152 offset:32768
	ds_read_b128 v[170:173], v152 offset:33792
	ds_read_b128 v[174:177], v152 offset:34816
	ds_read_b128 v[178:181], v152 offset:35840
	ds_read_b128 v[182:185], v153 offset:32768
	ds_read_b128 v[186:189], v153 offset:33792
	ds_read_b128 v[190:193], v153 offset:34816
	ds_read_b128 v[194:197], v153 offset:35840
	ds_read_b128 v[198:201], v153 offset:36864
	ds_read_b128 v[202:205], v153 offset:37888
	ds_read_b128 v[206:209], v153 offset:38912
	ds_read_b128 v[210:213], v153 offset:39936
	ds_read_b128 v[220:223], v153 offset:49152
	ds_read_b128 v[224:227], v153 offset:50176
	ds_read_b128 v[228:231], v153 offset:51200
	ds_read_b128 v[232:235], v153 offset:52224
	ds_read_b128 v[236:239], v153 offset:53248
	ds_read_b128 v[240:243], v153 offset:54272
	ds_read_b128 v[244:247], v153 offset:55296
	ds_read_b128 v[248:251], v153 offset:56320
	s_waitcnt lgkmcnt(0)
	s_barrier
	v_mfma_f32_16x16x32_bf16 v[124:127], v[144:147], v[182:185], v[124:127]
	v_mfma_f32_16x16x32_bf16 v[120:123], v[158:161], v[182:185], v[120:123]
	v_mfma_f32_16x16x32_bf16 v[108:111], v[144:147], v[190:193], v[108:111]
	v_mfma_f32_16x16x32_bf16 v[104:107], v[158:161], v[190:193], v[104:107]
	v_mfma_f32_16x16x32_bf16 v[92:95], v[144:147], v[198:201], v[92:95]
	v_mfma_f32_16x16x32_bf16 v[88:91], v[158:161], v[198:201], v[88:91]
	v_mfma_f32_16x16x32_bf16 v[76:79], v[144:147], v[206:209], v[76:79]
	v_mfma_f32_16x16x32_bf16 v[72:75], v[158:161], v[206:209], v[72:75]
	v_mfma_f32_16x16x32_bf16 v[124:127], v[154:157], v[186:189], v[124:127]
	v_mfma_f32_16x16x32_bf16 v[120:123], v[162:165], v[186:189], v[120:123]
	v_mfma_f32_16x16x32_bf16 v[108:111], v[154:157], v[194:197], v[108:111]
	v_mfma_f32_16x16x32_bf16 v[104:107], v[162:165], v[194:197], v[104:107]
	v_mfma_f32_16x16x32_bf16 v[92:95], v[154:157], v[202:205], v[92:95]
	v_mfma_f32_16x16x32_bf16 v[88:91], v[162:165], v[202:205], v[88:91]
	v_mfma_f32_16x16x32_bf16 v[76:79], v[154:157], v[210:213], v[76:79]
	v_mfma_f32_16x16x32_bf16 v[72:75], v[162:165], v[210:213], v[72:75]
	v_mfma_f32_16x16x32_bf16 v[116:119], v[166:169], v[182:185], v[116:119]
	v_mfma_f32_16x16x32_bf16 v[112:115], v[174:177], v[182:185], v[112:115]
	v_mfma_f32_16x16x32_bf16 v[100:103], v[166:169], v[190:193], v[100:103]
	v_mfma_f32_16x16x32_bf16 v[96:99], v[174:177], v[190:193], v[96:99]
	v_mfma_f32_16x16x32_bf16 v[84:87], v[166:169], v[198:201], v[84:87]
	v_mfma_f32_16x16x32_bf16 v[80:83], v[174:177], v[198:201], v[80:83]
	v_mfma_f32_16x16x32_bf16 v[68:71], v[166:169], v[206:209], v[68:71]
	v_mfma_f32_16x16x32_bf16 v[64:67], v[174:177], v[206:209], v[64:67]
	v_mfma_f32_16x16x32_bf16 v[116:119], v[170:173], v[186:189], v[116:119]
	v_mfma_f32_16x16x32_bf16 v[112:115], v[178:181], v[186:189], v[112:115]
	v_mfma_f32_16x16x32_bf16 v[100:103], v[170:173], v[194:197], v[100:103]
	v_mfma_f32_16x16x32_bf16 v[96:99], v[178:181], v[194:197], v[96:99]
	v_mfma_f32_16x16x32_bf16 v[84:87], v[170:173], v[202:205], v[84:87]
	v_mfma_f32_16x16x32_bf16 v[80:83], v[178:181], v[202:205], v[80:83]
	v_mfma_f32_16x16x32_bf16 v[68:71], v[170:173], v[210:213], v[68:71]
	v_mfma_f32_16x16x32_bf16 v[64:67], v[178:181], v[210:213], v[64:67]
	v_mfma_f32_16x16x32_bf16 v[60:63], v[144:147], v[220:223], v[60:63]
	v_mfma_f32_16x16x32_bf16 v[56:59], v[158:161], v[220:223], v[56:59]
	v_mfma_f32_16x16x32_bf16 v[44:47], v[144:147], v[228:231], v[44:47]
	v_mfma_f32_16x16x32_bf16 v[40:43], v[158:161], v[228:231], v[40:43]
	v_mfma_f32_16x16x32_bf16 v[28:31], v[144:147], v[236:239], v[28:31]
	v_mfma_f32_16x16x32_bf16 v[24:27], v[158:161], v[236:239], v[24:27]
	v_mfma_f32_16x16x32_bf16 v[12:15], v[144:147], v[244:247], v[12:15]
	v_mfma_f32_16x16x32_bf16 v[8:11], v[158:161], v[244:247], v[8:11]
	v_mfma_f32_16x16x32_bf16 v[60:63], v[154:157], v[224:227], v[60:63]
	v_mfma_f32_16x16x32_bf16 v[56:59], v[162:165], v[224:227], v[56:59]
	v_mfma_f32_16x16x32_bf16 v[44:47], v[154:157], v[232:235], v[44:47]
	v_mfma_f32_16x16x32_bf16 v[40:43], v[162:165], v[232:235], v[40:43]
	v_mfma_f32_16x16x32_bf16 v[28:31], v[154:157], v[240:243], v[28:31]
	v_mfma_f32_16x16x32_bf16 v[24:27], v[162:165], v[240:243], v[24:27]
	v_mfma_f32_16x16x32_bf16 v[12:15], v[154:157], v[248:251], v[12:15]
	v_mfma_f32_16x16x32_bf16 v[8:11], v[162:165], v[248:251], v[8:11]
	v_mfma_f32_16x16x32_bf16 v[52:55], v[166:169], v[220:223], v[52:55]
	v_mfma_f32_16x16x32_bf16 v[48:51], v[174:177], v[220:223], v[48:51]
	v_mfma_f32_16x16x32_bf16 v[36:39], v[166:169], v[228:231], v[36:39]
	v_mfma_f32_16x16x32_bf16 v[32:35], v[174:177], v[228:231], v[32:35]
	v_mfma_f32_16x16x32_bf16 v[20:23], v[166:169], v[236:239], v[20:23]
	v_mfma_f32_16x16x32_bf16 v[16:19], v[174:177], v[236:239], v[16:19]
	v_mfma_f32_16x16x32_bf16 v[4:7], v[166:169], v[244:247], v[4:7]
	v_mfma_f32_16x16x32_bf16 v[0:3], v[174:177], v[244:247], v[0:3]
	v_mfma_f32_16x16x32_bf16 v[52:55], v[170:173], v[224:227], v[52:55]
	v_mfma_f32_16x16x32_bf16 v[48:51], v[178:181], v[224:227], v[48:51]
	v_mfma_f32_16x16x32_bf16 v[36:39], v[170:173], v[232:235], v[36:39]
	v_mfma_f32_16x16x32_bf16 v[32:35], v[178:181], v[232:235], v[32:35]
	v_mfma_f32_16x16x32_bf16 v[20:23], v[170:173], v[240:243], v[20:23]
	v_mfma_f32_16x16x32_bf16 v[16:19], v[178:181], v[240:243], v[16:19]
	v_mfma_f32_16x16x32_bf16 v[4:7], v[170:173], v[248:251], v[4:7]
	v_mfma_f32_16x16x32_bf16 v[0:3], v[178:181], v[248:251], v[0:3]
	s_waitcnt vmcnt(0)
	s_barrier
	s_add_i32 s56, s56, 2
	s_add_u32 s12, s12, 0x100
	s_addc_u32 s13, s13, 0
	s_add_u32 s54, s54, 0x100
	s_addc_u32 s55, s55, 0
	s_cmp_gt_u32 s56, 13
	s_cbranch_scc0 .LBB0_686

.LBB0_761:
	s_add_u32 s36, s34, 0xfff80080
	s_addc_u32 s37, s35, -1
	s_cmp_eq_u32 s58, 28
	s_cselect_b32 s43, s23, s37
	s_cselect_b32 s42, s29, s36
	s_cselect_b32 s37, s13, s57
	s_cselect_b32 s36, s31, s56
	s_and_b64 vcc, exec, s[10:11]
	s_cbranch_vccz .Lk64_trail_p5
	s_setprio 1
	s_sub_u32 vcc_lo, s56, 0x80
	s_subb_u32 vcc_hi, s57, 0
	s_add_i32 m0, s44, 0x18000
	s_nop 0
	global_load_lds_dwordx4 v130, vcc
	s_add_i32 m0, s44, 0x1a000
	s_nop 0
	global_load_lds_dwordx4 v134, vcc
	s_add_u32 vcc_lo, vcc_lo, 0x20000
	s_addc_u32 vcc_hi, vcc_hi, 0
	s_add_i32 m0, s44, 0x19000
	s_nop 0
	global_load_lds_dwordx4 v130, vcc
	s_add_i32 m0, s44, 0x1b000
	s_nop 0
	global_load_lds_dwordx4 v134, vcc
	s_add_u32 vcc_lo, vcc_lo, 0x60000
	s_addc_u32 vcc_hi, vcc_hi, 0
	s_add_i32 m0, s44, 0x1c000
	s_nop 0
	global_load_lds_dwordx4 v130, vcc
	s_add_i32 m0, s44, 0x1e000
	s_nop 0
	global_load_lds_dwordx4 v134, vcc
	s_add_u32 vcc_lo, vcc_lo, 0x20000
	s_addc_u32 vcc_hi, vcc_hi, 0
	s_add_i32 m0, s44, 0x1d000
	s_nop 0
	global_load_lds_dwordx4 v130, vcc
	s_add_i32 m0, s44, 0x1f000
	s_nop 0
	global_load_lds_dwordx4 v134, vcc
	ds_read_b128 v[144:147], v153 offset:0
	ds_read_b128 v[158:161], v153 offset:1024
	ds_read_b128 v[162:165], v153 offset:2048
	ds_read_b128 v[166:169], v153 offset:3072
	ds_read_b128 v[170:173], v154 offset:0
	ds_read_b128 v[174:177], v154 offset:1024
	ds_read_b128 v[178:181], v154 offset:2048
	ds_read_b128 v[182:185], v154 offset:3072
	ds_read_b128 v[186:189], v155 offset:0
	ds_read_b128 v[190:193], v155 offset:1024
	ds_read_b128 v[194:197], v155 offset:2048
	ds_read_b128 v[198:201], v155 offset:3072
	ds_read_b128 v[202:205], v155 offset:4096
	ds_read_b128 v[206:209], v155 offset:5120
	ds_read_b128 v[210:213], v155 offset:6144
	ds_read_b128 v[214:217], v155 offset:7168
	ds_read_b128 v[220:223], v155 offset:16384
	ds_read_b128 v[224:227], v155 offset:17408
	ds_read_b128 v[228:231], v155 offset:18432
	ds_read_b128 v[232:235], v155 offset:19456
	ds_read_b128 v[236:239], v155 offset:20480
	ds_read_b128 v[240:243], v155 offset:21504
	ds_read_b128 v[244:247], v155 offset:22528
	ds_read_b128 v[248:251], v155 offset:23552
	s_waitcnt lgkmcnt(0)
	s_barrier
	v_mfma_f32_16x16x32_bf16 v[124:127], v[144:147], v[186:189], v[124:127]
	v_mfma_f32_16x16x32_bf16 v[120:123], v[162:165], v[186:189], v[120:123]
	v_mfma_f32_16x16x32_bf16 v[108:111], v[144:147], v[194:197], v[108:111]
	v_mfma_f32_16x16x32_bf16 v[104:107], v[162:165], v[194:197], v[104:107]
	v_mfma_f32_16x16x32_bf16 v[92:95], v[144:147], v[202:205], v[92:95]
	v_mfma_f32_16x16x32_bf16 v[88:91], v[162:165], v[202:205], v[88:91]
	v_mfma_f32_16x16x32_bf16 v[76:79], v[144:147], v[210:213], v[76:79]
	v_mfma_f32_16x16x32_bf16 v[72:75], v[162:165], v[210:213], v[72:75]
	v_mfma_f32_16x16x32_bf16 v[124:127], v[158:161], v[190:193], v[124:127]
	v_mfma_f32_16x16x32_bf16 v[120:123], v[166:169], v[190:193], v[120:123]
	v_mfma_f32_16x16x32_bf16 v[108:111], v[158:161], v[198:201], v[108:111]
	v_mfma_f32_16x16x32_bf16 v[104:107], v[166:169], v[198:201], v[104:107]
	v_mfma_f32_16x16x32_bf16 v[92:95], v[158:161], v[206:209], v[92:95]
	v_mfma_f32_16x16x32_bf16 v[88:91], v[166:169], v[206:209], v[88:91]
	v_mfma_f32_16x16x32_bf16 v[76:79], v[158:161], v[214:217], v[76:79]
	v_mfma_f32_16x16x32_bf16 v[72:75], v[166:169], v[214:217], v[72:75]
	v_mfma_f32_16x16x32_bf16 v[116:119], v[170:173], v[186:189], v[116:119]
	v_mfma_f32_16x16x32_bf16 v[112:115], v[178:181], v[186:189], v[112:115]
	v_mfma_f32_16x16x32_bf16 v[100:103], v[170:173], v[194:197], v[100:103]
	v_mfma_f32_16x16x32_bf16 v[96:99], v[178:181], v[194:197], v[96:99]
	v_mfma_f32_16x16x32_bf16 v[84:87], v[170:173], v[202:205], v[84:87]
	v_mfma_f32_16x16x32_bf16 v[80:83], v[178:181], v[202:205], v[80:83]
	v_mfma_f32_16x16x32_bf16 v[68:71], v[170:173], v[210:213], v[68:71]
	v_mfma_f32_16x16x32_bf16 v[64:67], v[178:181], v[210:213], v[64:67]
	v_mfma_f32_16x16x32_bf16 v[116:119], v[174:177], v[190:193], v[116:119]
	v_mfma_f32_16x16x32_bf16 v[112:115], v[182:185], v[190:193], v[112:115]
	v_mfma_f32_16x16x32_bf16 v[100:103], v[174:177], v[198:201], v[100:103]
	v_mfma_f32_16x16x32_bf16 v[96:99], v[182:185], v[198:201], v[96:99]
	v_mfma_f32_16x16x32_bf16 v[84:87], v[174:177], v[206:209], v[84:87]
	v_mfma_f32_16x16x32_bf16 v[80:83], v[182:185], v[206:209], v[80:83]
	v_mfma_f32_16x16x32_bf16 v[68:71], v[174:177], v[214:217], v[68:71]
	v_mfma_f32_16x16x32_bf16 v[64:67], v[182:185], v[214:217], v[64:67]
	v_mfma_f32_16x16x32_bf16 v[60:63], v[144:147], v[220:223], v[60:63]
	v_mfma_f32_16x16x32_bf16 v[56:59], v[162:165], v[220:223], v[56:59]
	v_mfma_f32_16x16x32_bf16 v[44:47], v[144:147], v[228:231], v[44:47]
	v_mfma_f32_16x16x32_bf16 v[40:43], v[162:165], v[228:231], v[40:43]
	v_mfma_f32_16x16x32_bf16 v[28:31], v[144:147], v[236:239], v[28:31]
	v_mfma_f32_16x16x32_bf16 v[24:27], v[162:165], v[236:239], v[24:27]
	v_mfma_f32_16x16x32_bf16 v[12:15], v[144:147], v[244:247], v[12:15]
	v_mfma_f32_16x16x32_bf16 v[8:11], v[162:165], v[244:247], v[8:11]
	v_mfma_f32_16x16x32_bf16 v[60:63], v[158:161], v[224:227], v[60:63]
	v_mfma_f32_16x16x32_bf16 v[56:59], v[166:169], v[224:227], v[56:59]
	v_mfma_f32_16x16x32_bf16 v[44:47], v[158:161], v[232:235], v[44:47]
	v_mfma_f32_16x16x32_bf16 v[40:43], v[166:169], v[232:235], v[40:43]
	v_mfma_f32_16x16x32_bf16 v[28:31], v[158:161], v[240:243], v[28:31]
	v_mfma_f32_16x16x32_bf16 v[24:27], v[166:169], v[240:243], v[24:27]
	v_mfma_f32_16x16x32_bf16 v[12:15], v[158:161], v[248:251], v[12:15]
	v_mfma_f32_16x16x32_bf16 v[8:11], v[166:169], v[248:251], v[8:11]
	v_mfma_f32_16x16x32_bf16 v[52:55], v[170:173], v[220:223], v[52:55]
	v_mfma_f32_16x16x32_bf16 v[48:51], v[178:181], v[220:223], v[48:51]
	v_mfma_f32_16x16x32_bf16 v[36:39], v[170:173], v[228:231], v[36:39]
	v_mfma_f32_16x16x32_bf16 v[32:35], v[178:181], v[228:231], v[32:35]
	v_mfma_f32_16x16x32_bf16 v[20:23], v[170:173], v[236:239], v[20:23]
	v_mfma_f32_16x16x32_bf16 v[16:19], v[178:181], v[236:239], v[16:19]
	v_mfma_f32_16x16x32_bf16 v[4:7], v[170:173], v[244:247], v[4:7]
	v_mfma_f32_16x16x32_bf16 v[0:3], v[178:181], v[244:247], v[0:3]
	v_mfma_f32_16x16x32_bf16 v[52:55], v[174:177], v[224:227], v[52:55]
	v_mfma_f32_16x16x32_bf16 v[48:51], v[182:185], v[224:227], v[48:51]
	v_mfma_f32_16x16x32_bf16 v[36:39], v[174:177], v[232:235], v[36:39]
	v_mfma_f32_16x16x32_bf16 v[32:35], v[182:185], v[232:235], v[32:35]
	v_mfma_f32_16x16x32_bf16 v[20:23], v[174:177], v[240:243], v[20:23]
	v_mfma_f32_16x16x32_bf16 v[16:19], v[182:185], v[240:243], v[16:19]
	v_mfma_f32_16x16x32_bf16 v[4:7], v[174:177], v[248:251], v[4:7]
	v_mfma_f32_16x16x32_bf16 v[0:3], v[182:185], v[248:251], v[0:3]
	s_waitcnt vmcnt(0)
	s_barrier
	s_add_u32 vcc_lo, s36, 0x0
	s_addc_u32 vcc_hi, s37, 0
	s_add_i32 m0, s44, 0x10000
	s_nop 0
	global_load_lds_dwordx4 v130, vcc
	s_add_i32 m0, s44, 0x12000
	s_nop 0
	global_load_lds_dwordx4 v134, vcc
	s_add_u32 vcc_lo, vcc_lo, 0x20000
	s_addc_u32 vcc_hi, vcc_hi, 0
	s_add_i32 m0, s44, 0x11000
	s_nop 0
	global_load_lds_dwordx4 v130, vcc
	s_add_i32 m0, s44, 0x13000
	s_nop 0
	global_load_lds_dwordx4 v134, vcc
	s_add_u32 vcc_lo, vcc_lo, 0x60000
	s_addc_u32 vcc_hi, vcc_hi, 0
	s_add_i32 m0, s44, 0x14000
	s_nop 0
	global_load_lds_dwordx4 v130, vcc
	s_add_i32 m0, s44, 0x16000
	s_nop 0
	global_load_lds_dwordx4 v134, vcc
	s_add_u32 vcc_lo, vcc_lo, 0x20000
	s_addc_u32 vcc_hi, vcc_hi, 0
	s_add_i32 m0, s44, 0x15000
	s_nop 0
	global_load_lds_dwordx4 v130, vcc
	s_add_i32 m0, s44, 0x17000
	s_nop 0
	global_load_lds_dwordx4 v134, vcc
	ds_read_b128 v[144:147], v153 offset:32768
	ds_read_b128 v[158:161], v153 offset:33792
	ds_read_b128 v[162:165], v153 offset:34816
	ds_read_b128 v[166:169], v153 offset:35840
	ds_read_b128 v[170:173], v154 offset:32768
	ds_read_b128 v[174:177], v154 offset:33792
	ds_read_b128 v[178:181], v154 offset:34816
	ds_read_b128 v[182:185], v154 offset:35840
	ds_read_b128 v[186:189], v155 offset:32768
	ds_read_b128 v[190:193], v155 offset:33792
	ds_read_b128 v[194:197], v155 offset:34816
	ds_read_b128 v[198:201], v155 offset:35840
	ds_read_b128 v[202:205], v155 offset:36864
	ds_read_b128 v[206:209], v155 offset:37888
	ds_read_b128 v[210:213], v155 offset:38912
	ds_read_b128 v[214:217], v155 offset:39936
	ds_read_b128 v[220:223], v155 offset:49152
	ds_read_b128 v[224:227], v155 offset:50176
	ds_read_b128 v[228:231], v155 offset:51200
	ds_read_b128 v[232:235], v155 offset:52224
	ds_read_b128 v[236:239], v155 offset:53248
	ds_read_b128 v[240:243], v155 offset:54272
	ds_read_b128 v[244:247], v155 offset:55296
	ds_read_b128 v[248:251], v155 offset:56320
	s_waitcnt lgkmcnt(0)
	s_barrier
	v_mfma_f32_16x16x32_bf16 v[124:127], v[144:147], v[186:189], v[124:127]
	v_mfma_f32_16x16x32_bf16 v[120:123], v[162:165], v[186:189], v[120:123]
	v_mfma_f32_16x16x32_bf16 v[108:111], v[144:147], v[194:197], v[108:111]
	v_mfma_f32_16x16x32_bf16 v[104:107], v[162:165], v[194:197], v[104:107]
	v_mfma_f32_16x16x32_bf16 v[92:95], v[144:147], v[202:205], v[92:95]
	v_mfma_f32_16x16x32_bf16 v[88:91], v[162:165], v[202:205], v[88:91]
	v_mfma_f32_16x16x32_bf16 v[76:79], v[144:147], v[210:213], v[76:79]
	v_mfma_f32_16x16x32_bf16 v[72:75], v[162:165], v[210:213], v[72:75]
	v_mfma_f32_16x16x32_bf16 v[124:127], v[158:161], v[190:193], v[124:127]
	v_mfma_f32_16x16x32_bf16 v[120:123], v[166:169], v[190:193], v[120:123]
	v_mfma_f32_16x16x32_bf16 v[108:111], v[158:161], v[198:201], v[108:111]
	v_mfma_f32_16x16x32_bf16 v[104:107], v[166:169], v[198:201], v[104:107]
	v_mfma_f32_16x16x32_bf16 v[92:95], v[158:161], v[206:209], v[92:95]
	v_mfma_f32_16x16x32_bf16 v[88:91], v[166:169], v[206:209], v[88:91]
	v_mfma_f32_16x16x32_bf16 v[76:79], v[158:161], v[214:217], v[76:79]
	v_mfma_f32_16x16x32_bf16 v[72:75], v[166:169], v[214:217], v[72:75]
	v_mfma_f32_16x16x32_bf16 v[116:119], v[170:173], v[186:189], v[116:119]
	v_mfma_f32_16x16x32_bf16 v[112:115], v[178:181], v[186:189], v[112:115]
	v_mfma_f32_16x16x32_bf16 v[100:103], v[170:173], v[194:197], v[100:103]
	v_mfma_f32_16x16x32_bf16 v[96:99], v[178:181], v[194:197], v[96:99]
	v_mfma_f32_16x16x32_bf16 v[84:87], v[170:173], v[202:205], v[84:87]
	v_mfma_f32_16x16x32_bf16 v[80:83], v[178:181], v[202:205], v[80:83]
	v_mfma_f32_16x16x32_bf16 v[68:71], v[170:173], v[210:213], v[68:71]
	v_mfma_f32_16x16x32_bf16 v[64:67], v[178:181], v[210:213], v[64:67]
	v_mfma_f32_16x16x32_bf16 v[116:119], v[174:177], v[190:193], v[116:119]
	v_mfma_f32_16x16x32_bf16 v[112:115], v[182:185], v[190:193], v[112:115]
	v_mfma_f32_16x16x32_bf16 v[100:103], v[174:177], v[198:201], v[100:103]
	v_mfma_f32_16x16x32_bf16 v[96:99], v[182:185], v[198:201], v[96:99]
	v_mfma_f32_16x16x32_bf16 v[84:87], v[174:177], v[206:209], v[84:87]
	v_mfma_f32_16x16x32_bf16 v[80:83], v[182:185], v[206:209], v[80:83]
	v_mfma_f32_16x16x32_bf16 v[68:71], v[174:177], v[214:217], v[68:71]
	v_mfma_f32_16x16x32_bf16 v[64:67], v[182:185], v[214:217], v[64:67]
	v_mfma_f32_16x16x32_bf16 v[60:63], v[144:147], v[220:223], v[60:63]
	v_mfma_f32_16x16x32_bf16 v[56:59], v[162:165], v[220:223], v[56:59]
	v_mfma_f32_16x16x32_bf16 v[44:47], v[144:147], v[228:231], v[44:47]
	v_mfma_f32_16x16x32_bf16 v[40:43], v[162:165], v[228:231], v[40:43]
	v_mfma_f32_16x16x32_bf16 v[28:31], v[144:147], v[236:239], v[28:31]
	v_mfma_f32_16x16x32_bf16 v[24:27], v[162:165], v[236:239], v[24:27]
	v_mfma_f32_16x16x32_bf16 v[12:15], v[144:147], v[244:247], v[12:15]
	v_mfma_f32_16x16x32_bf16 v[8:11], v[162:165], v[244:247], v[8:11]
	v_mfma_f32_16x16x32_bf16 v[60:63], v[158:161], v[224:227], v[60:63]
	v_mfma_f32_16x16x32_bf16 v[56:59], v[166:169], v[224:227], v[56:59]
	v_mfma_f32_16x16x32_bf16 v[44:47], v[158:161], v[232:235], v[44:47]
	v_mfma_f32_16x16x32_bf16 v[40:43], v[166:169], v[232:235], v[40:43]
	v_mfma_f32_16x16x32_bf16 v[28:31], v[158:161], v[240:243], v[28:31]
	v_mfma_f32_16x16x32_bf16 v[24:27], v[166:169], v[240:243], v[24:27]
	v_mfma_f32_16x16x32_bf16 v[12:15], v[158:161], v[248:251], v[12:15]
	v_mfma_f32_16x16x32_bf16 v[8:11], v[166:169], v[248:251], v[8:11]
	v_mfma_f32_16x16x32_bf16 v[52:55], v[170:173], v[220:223], v[52:55]
	v_mfma_f32_16x16x32_bf16 v[48:51], v[178:181], v[220:223], v[48:51]
	v_mfma_f32_16x16x32_bf16 v[36:39], v[170:173], v[228:231], v[36:39]
	v_mfma_f32_16x16x32_bf16 v[32:35], v[178:181], v[228:231], v[32:35]
	v_mfma_f32_16x16x32_bf16 v[20:23], v[170:173], v[236:239], v[20:23]
	v_mfma_f32_16x16x32_bf16 v[16:19], v[178:181], v[236:239], v[16:19]
	v_mfma_f32_16x16x32_bf16 v[4:7], v[170:173], v[244:247], v[4:7]
	v_mfma_f32_16x16x32_bf16 v[0:3], v[178:181], v[244:247], v[0:3]
	v_mfma_f32_16x16x32_bf16 v[52:55], v[174:177], v[224:227], v[52:55]
	v_mfma_f32_16x16x32_bf16 v[48:51], v[182:185], v[224:227], v[48:51]
	v_mfma_f32_16x16x32_bf16 v[36:39], v[174:177], v[232:235], v[36:39]
	v_mfma_f32_16x16x32_bf16 v[32:35], v[182:185], v[232:235], v[32:35]
	v_mfma_f32_16x16x32_bf16 v[20:23], v[174:177], v[240:243], v[20:23]
	v_mfma_f32_16x16x32_bf16 v[16:19], v[182:185], v[240:243], v[16:19]
	v_mfma_f32_16x16x32_bf16 v[4:7], v[174:177], v[248:251], v[4:7]
	v_mfma_f32_16x16x32_bf16 v[0:3], v[182:185], v[248:251], v[0:3]
	s_waitcnt vmcnt(0)
	s_barrier
	s_add_i32 s58, s58, 2
	s_add_u32 s34, s34, 0x100
	s_addc_u32 s35, s35, 0
	s_add_u32 s56, s56, 0x100
	s_addc_u32 s57, s57, 0
	s_cmp_gt_u32 s58, 29
	s_cbranch_scc0 .LBB0_761
	s_branch .Lk64_done_p5
.Lk64_trail_p5:
	s_sub_u32 vcc_lo, s34, 0x80000
	s_subb_u32 vcc_hi, s35, 0
	s_add_i32 m0, s44, 0xa000
	s_nop 0
	global_load_lds_dwordx4 v132, vcc
	s_add_u32 vcc_lo, vcc_lo, 0x20000
	s_addc_u32 vcc_hi, vcc_hi, 0
	s_add_i32 m0, s44, 0x9000
	s_nop 0
	global_load_lds_dwordx4 v128, vcc
	s_add_u32 vcc_lo, vcc_lo, 0x60000
	s_addc_u32 vcc_hi, vcc_hi, 0
	s_add_i32 m0, s44, 0xe000
	s_nop 0
	global_load_lds_dwordx4 v132, vcc
	s_add_u32 vcc_lo, vcc_lo, 0x20000
	s_addc_u32 vcc_hi, vcc_hi, 0
	s_add_i32 m0, s44, 0xd000
	s_nop 0
	global_load_lds_dwordx4 v128, vcc
	s_add_u32 vcc_lo, s42, 0x0
	s_addc_u32 vcc_hi, s43, 0
	s_mov_b32 m0, s44
	s_nop 0
	global_load_lds_dwordx4 v128, vcc
	s_sub_u32 vcc_lo, vcc_lo, 0x20000
	s_subb_u32 vcc_hi, vcc_hi, 0
	s_sub_i32 m0, s44, 0x1000
	s_nop 0
	global_load_lds_dwordx4 v128, vcc
	s_add_u32 vcc_lo, vcc_lo, 0xa0000
	s_addc_u32 vcc_hi, vcc_hi, 0
	s_add_i32 m0, s44, 0x4000
	s_nop 0
	global_load_lds_dwordx4 v128, vcc
	s_sub_u32 vcc_lo, vcc_lo, 0x20000
	s_subb_u32 vcc_hi, vcc_hi, 0
	s_add_i32 m0, s44, 0x3000
	s_nop 0
	global_load_lds_dwordx4 v128, vcc
	ds_read_b128 v[144:147], v153 offset:0
	ds_read_b128 v[158:161], v153 offset:1024
	ds_read_b128 v[162:165], v153 offset:2048
	ds_read_b128 v[166:169], v153 offset:3072
	ds_read_b128 v[170:173], v154 offset:0
	ds_read_b128 v[174:177], v154 offset:1024
	ds_read_b128 v[178:181], v154 offset:2048
	ds_read_b128 v[182:185], v154 offset:3072
	ds_read_b128 v[186:189], v155 offset:0
	ds_read_b128 v[190:193], v155 offset:1024
	ds_read_b128 v[194:197], v155 offset:2048
	ds_read_b128 v[198:201], v155 offset:3072
	ds_read_b128 v[202:205], v155 offset:4096
	ds_read_b128 v[206:209], v155 offset:5120
	ds_read_b128 v[210:213], v155 offset:6144
	ds_read_b128 v[214:217], v155 offset:7168
	ds_read_b128 v[220:223], v155 offset:16384
	ds_read_b128 v[224:227], v155 offset:17408
	ds_read_b128 v[228:231], v155 offset:18432
	ds_read_b128 v[232:235], v155 offset:19456
	ds_read_b128 v[236:239], v155 offset:20480
	ds_read_b128 v[240:243], v155 offset:21504
	ds_read_b128 v[244:247], v155 offset:22528
	ds_read_b128 v[248:251], v155 offset:23552
	s_waitcnt lgkmcnt(0)
	s_barrier
	v_mfma_f32_16x16x32_bf16 v[124:127], v[144:147], v[186:189], v[124:127]
	v_mfma_f32_16x16x32_bf16 v[120:123], v[162:165], v[186:189], v[120:123]
	v_mfma_f32_16x16x32_bf16 v[108:111], v[144:147], v[194:197], v[108:111]
	v_mfma_f32_16x16x32_bf16 v[104:107], v[162:165], v[194:197], v[104:107]
	v_mfma_f32_16x16x32_bf16 v[92:95], v[144:147], v[202:205], v[92:95]
	v_mfma_f32_16x16x32_bf16 v[88:91], v[162:165], v[202:205], v[88:91]
	v_mfma_f32_16x16x32_bf16 v[76:79], v[144:147], v[210:213], v[76:79]
	v_mfma_f32_16x16x32_bf16 v[72:75], v[162:165], v[210:213], v[72:75]
	v_mfma_f32_16x16x32_bf16 v[124:127], v[158:161], v[190:193], v[124:127]
	v_mfma_f32_16x16x32_bf16 v[120:123], v[166:169], v[190:193], v[120:123]
	v_mfma_f32_16x16x32_bf16 v[108:111], v[158:161], v[198:201], v[108:111]
	v_mfma_f32_16x16x32_bf16 v[104:107], v[166:169], v[198:201], v[104:107]
	v_mfma_f32_16x16x32_bf16 v[92:95], v[158:161], v[206:209], v[92:95]
	v_mfma_f32_16x16x32_bf16 v[88:91], v[166:169], v[206:209], v[88:91]
	v_mfma_f32_16x16x32_bf16 v[76:79], v[158:161], v[214:217], v[76:79]
	v_mfma_f32_16x16x32_bf16 v[72:75], v[166:169], v[214:217], v[72:75]
	v_mfma_f32_16x16x32_bf16 v[116:119], v[170:173], v[186:189], v[116:119]
	v_mfma_f32_16x16x32_bf16 v[112:115], v[178:181], v[186:189], v[112:115]
	v_mfma_f32_16x16x32_bf16 v[100:103], v[170:173], v[194:197], v[100:103]
	v_mfma_f32_16x16x32_bf16 v[96:99], v[178:181], v[194:197], v[96:99]
	v_mfma_f32_16x16x32_bf16 v[84:87], v[170:173], v[202:205], v[84:87]
	v_mfma_f32_16x16x32_bf16 v[80:83], v[178:181], v[202:205], v[80:83]
	v_mfma_f32_16x16x32_bf16 v[68:71], v[170:173], v[210:213], v[68:71]
	v_mfma_f32_16x16x32_bf16 v[64:67], v[178:181], v[210:213], v[64:67]
	v_mfma_f32_16x16x32_bf16 v[116:119], v[174:177], v[190:193], v[116:119]
	v_mfma_f32_16x16x32_bf16 v[112:115], v[182:185], v[190:193], v[112:115]
	v_mfma_f32_16x16x32_bf16 v[100:103], v[174:177], v[198:201], v[100:103]
	v_mfma_f32_16x16x32_bf16 v[96:99], v[182:185], v[198:201], v[96:99]
	v_mfma_f32_16x16x32_bf16 v[84:87], v[174:177], v[206:209], v[84:87]
	v_mfma_f32_16x16x32_bf16 v[80:83], v[182:185], v[206:209], v[80:83]
	v_mfma_f32_16x16x32_bf16 v[68:71], v[174:177], v[214:217], v[68:71]
	v_mfma_f32_16x16x32_bf16 v[64:67], v[182:185], v[214:217], v[64:67]
	v_mfma_f32_16x16x32_bf16 v[60:63], v[144:147], v[220:223], v[60:63]
	v_mfma_f32_16x16x32_bf16 v[56:59], v[162:165], v[220:223], v[56:59]
	v_mfma_f32_16x16x32_bf16 v[44:47], v[144:147], v[228:231], v[44:47]
	v_mfma_f32_16x16x32_bf16 v[40:43], v[162:165], v[228:231], v[40:43]
	v_mfma_f32_16x16x32_bf16 v[28:31], v[144:147], v[236:239], v[28:31]
	v_mfma_f32_16x16x32_bf16 v[24:27], v[162:165], v[236:239], v[24:27]
	v_mfma_f32_16x16x32_bf16 v[12:15], v[144:147], v[244:247], v[12:15]
	v_mfma_f32_16x16x32_bf16 v[8:11], v[162:165], v[244:247], v[8:11]
	v_mfma_f32_16x16x32_bf16 v[60:63], v[158:161], v[224:227], v[60:63]
	v_mfma_f32_16x16x32_bf16 v[56:59], v[166:169], v[224:227], v[56:59]
	v_mfma_f32_16x16x32_bf16 v[44:47], v[158:161], v[232:235], v[44:47]
	v_mfma_f32_16x16x32_bf16 v[40:43], v[166:169], v[232:235], v[40:43]
	v_mfma_f32_16x16x32_bf16 v[28:31], v[158:161], v[240:243], v[28:31]
	v_mfma_f32_16x16x32_bf16 v[24:27], v[166:169], v[240:243], v[24:27]
	v_mfma_f32_16x16x32_bf16 v[12:15], v[158:161], v[248:251], v[12:15]
	v_mfma_f32_16x16x32_bf16 v[8:11], v[166:169], v[248:251], v[8:11]
	v_mfma_f32_16x16x32_bf16 v[52:55], v[170:173], v[220:223], v[52:55]
	v_mfma_f32_16x16x32_bf16 v[48:51], v[178:181], v[220:223], v[48:51]
	v_mfma_f32_16x16x32_bf16 v[36:39], v[170:173], v[228:231], v[36:39]
	v_mfma_f32_16x16x32_bf16 v[32:35], v[178:181], v[228:231], v[32:35]
	v_mfma_f32_16x16x32_bf16 v[20:23], v[170:173], v[236:239], v[20:23]
	v_mfma_f32_16x16x32_bf16 v[16:19], v[178:181], v[236:239], v[16:19]
	v_mfma_f32_16x16x32_bf16 v[4:7], v[170:173], v[244:247], v[4:7]
	v_mfma_f32_16x16x32_bf16 v[0:3], v[178:181], v[244:247], v[0:3]
	v_mfma_f32_16x16x32_bf16 v[52:55], v[174:177], v[224:227], v[52:55]
	v_mfma_f32_16x16x32_bf16 v[48:51], v[182:185], v[224:227], v[48:51]
	v_mfma_f32_16x16x32_bf16 v[36:39], v[174:177], v[232:235], v[36:39]
	v_mfma_f32_16x16x32_bf16 v[32:35], v[182:185], v[232:235], v[32:35]
	v_mfma_f32_16x16x32_bf16 v[20:23], v[174:177], v[240:243], v[20:23]
	v_mfma_f32_16x16x32_bf16 v[16:19], v[182:185], v[240:243], v[16:19]
	v_mfma_f32_16x16x32_bf16 v[4:7], v[174:177], v[248:251], v[4:7]
	v_mfma_f32_16x16x32_bf16 v[0:3], v[182:185], v[248:251], v[0:3]
	s_waitcnt vmcnt(0)
	s_barrier
	s_add_u32 vcc_lo, s42, 0x0
	s_addc_u32 vcc_hi, s43, 0
	s_add_i32 m0, s44, 0x2000
	s_nop 0
	global_load_lds_dwordx4 v132, vcc
	s_add_u32 vcc_lo, vcc_lo, 0x20000
	s_addc_u32 vcc_hi, vcc_hi, 0
	s_add_i32 m0, s44, 0x1000
	s_nop 0
	global_load_lds_dwordx4 v128, vcc
	s_add_u32 vcc_lo, vcc_lo, 0x60000
	s_addc_u32 vcc_hi, vcc_hi, 0
	s_add_i32 m0, s44, 0x6000
	s_nop 0
	global_load_lds_dwordx4 v132, vcc
	s_add_u32 vcc_lo, vcc_lo, 0x20000
	s_addc_u32 vcc_hi, vcc_hi, 0
	s_add_i32 m0, s44, 0x5000
	s_nop 0
	global_load_lds_dwordx4 v128, vcc
	s_add_u32 vcc_lo, s42, 0x80
	s_addc_u32 vcc_hi, s43, 0
	s_add_i32 m0, s44, 0x8000
	s_nop 0
	global_load_lds_dwordx4 v128, vcc
	s_sub_u32 vcc_lo, vcc_lo, 0x20000
	s_subb_u32 vcc_hi, vcc_hi, 0
	s_add_i32 m0, s44, 0x7000
	s_nop 0
	global_load_lds_dwordx4 v128, vcc
	s_add_u32 vcc_lo, vcc_lo, 0xa0000
	s_addc_u32 vcc_hi, vcc_hi, 0
	s_add_i32 m0, s44, 0xc000
	s_nop 0
	global_load_lds_dwordx4 v128, vcc
	s_sub_u32 vcc_lo, vcc_lo, 0x20000
	s_subb_u32 vcc_hi, vcc_hi, 0
	s_add_i32 m0, s44, 0xb000
	s_nop 0
	global_load_lds_dwordx4 v128, vcc
	ds_read_b128 v[144:147], v153 offset:32768
	ds_read_b128 v[158:161], v153 offset:33792
	ds_read_b128 v[162:165], v153 offset:34816
	ds_read_b128 v[166:169], v153 offset:35840
	ds_read_b128 v[170:173], v154 offset:32768
	ds_read_b128 v[174:177], v154 offset:33792
	ds_read_b128 v[178:181], v154 offset:34816
	ds_read_b128 v[182:185], v154 offset:35840
	ds_read_b128 v[186:189], v155 offset:32768
	ds_read_b128 v[190:193], v155 offset:33792
	ds_read_b128 v[194:197], v155 offset:34816
	ds_read_b128 v[198:201], v155 offset:35840
	ds_read_b128 v[202:205], v155 offset:36864
	ds_read_b128 v[206:209], v155 offset:37888
	ds_read_b128 v[210:213], v155 offset:38912
	ds_read_b128 v[214:217], v155 offset:39936
	ds_read_b128 v[220:223], v155 offset:49152
	ds_read_b128 v[224:227], v155 offset:50176
	ds_read_b128 v[228:231], v155 offset:51200
	ds_read_b128 v[232:235], v155 offset:52224
	ds_read_b128 v[236:239], v155 offset:53248
	ds_read_b128 v[240:243], v155 offset:54272
	ds_read_b128 v[244:247], v155 offset:55296
	ds_read_b128 v[248:251], v155 offset:56320
	s_waitcnt lgkmcnt(0)
	s_barrier
	v_mfma_f32_16x16x32_bf16 v[124:127], v[144:147], v[186:189], v[124:127]
	v_mfma_f32_16x16x32_bf16 v[120:123], v[162:165], v[186:189], v[120:123]
	v_mfma_f32_16x16x32_bf16 v[108:111], v[144:147], v[194:197], v[108:111]
	v_mfma_f32_16x16x32_bf16 v[104:107], v[162:165], v[194:197], v[104:107]
	v_mfma_f32_16x16x32_bf16 v[92:95], v[144:147], v[202:205], v[92:95]
	v_mfma_f32_16x16x32_bf16 v[88:91], v[162:165], v[202:205], v[88:91]
	v_mfma_f32_16x16x32_bf16 v[76:79], v[144:147], v[210:213], v[76:79]
	v_mfma_f32_16x16x32_bf16 v[72:75], v[162:165], v[210:213], v[72:75]
	v_mfma_f32_16x16x32_bf16 v[124:127], v[158:161], v[190:193], v[124:127]
	v_mfma_f32_16x16x32_bf16 v[120:123], v[166:169], v[190:193], v[120:123]
	v_mfma_f32_16x16x32_bf16 v[108:111], v[158:161], v[198:201], v[108:111]
	v_mfma_f32_16x16x32_bf16 v[104:107], v[166:169], v[198:201], v[104:107]
	v_mfma_f32_16x16x32_bf16 v[92:95], v[158:161], v[206:209], v[92:95]
	v_mfma_f32_16x16x32_bf16 v[88:91], v[166:169], v[206:209], v[88:91]
	v_mfma_f32_16x16x32_bf16 v[76:79], v[158:161], v[214:217], v[76:79]
	v_mfma_f32_16x16x32_bf16 v[72:75], v[166:169], v[214:217], v[72:75]
	v_mfma_f32_16x16x32_bf16 v[116:119], v[170:173], v[186:189], v[116:119]
	v_mfma_f32_16x16x32_bf16 v[112:115], v[178:181], v[186:189], v[112:115]
	v_mfma_f32_16x16x32_bf16 v[100:103], v[170:173], v[194:197], v[100:103]
	v_mfma_f32_16x16x32_bf16 v[96:99], v[178:181], v[194:197], v[96:99]
	v_mfma_f32_16x16x32_bf16 v[84:87], v[170:173], v[202:205], v[84:87]
	v_mfma_f32_16x16x32_bf16 v[80:83], v[178:181], v[202:205], v[80:83]
	v_mfma_f32_16x16x32_bf16 v[68:71], v[170:173], v[210:213], v[68:71]
	v_mfma_f32_16x16x32_bf16 v[64:67], v[178:181], v[210:213], v[64:67]
	v_mfma_f32_16x16x32_bf16 v[116:119], v[174:177], v[190:193], v[116:119]
	v_mfma_f32_16x16x32_bf16 v[112:115], v[182:185], v[190:193], v[112:115]
	v_mfma_f32_16x16x32_bf16 v[100:103], v[174:177], v[198:201], v[100:103]
	v_mfma_f32_16x16x32_bf16 v[96:99], v[182:185], v[198:201], v[96:99]
	v_mfma_f32_16x16x32_bf16 v[84:87], v[174:177], v[206:209], v[84:87]
	v_mfma_f32_16x16x32_bf16 v[80:83], v[182:185], v[206:209], v[80:83]
	v_mfma_f32_16x16x32_bf16 v[68:71], v[174:177], v[214:217], v[68:71]
	v_mfma_f32_16x16x32_bf16 v[64:67], v[182:185], v[214:217], v[64:67]
	v_mfma_f32_16x16x32_bf16 v[60:63], v[144:147], v[220:223], v[60:63]
	v_mfma_f32_16x16x32_bf16 v[56:59], v[162:165], v[220:223], v[56:59]
	v_mfma_f32_16x16x32_bf16 v[44:47], v[144:147], v[228:231], v[44:47]
	v_mfma_f32_16x16x32_bf16 v[40:43], v[162:165], v[228:231], v[40:43]
	v_mfma_f32_16x16x32_bf16 v[28:31], v[144:147], v[236:239], v[28:31]
	v_mfma_f32_16x16x32_bf16 v[24:27], v[162:165], v[236:239], v[24:27]
	v_mfma_f32_16x16x32_bf16 v[12:15], v[144:147], v[244:247], v[12:15]
	v_mfma_f32_16x16x32_bf16 v[8:11], v[162:165], v[244:247], v[8:11]
	v_mfma_f32_16x16x32_bf16 v[60:63], v[158:161], v[224:227], v[60:63]
	v_mfma_f32_16x16x32_bf16 v[56:59], v[166:169], v[224:227], v[56:59]
	v_mfma_f32_16x16x32_bf16 v[44:47], v[158:161], v[232:235], v[44:47]
	v_mfma_f32_16x16x32_bf16 v[40:43], v[166:169], v[232:235], v[40:43]
	v_mfma_f32_16x16x32_bf16 v[28:31], v[158:161], v[240:243], v[28:31]
	v_mfma_f32_16x16x32_bf16 v[24:27], v[166:169], v[240:243], v[24:27]
	v_mfma_f32_16x16x32_bf16 v[12:15], v[158:161], v[248:251], v[12:15]
	v_mfma_f32_16x16x32_bf16 v[8:11], v[166:169], v[248:251], v[8:11]
	v_mfma_f32_16x16x32_bf16 v[52:55], v[170:173], v[220:223], v[52:55]
	v_mfma_f32_16x16x32_bf16 v[48:51], v[178:181], v[220:223], v[48:51]
	v_mfma_f32_16x16x32_bf16 v[36:39], v[170:173], v[228:231], v[36:39]
	v_mfma_f32_16x16x32_bf16 v[32:35], v[178:181], v[228:231], v[32:35]
	v_mfma_f32_16x16x32_bf16 v[20:23], v[170:173], v[236:239], v[20:23]
	v_mfma_f32_16x16x32_bf16 v[16:19], v[178:181], v[236:239], v[16:19]
	v_mfma_f32_16x16x32_bf16 v[4:7], v[170:173], v[244:247], v[4:7]
	v_mfma_f32_16x16x32_bf16 v[0:3], v[178:181], v[244:247], v[0:3]
	v_mfma_f32_16x16x32_bf16 v[52:55], v[174:177], v[224:227], v[52:55]
	v_mfma_f32_16x16x32_bf16 v[48:51], v[182:185], v[224:227], v[48:51]
	v_mfma_f32_16x16x32_bf16 v[36:39], v[174:177], v[232:235], v[36:39]
	v_mfma_f32_16x16x32_bf16 v[32:35], v[182:185], v[232:235], v[32:35]
	v_mfma_f32_16x16x32_bf16 v[20:23], v[174:177], v[240:243], v[20:23]
	v_mfma_f32_16x16x32_bf16 v[16:19], v[182:185], v[240:243], v[16:19]
	v_mfma_f32_16x16x32_bf16 v[4:7], v[174:177], v[248:251], v[4:7]
	v_mfma_f32_16x16x32_bf16 v[0:3], v[182:185], v[248:251], v[0:3]
	s_waitcnt vmcnt(0)
	s_barrier
	s_add_i32 s58, s58, 2
	s_add_u32 s34, s34, 0x100
	s_addc_u32 s35, s35, 0
	s_add_u32 s56, s56, 0x100
	s_addc_u32 s57, s57, 0
	s_cmp_gt_u32 s58, 29
	s_cbranch_scc0 .LBB0_761

.Lk64_epd_p6_l:
	ds_read_b128 v[32:35], v169 offset:0
	ds_read_b128 v[36:39], v169 offset:1024
	ds_read_b128 v[40:43], v169 offset:2048
	ds_read_b128 v[44:47], v169 offset:3072
	ds_read_b128 v[162:165], v170 offset:0
	ds_read_b128 v[174:177], v170 offset:1024
	ds_read_b128 v[178:181], v170 offset:2048
	ds_read_b128 v[182:185], v170 offset:3072
	ds_read_b128 v[186:189], v171 offset:0
	ds_read_b128 v[190:193], v171 offset:1024
	ds_read_b128 v[194:197], v171 offset:2048
	ds_read_b128 v[198:201], v171 offset:3072
	ds_read_b128 v[202:205], v171 offset:4096
	ds_read_b128 v[206:209], v171 offset:5120
	ds_read_b128 v[210:213], v171 offset:6144
	ds_read_b128 v[214:217], v171 offset:7168
	ds_read_b128 v[220:223], v171 offset:16384
	ds_read_b128 v[224:227], v171 offset:17408
	ds_read_b128 v[228:231], v171 offset:18432
	ds_read_b128 v[232:235], v171 offset:19456
	ds_read_b128 v[236:239], v171 offset:20480
	ds_read_b128 v[240:243], v171 offset:21504
	ds_read_b128 v[244:247], v171 offset:22528
	ds_read_b128 v[248:251], v171 offset:23552
	s_waitcnt lgkmcnt(0)
	s_barrier
	v_mfma_f32_16x16x32_bf16 v[140:143], v[32:35], v[186:189], v[140:143]
	v_mfma_f32_16x16x32_bf16 v[136:139], v[40:43], v[186:189], v[136:139]
	v_mfma_f32_16x16x32_bf16 v[124:127], v[32:35], v[194:197], v[124:127]
	v_mfma_f32_16x16x32_bf16 v[120:123], v[40:43], v[194:197], v[120:123]
	v_mfma_f32_16x16x32_bf16 v[108:111], v[32:35], v[202:205], v[108:111]
	v_mfma_f32_16x16x32_bf16 v[104:107], v[40:43], v[202:205], v[104:107]
	v_mfma_f32_16x16x32_bf16 v[92:95], v[32:35], v[210:213], v[92:95]
	v_mfma_f32_16x16x32_bf16 v[88:91], v[40:43], v[210:213], v[88:91]
	v_mfma_f32_16x16x32_bf16 v[140:143], v[36:39], v[190:193], v[140:143]
	v_mfma_f32_16x16x32_bf16 v[136:139], v[44:47], v[190:193], v[136:139]
	v_mfma_f32_16x16x32_bf16 v[124:127], v[36:39], v[198:201], v[124:127]
	v_mfma_f32_16x16x32_bf16 v[120:123], v[44:47], v[198:201], v[120:123]
	v_mfma_f32_16x16x32_bf16 v[108:111], v[36:39], v[206:209], v[108:111]
	v_mfma_f32_16x16x32_bf16 v[104:107], v[44:47], v[206:209], v[104:107]
	v_mfma_f32_16x16x32_bf16 v[92:95], v[36:39], v[214:217], v[92:95]
	v_mfma_f32_16x16x32_bf16 v[88:91], v[44:47], v[214:217], v[88:91]
	v_mfma_f32_16x16x32_bf16 v[132:135], v[162:165], v[186:189], v[132:135]
	v_mfma_f32_16x16x32_bf16 v[128:131], v[178:181], v[186:189], v[128:131]
	v_mfma_f32_16x16x32_bf16 v[116:119], v[162:165], v[194:197], v[116:119]
	v_mfma_f32_16x16x32_bf16 v[112:115], v[178:181], v[194:197], v[112:115]
	v_mfma_f32_16x16x32_bf16 v[100:103], v[162:165], v[202:205], v[100:103]
	v_mfma_f32_16x16x32_bf16 v[96:99], v[178:181], v[202:205], v[96:99]
	v_mfma_f32_16x16x32_bf16 v[84:87], v[162:165], v[210:213], v[84:87]
	v_mfma_f32_16x16x32_bf16 v[80:83], v[178:181], v[210:213], v[80:83]
	v_mfma_f32_16x16x32_bf16 v[132:135], v[174:177], v[190:193], v[132:135]
	v_mfma_f32_16x16x32_bf16 v[128:131], v[182:185], v[190:193], v[128:131]
	v_mfma_f32_16x16x32_bf16 v[116:119], v[174:177], v[198:201], v[116:119]
	v_mfma_f32_16x16x32_bf16 v[112:115], v[182:185], v[198:201], v[112:115]
	v_mfma_f32_16x16x32_bf16 v[100:103], v[174:177], v[206:209], v[100:103]
	v_mfma_f32_16x16x32_bf16 v[96:99], v[182:185], v[206:209], v[96:99]
	v_mfma_f32_16x16x32_bf16 v[84:87], v[174:177], v[214:217], v[84:87]
	v_mfma_f32_16x16x32_bf16 v[80:83], v[182:185], v[214:217], v[80:83]
	v_mfma_f32_16x16x32_bf16 v[76:79], v[32:35], v[220:223], v[76:79]
	v_mfma_f32_16x16x32_bf16 v[72:75], v[40:43], v[220:223], v[72:75]
	v_mfma_f32_16x16x32_bf16 v[60:63], v[32:35], v[228:231], v[60:63]
	v_mfma_f32_16x16x32_bf16 v[56:59], v[40:43], v[228:231], v[56:59]
	v_mfma_f32_16x16x32_bf16 v[28:31], v[32:35], v[236:239], v[28:31]
	v_mfma_f32_16x16x32_bf16 v[24:27], v[40:43], v[236:239], v[24:27]
	v_mfma_f32_16x16x32_bf16 v[12:15], v[32:35], v[244:247], v[12:15]
	v_mfma_f32_16x16x32_bf16 v[8:11], v[40:43], v[244:247], v[8:11]
	v_mfma_f32_16x16x32_bf16 v[76:79], v[36:39], v[224:227], v[76:79]
	v_mfma_f32_16x16x32_bf16 v[72:75], v[44:47], v[224:227], v[72:75]
	v_mfma_f32_16x16x32_bf16 v[60:63], v[36:39], v[232:235], v[60:63]
	v_mfma_f32_16x16x32_bf16 v[56:59], v[44:47], v[232:235], v[56:59]
	v_mfma_f32_16x16x32_bf16 v[28:31], v[36:39], v[240:243], v[28:31]
	v_mfma_f32_16x16x32_bf16 v[24:27], v[44:47], v[240:243], v[24:27]
	v_mfma_f32_16x16x32_bf16 v[12:15], v[36:39], v[248:251], v[12:15]
	v_mfma_f32_16x16x32_bf16 v[8:11], v[44:47], v[248:251], v[8:11]
	v_mfma_f32_16x16x32_bf16 v[68:71], v[162:165], v[220:223], v[68:71]
	v_mfma_f32_16x16x32_bf16 v[64:67], v[178:181], v[220:223], v[64:67]
	v_mfma_f32_16x16x32_bf16 v[52:55], v[162:165], v[228:231], v[52:55]
	v_mfma_f32_16x16x32_bf16 v[48:51], v[178:181], v[228:231], v[48:51]
	v_mfma_f32_16x16x32_bf16 v[20:23], v[162:165], v[236:239], v[20:23]
	v_mfma_f32_16x16x32_bf16 v[16:19], v[178:181], v[236:239], v[16:19]
	v_mfma_f32_16x16x32_bf16 v[4:7], v[162:165], v[244:247], v[4:7]
	v_mfma_f32_16x16x32_bf16 v[0:3], v[178:181], v[244:247], v[0:3]
	v_mfma_f32_16x16x32_bf16 v[68:71], v[174:177], v[224:227], v[68:71]
	v_mfma_f32_16x16x32_bf16 v[64:67], v[182:185], v[224:227], v[64:67]
	v_mfma_f32_16x16x32_bf16 v[52:55], v[174:177], v[232:235], v[52:55]
	v_mfma_f32_16x16x32_bf16 v[48:51], v[182:185], v[232:235], v[48:51]
	v_mfma_f32_16x16x32_bf16 v[20:23], v[174:177], v[240:243], v[20:23]
	v_mfma_f32_16x16x32_bf16 v[16:19], v[182:185], v[240:243], v[16:19]
	v_mfma_f32_16x16x32_bf16 v[4:7], v[174:177], v[248:251], v[4:7]
	v_mfma_f32_16x16x32_bf16 v[0:3], v[182:185], v[248:251], v[0:3]
	s_waitcnt vmcnt(0)
	s_barrier
	s_add_u32 vcc_lo, s30, 0x0
	s_addc_u32 vcc_hi, s31, 0
	s_add_i32 m0, s37, 0x10000
	s_nop 0
	global_load_lds_dwordx4 v148, vcc
	s_add_i32 m0, s37, 0x12000
	s_nop 0
	global_load_lds_dwordx4 v144, vcc
	s_add_u32 vcc_lo, vcc_lo, 0x20000
	s_addc_u32 vcc_hi, vcc_hi, 0
	s_add_i32 m0, s37, 0x11000
	s_nop 0
	global_load_lds_dwordx4 v148, vcc
	s_add_i32 m0, s37, 0x13000
	s_nop 0
	global_load_lds_dwordx4 v144, vcc
	s_add_u32 vcc_lo, vcc_lo, 0x60000
	s_addc_u32 vcc_hi, vcc_hi, 0
	s_add_i32 m0, s37, 0x14000
	s_nop 0
	global_load_lds_dwordx4 v148, vcc
	s_add_i32 m0, s37, 0x16000
	s_nop 0
	global_load_lds_dwordx4 v144, vcc
	s_add_u32 vcc_lo, vcc_lo, 0x20000
	s_addc_u32 vcc_hi, vcc_hi, 0
	s_add_i32 m0, s37, 0x15000
	s_nop 0
	global_load_lds_dwordx4 v148, vcc
	s_add_i32 m0, s37, 0x17000
	s_nop 0
	global_load_lds_dwordx4 v144, vcc
	ds_read_b128 v[32:35], v169 offset:32768
	ds_read_b128 v[36:39], v169 offset:33792
	ds_read_b128 v[40:43], v169 offset:34816
	ds_read_b128 v[44:47], v169 offset:35840
	ds_read_b128 v[162:165], v170 offset:32768
	ds_read_b128 v[174:177], v170 offset:33792
	ds_read_b128 v[178:181], v170 offset:34816
	ds_read_b128 v[182:185], v170 offset:35840
	ds_read_b128 v[186:189], v171 offset:32768
	ds_read_b128 v[190:193], v171 offset:33792
	ds_read_b128 v[194:197], v171 offset:34816
	ds_read_b128 v[198:201], v171 offset:35840
	ds_read_b128 v[202:205], v171 offset:36864
	ds_read_b128 v[206:209], v171 offset:37888
	ds_read_b128 v[210:213], v171 offset:38912
	ds_read_b128 v[214:217], v171 offset:39936
	ds_read_b128 v[220:223], v171 offset:49152
	ds_read_b128 v[224:227], v171 offset:50176
	ds_read_b128 v[228:231], v171 offset:51200
	ds_read_b128 v[232:235], v171 offset:52224
	ds_read_b128 v[236:239], v171 offset:53248
	ds_read_b128 v[240:243], v171 offset:54272
	ds_read_b128 v[244:247], v171 offset:55296
	ds_read_b128 v[248:251], v171 offset:56320
	s_waitcnt lgkmcnt(0)
	s_barrier
	v_mfma_f32_16x16x32_bf16 v[140:143], v[32:35], v[186:189], v[140:143]
	v_mfma_f32_16x16x32_bf16 v[136:139], v[40:43], v[186:189], v[136:139]
	v_mfma_f32_16x16x32_bf16 v[124:127], v[32:35], v[194:197], v[124:127]
	v_mfma_f32_16x16x32_bf16 v[120:123], v[40:43], v[194:197], v[120:123]
	v_mfma_f32_16x16x32_bf16 v[108:111], v[32:35], v[202:205], v[108:111]
	v_mfma_f32_16x16x32_bf16 v[104:107], v[40:43], v[202:205], v[104:107]
	v_mfma_f32_16x16x32_bf16 v[92:95], v[32:35], v[210:213], v[92:95]
	v_mfma_f32_16x16x32_bf16 v[88:91], v[40:43], v[210:213], v[88:91]
	v_mfma_f32_16x16x32_bf16 v[140:143], v[36:39], v[190:193], v[140:143]
	v_mfma_f32_16x16x32_bf16 v[136:139], v[44:47], v[190:193], v[136:139]
	v_mfma_f32_16x16x32_bf16 v[124:127], v[36:39], v[198:201], v[124:127]
	v_mfma_f32_16x16x32_bf16 v[120:123], v[44:47], v[198:201], v[120:123]
	v_mfma_f32_16x16x32_bf16 v[108:111], v[36:39], v[206:209], v[108:111]
	v_mfma_f32_16x16x32_bf16 v[104:107], v[44:47], v[206:209], v[104:107]
	v_mfma_f32_16x16x32_bf16 v[92:95], v[36:39], v[214:217], v[92:95]
	v_mfma_f32_16x16x32_bf16 v[88:91], v[44:47], v[214:217], v[88:91]
	v_mfma_f32_16x16x32_bf16 v[132:135], v[162:165], v[186:189], v[132:135]
	v_mfma_f32_16x16x32_bf16 v[128:131], v[178:181], v[186:189], v[128:131]
	v_mfma_f32_16x16x32_bf16 v[116:119], v[162:165], v[194:197], v[116:119]
	v_mfma_f32_16x16x32_bf16 v[112:115], v[178:181], v[194:197], v[112:115]
	v_mfma_f32_16x16x32_bf16 v[100:103], v[162:165], v[202:205], v[100:103]
	v_mfma_f32_16x16x32_bf16 v[96:99], v[178:181], v[202:205], v[96:99]
	v_mfma_f32_16x16x32_bf16 v[84:87], v[162:165], v[210:213], v[84:87]
	v_mfma_f32_16x16x32_bf16 v[80:83], v[178:181], v[210:213], v[80:83]
	v_mfma_f32_16x16x32_bf16 v[132:135], v[174:177], v[190:193], v[132:135]
	v_mfma_f32_16x16x32_bf16 v[128:131], v[182:185], v[190:193], v[128:131]
	v_mfma_f32_16x16x32_bf16 v[116:119], v[174:177], v[198:201], v[116:119]
	v_mfma_f32_16x16x32_bf16 v[112:115], v[182:185], v[198:201], v[112:115]
	v_mfma_f32_16x16x32_bf16 v[100:103], v[174:177], v[206:209], v[100:103]
	v_mfma_f32_16x16x32_bf16 v[96:99], v[182:185], v[206:209], v[96:99]
	v_mfma_f32_16x16x32_bf16 v[84:87], v[174:177], v[214:217], v[84:87]
	v_mfma_f32_16x16x32_bf16 v[80:83], v[182:185], v[214:217], v[80:83]
	v_mfma_f32_16x16x32_bf16 v[76:79], v[32:35], v[220:223], v[76:79]
	v_mfma_f32_16x16x32_bf16 v[72:75], v[40:43], v[220:223], v[72:75]
	v_mfma_f32_16x16x32_bf16 v[60:63], v[32:35], v[228:231], v[60:63]
	v_mfma_f32_16x16x32_bf16 v[56:59], v[40:43], v[228:231], v[56:59]
	v_mfma_f32_16x16x32_bf16 v[28:31], v[32:35], v[236:239], v[28:31]
	v_mfma_f32_16x16x32_bf16 v[24:27], v[40:43], v[236:239], v[24:27]
	v_mfma_f32_16x16x32_bf16 v[12:15], v[32:35], v[244:247], v[12:15]
	v_mfma_f32_16x16x32_bf16 v[8:11], v[40:43], v[244:247], v[8:11]
	v_mfma_f32_16x16x32_bf16 v[76:79], v[36:39], v[224:227], v[76:79]
	v_mfma_f32_16x16x32_bf16 v[72:75], v[44:47], v[224:227], v[72:75]
	v_mfma_f32_16x16x32_bf16 v[60:63], v[36:39], v[232:235], v[60:63]
	v_mfma_f32_16x16x32_bf16 v[56:59], v[44:47], v[232:235], v[56:59]
	v_mfma_f32_16x16x32_bf16 v[28:31], v[36:39], v[240:243], v[28:31]
	v_mfma_f32_16x16x32_bf16 v[24:27], v[44:47], v[240:243], v[24:27]
	v_mfma_f32_16x16x32_bf16 v[12:15], v[36:39], v[248:251], v[12:15]
	v_mfma_f32_16x16x32_bf16 v[8:11], v[44:47], v[248:251], v[8:11]
	v_mfma_f32_16x16x32_bf16 v[68:71], v[162:165], v[220:223], v[68:71]
	v_mfma_f32_16x16x32_bf16 v[64:67], v[178:181], v[220:223], v[64:67]
	v_mfma_f32_16x16x32_bf16 v[52:55], v[162:165], v[228:231], v[52:55]
	v_mfma_f32_16x16x32_bf16 v[48:51], v[178:181], v[228:231], v[48:51]
	v_mfma_f32_16x16x32_bf16 v[20:23], v[162:165], v[236:239], v[20:23]
	v_mfma_f32_16x16x32_bf16 v[16:19], v[178:181], v[236:239], v[16:19]
	v_mfma_f32_16x16x32_bf16 v[4:7], v[162:165], v[244:247], v[4:7]
	v_mfma_f32_16x16x32_bf16 v[0:3], v[178:181], v[244:247], v[0:3]
	v_mfma_f32_16x16x32_bf16 v[68:71], v[174:177], v[224:227], v[68:71]
	v_mfma_f32_16x16x32_bf16 v[64:67], v[182:185], v[224:227], v[64:67]
	v_mfma_f32_16x16x32_bf16 v[52:55], v[174:177], v[232:235], v[52:55]
	v_mfma_f32_16x16x32_bf16 v[48:51], v[182:185], v[232:235], v[48:51]
	v_mfma_f32_16x16x32_bf16 v[20:23], v[174:177], v[240:243], v[20:23]
	v_mfma_f32_16x16x32_bf16 v[16:19], v[182:185], v[240:243], v[16:19]
	v_mfma_f32_16x16x32_bf16 v[4:7], v[174:177], v[248:251], v[4:7]
	v_mfma_f32_16x16x32_bf16 v[0:3], v[182:185], v[248:251], v[0:3]
	s_waitcnt vmcnt(0)
	s_barrier
	s_add_i32 s56, s56, 2
	s_add_u32 s12, s12, 0x100
	s_addc_u32 s13, s13, 0
	s_add_u32 s54, s54, 0x100
	s_addc_u32 s55, s55, 0
	s_cmp_gt_u32 s56, 29
	s_cbranch_scc0 .LBB0_846
	s_branch .Lk64_done_p6

.Lk64_epd_p6_t:
	ds_read_b128 v[32:35], v169 offset:0
	ds_read_b128 v[36:39], v169 offset:1024
	ds_read_b128 v[40:43], v169 offset:2048
	ds_read_b128 v[44:47], v169 offset:3072
	ds_read_b128 v[162:165], v170 offset:0
	ds_read_b128 v[174:177], v170 offset:1024
	ds_read_b128 v[178:181], v170 offset:2048
	ds_read_b128 v[182:185], v170 offset:3072
	ds_read_b128 v[186:189], v171 offset:0
	ds_read_b128 v[190:193], v171 offset:1024
	ds_read_b128 v[194:197], v171 offset:2048
	ds_read_b128 v[198:201], v171 offset:3072
	ds_read_b128 v[202:205], v171 offset:4096
	ds_read_b128 v[206:209], v171 offset:5120
	ds_read_b128 v[210:213], v171 offset:6144
	ds_read_b128 v[214:217], v171 offset:7168
	ds_read_b128 v[220:223], v171 offset:16384
	ds_read_b128 v[224:227], v171 offset:17408
	ds_read_b128 v[228:231], v171 offset:18432
	ds_read_b128 v[232:235], v171 offset:19456
	ds_read_b128 v[236:239], v171 offset:20480
	ds_read_b128 v[240:243], v171 offset:21504
	ds_read_b128 v[244:247], v171 offset:22528
	ds_read_b128 v[248:251], v171 offset:23552
	s_waitcnt lgkmcnt(0)
	s_barrier
	v_mfma_f32_16x16x32_bf16 v[140:143], v[32:35], v[186:189], v[140:143]
	v_mfma_f32_16x16x32_bf16 v[136:139], v[40:43], v[186:189], v[136:139]
	v_mfma_f32_16x16x32_bf16 v[124:127], v[32:35], v[194:197], v[124:127]
	v_mfma_f32_16x16x32_bf16 v[120:123], v[40:43], v[194:197], v[120:123]
	v_mfma_f32_16x16x32_bf16 v[108:111], v[32:35], v[202:205], v[108:111]
	v_mfma_f32_16x16x32_bf16 v[104:107], v[40:43], v[202:205], v[104:107]
	v_mfma_f32_16x16x32_bf16 v[92:95], v[32:35], v[210:213], v[92:95]
	v_mfma_f32_16x16x32_bf16 v[88:91], v[40:43], v[210:213], v[88:91]
	v_mfma_f32_16x16x32_bf16 v[140:143], v[36:39], v[190:193], v[140:143]
	v_mfma_f32_16x16x32_bf16 v[136:139], v[44:47], v[190:193], v[136:139]
	v_mfma_f32_16x16x32_bf16 v[124:127], v[36:39], v[198:201], v[124:127]
	v_mfma_f32_16x16x32_bf16 v[120:123], v[44:47], v[198:201], v[120:123]
	v_mfma_f32_16x16x32_bf16 v[108:111], v[36:39], v[206:209], v[108:111]
	v_mfma_f32_16x16x32_bf16 v[104:107], v[44:47], v[206:209], v[104:107]
	v_mfma_f32_16x16x32_bf16 v[92:95], v[36:39], v[214:217], v[92:95]
	v_mfma_f32_16x16x32_bf16 v[88:91], v[44:47], v[214:217], v[88:91]
	v_mfma_f32_16x16x32_bf16 v[132:135], v[162:165], v[186:189], v[132:135]
	v_mfma_f32_16x16x32_bf16 v[128:131], v[178:181], v[186:189], v[128:131]
	v_mfma_f32_16x16x32_bf16 v[116:119], v[162:165], v[194:197], v[116:119]
	v_mfma_f32_16x16x32_bf16 v[112:115], v[178:181], v[194:197], v[112:115]
	v_mfma_f32_16x16x32_bf16 v[100:103], v[162:165], v[202:205], v[100:103]
	v_mfma_f32_16x16x32_bf16 v[96:99], v[178:181], v[202:205], v[96:99]
	v_mfma_f32_16x16x32_bf16 v[84:87], v[162:165], v[210:213], v[84:87]
	v_mfma_f32_16x16x32_bf16 v[80:83], v[178:181], v[210:213], v[80:83]
	v_mfma_f32_16x16x32_bf16 v[132:135], v[174:177], v[190:193], v[132:135]
	v_mfma_f32_16x16x32_bf16 v[128:131], v[182:185], v[190:193], v[128:131]
	v_mfma_f32_16x16x32_bf16 v[116:119], v[174:177], v[198:201], v[116:119]
	v_mfma_f32_16x16x32_bf16 v[112:115], v[182:185], v[198:201], v[112:115]
	v_mfma_f32_16x16x32_bf16 v[100:103], v[174:177], v[206:209], v[100:103]
	v_mfma_f32_16x16x32_bf16 v[96:99], v[182:185], v[206:209], v[96:99]
	v_mfma_f32_16x16x32_bf16 v[84:87], v[174:177], v[214:217], v[84:87]
	v_mfma_f32_16x16x32_bf16 v[80:83], v[182:185], v[214:217], v[80:83]
	v_mfma_f32_16x16x32_bf16 v[76:79], v[32:35], v[220:223], v[76:79]
	v_mfma_f32_16x16x32_bf16 v[72:75], v[40:43], v[220:223], v[72:75]
	v_mfma_f32_16x16x32_bf16 v[60:63], v[32:35], v[228:231], v[60:63]
	v_mfma_f32_16x16x32_bf16 v[56:59], v[40:43], v[228:231], v[56:59]
	v_mfma_f32_16x16x32_bf16 v[28:31], v[32:35], v[236:239], v[28:31]
	v_mfma_f32_16x16x32_bf16 v[24:27], v[40:43], v[236:239], v[24:27]
	v_mfma_f32_16x16x32_bf16 v[12:15], v[32:35], v[244:247], v[12:15]
	v_mfma_f32_16x16x32_bf16 v[8:11], v[40:43], v[244:247], v[8:11]
	v_mfma_f32_16x16x32_bf16 v[76:79], v[36:39], v[224:227], v[76:79]
	v_mfma_f32_16x16x32_bf16 v[72:75], v[44:47], v[224:227], v[72:75]
	v_mfma_f32_16x16x32_bf16 v[60:63], v[36:39], v[232:235], v[60:63]
	v_mfma_f32_16x16x32_bf16 v[56:59], v[44:47], v[232:235], v[56:59]
	v_mfma_f32_16x16x32_bf16 v[28:31], v[36:39], v[240:243], v[28:31]
	v_mfma_f32_16x16x32_bf16 v[24:27], v[44:47], v[240:243], v[24:27]
	v_mfma_f32_16x16x32_bf16 v[12:15], v[36:39], v[248:251], v[12:15]
	v_mfma_f32_16x16x32_bf16 v[8:11], v[44:47], v[248:251], v[8:11]
	v_mfma_f32_16x16x32_bf16 v[68:71], v[162:165], v[220:223], v[68:71]
	v_mfma_f32_16x16x32_bf16 v[64:67], v[178:181], v[220:223], v[64:67]
	v_mfma_f32_16x16x32_bf16 v[52:55], v[162:165], v[228:231], v[52:55]
	v_mfma_f32_16x16x32_bf16 v[48:51], v[178:181], v[228:231], v[48:51]
	v_mfma_f32_16x16x32_bf16 v[20:23], v[162:165], v[236:239], v[20:23]
	v_mfma_f32_16x16x32_bf16 v[16:19], v[178:181], v[236:239], v[16:19]
	v_mfma_f32_16x16x32_bf16 v[4:7], v[162:165], v[244:247], v[4:7]
	v_mfma_f32_16x16x32_bf16 v[0:3], v[178:181], v[244:247], v[0:3]
	v_mfma_f32_16x16x32_bf16 v[68:71], v[174:177], v[224:227], v[68:71]
	v_mfma_f32_16x16x32_bf16 v[64:67], v[182:185], v[224:227], v[64:67]
	v_mfma_f32_16x16x32_bf16 v[52:55], v[174:177], v[232:235], v[52:55]
	v_mfma_f32_16x16x32_bf16 v[48:51], v[182:185], v[232:235], v[48:51]
	v_mfma_f32_16x16x32_bf16 v[20:23], v[174:177], v[240:243], v[20:23]
	v_mfma_f32_16x16x32_bf16 v[16:19], v[182:185], v[240:243], v[16:19]
	v_mfma_f32_16x16x32_bf16 v[4:7], v[174:177], v[248:251], v[4:7]
	v_mfma_f32_16x16x32_bf16 v[0:3], v[182:185], v[248:251], v[0:3]
	s_waitcnt vmcnt(0)
	s_barrier
	s_add_u32 vcc_lo, s34, 0x0
	s_addc_u32 vcc_hi, s35, 0
	s_add_i32 m0, s37, 0x2000
	s_nop 0
	global_load_lds_dwordx4 v146, vcc
	s_add_u32 vcc_lo, vcc_lo, 0x20000
	s_addc_u32 vcc_hi, vcc_hi, 0
	s_add_i32 m0, s37, 0x1000
	s_nop 0
	global_load_lds_dwordx4 v150, vcc
	s_add_u32 vcc_lo, vcc_lo, 0x60000
	s_addc_u32 vcc_hi, vcc_hi, 0
	s_add_i32 m0, s37, 0x6000
	s_nop 0
	global_load_lds_dwordx4 v146, vcc
	s_add_u32 vcc_lo, vcc_lo, 0x20000
	s_addc_u32 vcc_hi, vcc_hi, 0
	s_add_i32 m0, s37, 0x5000
	s_nop 0
	global_load_lds_dwordx4 v150, vcc
	s_add_u32 vcc_lo, s34, 0x80
	s_addc_u32 vcc_hi, s35, 0
	s_add_i32 m0, s37, 0x8000
	s_nop 0
	global_load_lds_dwordx4 v150, vcc
	s_sub_u32 vcc_lo, vcc_lo, 0x20000
	s_subb_u32 vcc_hi, vcc_hi, 0
	s_add_i32 m0, s37, 0x7000
	s_nop 0
	global_load_lds_dwordx4 v150, vcc
	s_add_u32 vcc_lo, vcc_lo, 0xa0000
	s_addc_u32 vcc_hi, vcc_hi, 0
	s_add_i32 m0, s37, 0xc000
	s_nop 0
	global_load_lds_dwordx4 v150, vcc
	s_sub_u32 vcc_lo, vcc_lo, 0x20000
	s_subb_u32 vcc_hi, vcc_hi, 0
	s_add_i32 m0, s37, 0xb000
	s_nop 0
	global_load_lds_dwordx4 v150, vcc
	ds_read_b128 v[32:35], v169 offset:32768
	ds_read_b128 v[36:39], v169 offset:33792
	ds_read_b128 v[40:43], v169 offset:34816
	ds_read_b128 v[44:47], v169 offset:35840
	ds_read_b128 v[162:165], v170 offset:32768
	ds_read_b128 v[174:177], v170 offset:33792
	ds_read_b128 v[178:181], v170 offset:34816
	ds_read_b128 v[182:185], v170 offset:35840
	ds_read_b128 v[186:189], v171 offset:32768
	ds_read_b128 v[190:193], v171 offset:33792
	ds_read_b128 v[194:197], v171 offset:34816
	ds_read_b128 v[198:201], v171 offset:35840
	ds_read_b128 v[202:205], v171 offset:36864
	ds_read_b128 v[206:209], v171 offset:37888
	ds_read_b128 v[210:213], v171 offset:38912
	ds_read_b128 v[214:217], v171 offset:39936
	ds_read_b128 v[220:223], v171 offset:49152
	ds_read_b128 v[224:227], v171 offset:50176
	ds_read_b128 v[228:231], v171 offset:51200
	ds_read_b128 v[232:235], v171 offset:52224
	ds_read_b128 v[236:239], v171 offset:53248
	ds_read_b128 v[240:243], v171 offset:54272
	ds_read_b128 v[244:247], v171 offset:55296
	ds_read_b128 v[248:251], v171 offset:56320
	s_waitcnt lgkmcnt(0)
	s_barrier
	v_mfma_f32_16x16x32_bf16 v[140:143], v[32:35], v[186:189], v[140:143]
	v_mfma_f32_16x16x32_bf16 v[136:139], v[40:43], v[186:189], v[136:139]
	v_mfma_f32_16x16x32_bf16 v[124:127], v[32:35], v[194:197], v[124:127]
	v_mfma_f32_16x16x32_bf16 v[120:123], v[40:43], v[194:197], v[120:123]
	v_mfma_f32_16x16x32_bf16 v[108:111], v[32:35], v[202:205], v[108:111]
	v_mfma_f32_16x16x32_bf16 v[104:107], v[40:43], v[202:205], v[104:107]
	v_mfma_f32_16x16x32_bf16 v[92:95], v[32:35], v[210:213], v[92:95]
	v_mfma_f32_16x16x32_bf16 v[88:91], v[40:43], v[210:213], v[88:91]
	v_mfma_f32_16x16x32_bf16 v[140:143], v[36:39], v[190:193], v[140:143]
	v_mfma_f32_16x16x32_bf16 v[136:139], v[44:47], v[190:193], v[136:139]
	v_mfma_f32_16x16x32_bf16 v[124:127], v[36:39], v[198:201], v[124:127]
	v_mfma_f32_16x16x32_bf16 v[120:123], v[44:47], v[198:201], v[120:123]
	v_mfma_f32_16x16x32_bf16 v[108:111], v[36:39], v[206:209], v[108:111]
	v_mfma_f32_16x16x32_bf16 v[104:107], v[44:47], v[206:209], v[104:107]
	v_mfma_f32_16x16x32_bf16 v[92:95], v[36:39], v[214:217], v[92:95]
	v_mfma_f32_16x16x32_bf16 v[88:91], v[44:47], v[214:217], v[88:91]
	v_mfma_f32_16x16x32_bf16 v[132:135], v[162:165], v[186:189], v[132:135]
	v_mfma_f32_16x16x32_bf16 v[128:131], v[178:181], v[186:189], v[128:131]
	v_mfma_f32_16x16x32_bf16 v[116:119], v[162:165], v[194:197], v[116:119]
	v_mfma_f32_16x16x32_bf16 v[112:115], v[178:181], v[194:197], v[112:115]
	v_mfma_f32_16x16x32_bf16 v[100:103], v[162:165], v[202:205], v[100:103]
	v_mfma_f32_16x16x32_bf16 v[96:99], v[178:181], v[202:205], v[96:99]
	v_mfma_f32_16x16x32_bf16 v[84:87], v[162:165], v[210:213], v[84:87]
	v_mfma_f32_16x16x32_bf16 v[80:83], v[178:181], v[210:213], v[80:83]
	v_mfma_f32_16x16x32_bf16 v[132:135], v[174:177], v[190:193], v[132:135]
	v_mfma_f32_16x16x32_bf16 v[128:131], v[182:185], v[190:193], v[128:131]
	v_mfma_f32_16x16x32_bf16 v[116:119], v[174:177], v[198:201], v[116:119]
	v_mfma_f32_16x16x32_bf16 v[112:115], v[182:185], v[198:201], v[112:115]
	v_mfma_f32_16x16x32_bf16 v[100:103], v[174:177], v[206:209], v[100:103]
	v_mfma_f32_16x16x32_bf16 v[96:99], v[182:185], v[206:209], v[96:99]
	v_mfma_f32_16x16x32_bf16 v[84:87], v[174:177], v[214:217], v[84:87]
	v_mfma_f32_16x16x32_bf16 v[80:83], v[182:185], v[214:217], v[80:83]
	v_mfma_f32_16x16x32_bf16 v[76:79], v[32:35], v[220:223], v[76:79]
	v_mfma_f32_16x16x32_bf16 v[72:75], v[40:43], v[220:223], v[72:75]
	v_mfma_f32_16x16x32_bf16 v[60:63], v[32:35], v[228:231], v[60:63]
	v_mfma_f32_16x16x32_bf16 v[56:59], v[40:43], v[228:231], v[56:59]
	v_mfma_f32_16x16x32_bf16 v[28:31], v[32:35], v[236:239], v[28:31]
	v_mfma_f32_16x16x32_bf16 v[24:27], v[40:43], v[236:239], v[24:27]
	v_mfma_f32_16x16x32_bf16 v[12:15], v[32:35], v[244:247], v[12:15]
	v_mfma_f32_16x16x32_bf16 v[8:11], v[40:43], v[244:247], v[8:11]
	v_mfma_f32_16x16x32_bf16 v[76:79], v[36:39], v[224:227], v[76:79]
	v_mfma_f32_16x16x32_bf16 v[72:75], v[44:47], v[224:227], v[72:75]
	v_mfma_f32_16x16x32_bf16 v[60:63], v[36:39], v[232:235], v[60:63]
	v_mfma_f32_16x16x32_bf16 v[56:59], v[44:47], v[232:235], v[56:59]
	v_mfma_f32_16x16x32_bf16 v[28:31], v[36:39], v[240:243], v[28:31]
	v_mfma_f32_16x16x32_bf16 v[24:27], v[44:47], v[240:243], v[24:27]
	v_mfma_f32_16x16x32_bf16 v[12:15], v[36:39], v[248:251], v[12:15]
	v_mfma_f32_16x16x32_bf16 v[8:11], v[44:47], v[248:251], v[8:11]
	v_mfma_f32_16x16x32_bf16 v[68:71], v[162:165], v[220:223], v[68:71]
	v_mfma_f32_16x16x32_bf16 v[64:67], v[178:181], v[220:223], v[64:67]
	v_mfma_f32_16x16x32_bf16 v[52:55], v[162:165], v[228:231], v[52:55]
	v_mfma_f32_16x16x32_bf16 v[48:51], v[178:181], v[228:231], v[48:51]
	v_mfma_f32_16x16x32_bf16 v[20:23], v[162:165], v[236:239], v[20:23]
	v_mfma_f32_16x16x32_bf16 v[16:19], v[178:181], v[236:239], v[16:19]
	v_mfma_f32_16x16x32_bf16 v[4:7], v[162:165], v[244:247], v[4:7]
	v_mfma_f32_16x16x32_bf16 v[0:3], v[178:181], v[244:247], v[0:3]
	v_mfma_f32_16x16x32_bf16 v[68:71], v[174:177], v[224:227], v[68:71]
	v_mfma_f32_16x16x32_bf16 v[64:67], v[182:185], v[224:227], v[64:67]
	v_mfma_f32_16x16x32_bf16 v[52:55], v[174:177], v[232:235], v[52:55]
	v_mfma_f32_16x16x32_bf16 v[48:51], v[182:185], v[232:235], v[48:51]
	v_mfma_f32_16x16x32_bf16 v[20:23], v[174:177], v[240:243], v[20:23]
	v_mfma_f32_16x16x32_bf16 v[16:19], v[182:185], v[240:243], v[16:19]
	v_mfma_f32_16x16x32_bf16 v[4:7], v[174:177], v[248:251], v[4:7]
	v_mfma_f32_16x16x32_bf16 v[0:3], v[182:185], v[248:251], v[0:3]
	s_waitcnt vmcnt(0)
	s_barrier
	s_add_i32 s56, s56, 2
	s_add_u32 s12, s12, 0x100
	s_addc_u32 s13, s13, 0
	s_add_u32 s54, s54, 0x100
	s_addc_u32 s55, s55, 0
	s_cmp_gt_u32 s56, 29
	s_cbranch_scc0 .LBB0_846

.LBB0_940:
	s_add_u32 s24, s22, 0x100
	s_addc_u32 s25, s23, 0
	s_cmpk_eq_i32 s56, 0x54
	s_cselect_b32 s29, s19, s25
	s_cselect_b32 s28, s18, s24
	s_cselect_b32 s27, s21, s47
	s_cselect_b32 s26, s20, s46
	s_and_b64 vcc, exec, s[12:13]
	s_cbranch_vccz .Lk64_trail_p7
	s_setprio 1
	s_sub_u32 vcc_lo, s46, 0x80
	s_subb_u32 vcc_hi, s47, 0
	s_add_i32 m0, s30, 0x18000
	s_nop 0
	global_load_lds_dwordx4 v130, vcc
	s_add_i32 m0, s30, 0x1a000
	s_nop 0
	global_load_lds_dwordx4 v134, vcc
	s_add_u32 vcc_lo, vcc_lo, 0x58000
	s_addc_u32 vcc_hi, vcc_hi, 0
	s_add_i32 m0, s30, 0x19000
	s_nop 0
	global_load_lds_dwordx4 v130, vcc
	s_add_i32 m0, s30, 0x1b000
	s_nop 0
	global_load_lds_dwordx4 v134, vcc
	s_add_u32 vcc_lo, vcc_lo, 0x108000
	s_addc_u32 vcc_hi, vcc_hi, 0
	s_add_i32 m0, s30, 0x1c000
	s_nop 0
	global_load_lds_dwordx4 v130, vcc
	s_add_i32 m0, s30, 0x1e000
	s_nop 0
	global_load_lds_dwordx4 v134, vcc
	s_add_u32 vcc_lo, vcc_lo, 0x58000
	s_addc_u32 vcc_hi, vcc_hi, 0
	s_add_i32 m0, s30, 0x1d000
	s_nop 0
	global_load_lds_dwordx4 v130, vcc
	s_add_i32 m0, s30, 0x1f000
	s_nop 0
	global_load_lds_dwordx4 v134, vcc
	ds_read_b128 v[144:147], v185 offset:0
	ds_read_b128 v[148:151], v185 offset:1024
	ds_read_b128 v[152:155], v185 offset:2048
	ds_read_b128 v[156:159], v185 offset:3072
	ds_read_b128 v[160:163], v186 offset:0
	ds_read_b128 v[164:167], v186 offset:1024
	ds_read_b128 v[168:171], v186 offset:2048
	ds_read_b128 v[172:175], v186 offset:3072
	ds_read_b128 v[176:179], v187 offset:0
	ds_read_b128 v[190:193], v187 offset:1024
	ds_read_b128 v[194:197], v187 offset:2048
	ds_read_b128 v[198:201], v187 offset:3072
	ds_read_b128 v[202:205], v187 offset:4096
	ds_read_b128 v[206:209], v187 offset:5120
	ds_read_b128 v[210:213], v187 offset:6144
	ds_read_b128 v[214:217], v187 offset:7168
	ds_read_b128 v[220:223], v187 offset:16384
	ds_read_b128 v[224:227], v187 offset:17408
	ds_read_b128 v[228:231], v187 offset:18432
	ds_read_b128 v[232:235], v187 offset:19456
	ds_read_b128 v[236:239], v187 offset:20480
	ds_read_b128 v[240:243], v187 offset:21504
	ds_read_b128 v[244:247], v187 offset:22528
	ds_read_b128 v[248:251], v187 offset:23552
	s_waitcnt lgkmcnt(0)
	s_barrier
	v_mfma_f32_16x16x32_bf16 v[72:75], v[144:147], v[176:179], v[72:75]
	v_mfma_f32_16x16x32_bf16 v[76:79], v[152:155], v[176:179], v[76:79]
	v_mfma_f32_16x16x32_bf16 v[96:99], v[144:147], v[194:197], v[96:99]
	v_mfma_f32_16x16x32_bf16 v[100:103], v[152:155], v[194:197], v[100:103]
	v_mfma_f32_16x16x32_bf16 v[120:123], v[144:147], v[202:205], v[120:123]
	v_mfma_f32_16x16x32_bf16 v[124:127], v[152:155], v[202:205], v[124:127]
	v_mfma_f32_16x16x32_bf16 v[92:95], v[144:147], v[210:213], v[92:95]
	v_mfma_f32_16x16x32_bf16 v[84:87], v[152:155], v[210:213], v[84:87]
	v_mfma_f32_16x16x32_bf16 v[72:75], v[148:151], v[190:193], v[72:75]
	v_mfma_f32_16x16x32_bf16 v[76:79], v[156:159], v[190:193], v[76:79]
	v_mfma_f32_16x16x32_bf16 v[96:99], v[148:151], v[198:201], v[96:99]
	v_mfma_f32_16x16x32_bf16 v[100:103], v[156:159], v[198:201], v[100:103]
	v_mfma_f32_16x16x32_bf16 v[120:123], v[148:151], v[206:209], v[120:123]
	v_mfma_f32_16x16x32_bf16 v[124:127], v[156:159], v[206:209], v[124:127]
	v_mfma_f32_16x16x32_bf16 v[92:95], v[148:151], v[214:217], v[92:95]
	v_mfma_f32_16x16x32_bf16 v[84:87], v[156:159], v[214:217], v[84:87]
	v_mfma_f32_16x16x32_bf16 v[80:83], v[160:163], v[176:179], v[80:83]
	v_mfma_f32_16x16x32_bf16 v[88:91], v[168:171], v[176:179], v[88:91]
	v_mfma_f32_16x16x32_bf16 v[108:111], v[160:163], v[194:197], v[108:111]
	v_mfma_f32_16x16x32_bf16 v[112:115], v[168:171], v[194:197], v[112:115]
	v_mfma_f32_16x16x32_bf16 v[116:119], v[160:163], v[202:205], v[116:119]
	v_mfma_f32_16x16x32_bf16 v[104:107], v[168:171], v[202:205], v[104:107]
	v_mfma_f32_16x16x32_bf16 v[68:71], v[160:163], v[210:213], v[68:71]
	v_mfma_f32_16x16x32_bf16 v[64:67], v[168:171], v[210:213], v[64:67]
	v_mfma_f32_16x16x32_bf16 v[80:83], v[164:167], v[190:193], v[80:83]
	v_mfma_f32_16x16x32_bf16 v[88:91], v[172:175], v[190:193], v[88:91]
	v_mfma_f32_16x16x32_bf16 v[108:111], v[164:167], v[198:201], v[108:111]
	v_mfma_f32_16x16x32_bf16 v[112:115], v[172:175], v[198:201], v[112:115]
	v_mfma_f32_16x16x32_bf16 v[116:119], v[164:167], v[206:209], v[116:119]
	v_mfma_f32_16x16x32_bf16 v[104:107], v[172:175], v[206:209], v[104:107]
	v_mfma_f32_16x16x32_bf16 v[68:71], v[164:167], v[214:217], v[68:71]
	v_mfma_f32_16x16x32_bf16 v[64:67], v[172:175], v[214:217], v[64:67]
	v_mfma_f32_16x16x32_bf16 v[60:63], v[144:147], v[220:223], v[60:63]
	v_mfma_f32_16x16x32_bf16 v[56:59], v[152:155], v[220:223], v[56:59]
	v_mfma_f32_16x16x32_bf16 v[44:47], v[144:147], v[228:231], v[44:47]
	v_mfma_f32_16x16x32_bf16 v[40:43], v[152:155], v[228:231], v[40:43]
	v_mfma_f32_16x16x32_bf16 v[28:31], v[144:147], v[236:239], v[28:31]
	v_mfma_f32_16x16x32_bf16 v[24:27], v[152:155], v[236:239], v[24:27]
	v_mfma_f32_16x16x32_bf16 v[12:15], v[144:147], v[244:247], v[12:15]
	v_mfma_f32_16x16x32_bf16 v[8:11], v[152:155], v[244:247], v[8:11]
	v_mfma_f32_16x16x32_bf16 v[60:63], v[148:151], v[224:227], v[60:63]
	v_mfma_f32_16x16x32_bf16 v[56:59], v[156:159], v[224:227], v[56:59]
	v_mfma_f32_16x16x32_bf16 v[44:47], v[148:151], v[232:235], v[44:47]
	v_mfma_f32_16x16x32_bf16 v[40:43], v[156:159], v[232:235], v[40:43]
	v_mfma_f32_16x16x32_bf16 v[28:31], v[148:151], v[240:243], v[28:31]
	v_mfma_f32_16x16x32_bf16 v[24:27], v[156:159], v[240:243], v[24:27]
	v_mfma_f32_16x16x32_bf16 v[12:15], v[148:151], v[248:251], v[12:15]
	v_mfma_f32_16x16x32_bf16 v[8:11], v[156:159], v[248:251], v[8:11]
	v_mfma_f32_16x16x32_bf16 v[52:55], v[160:163], v[220:223], v[52:55]
	v_mfma_f32_16x16x32_bf16 v[48:51], v[168:171], v[220:223], v[48:51]
	v_mfma_f32_16x16x32_bf16 v[36:39], v[160:163], v[228:231], v[36:39]
	v_mfma_f32_16x16x32_bf16 v[32:35], v[168:171], v[228:231], v[32:35]
	v_mfma_f32_16x16x32_bf16 v[20:23], v[160:163], v[236:239], v[20:23]
	v_mfma_f32_16x16x32_bf16 v[16:19], v[168:171], v[236:239], v[16:19]
	v_mfma_f32_16x16x32_bf16 v[4:7], v[160:163], v[244:247], v[4:7]
	v_mfma_f32_16x16x32_bf16 v[0:3], v[168:171], v[244:247], v[0:3]
	v_mfma_f32_16x16x32_bf16 v[52:55], v[164:167], v[224:227], v[52:55]
	v_mfma_f32_16x16x32_bf16 v[48:51], v[172:175], v[224:227], v[48:51]
	v_mfma_f32_16x16x32_bf16 v[36:39], v[164:167], v[232:235], v[36:39]
	v_mfma_f32_16x16x32_bf16 v[32:35], v[172:175], v[232:235], v[32:35]
	v_mfma_f32_16x16x32_bf16 v[20:23], v[164:167], v[240:243], v[20:23]
	v_mfma_f32_16x16x32_bf16 v[16:19], v[172:175], v[240:243], v[16:19]
	v_mfma_f32_16x16x32_bf16 v[4:7], v[164:167], v[248:251], v[4:7]
	v_mfma_f32_16x16x32_bf16 v[0:3], v[172:175], v[248:251], v[0:3]
	s_waitcnt vmcnt(0)
	s_barrier
	s_add_u32 vcc_lo, s26, 0x0
	s_addc_u32 vcc_hi, s27, 0
	s_add_i32 m0, s30, 0x10000
	s_nop 0
	global_load_lds_dwordx4 v130, vcc
	s_add_i32 m0, s30, 0x12000
	s_nop 0
	global_load_lds_dwordx4 v134, vcc
	s_add_u32 vcc_lo, vcc_lo, 0x58000
	s_addc_u32 vcc_hi, vcc_hi, 0
	s_add_i32 m0, s30, 0x11000
	s_nop 0
	global_load_lds_dwordx4 v130, vcc
	s_add_i32 m0, s30, 0x13000
	s_nop 0
	global_load_lds_dwordx4 v134, vcc
	s_add_u32 vcc_lo, vcc_lo, 0x108000
	s_addc_u32 vcc_hi, vcc_hi, 0
	s_add_i32 m0, s30, 0x14000
	s_nop 0
	global_load_lds_dwordx4 v130, vcc
	s_add_i32 m0, s30, 0x16000
	s_nop 0
	global_load_lds_dwordx4 v134, vcc
	s_add_u32 vcc_lo, vcc_lo, 0x58000
	s_addc_u32 vcc_hi, vcc_hi, 0
	s_add_i32 m0, s30, 0x15000
	s_nop 0
	global_load_lds_dwordx4 v130, vcc
	s_add_i32 m0, s30, 0x17000
	s_nop 0
	global_load_lds_dwordx4 v134, vcc
	ds_read_b128 v[144:147], v185 offset:32768
	ds_read_b128 v[148:151], v185 offset:33792
	ds_read_b128 v[152:155], v185 offset:34816
	ds_read_b128 v[156:159], v185 offset:35840
	ds_read_b128 v[160:163], v186 offset:32768
	ds_read_b128 v[164:167], v186 offset:33792
	ds_read_b128 v[168:171], v186 offset:34816
	ds_read_b128 v[172:175], v186 offset:35840
	ds_read_b128 v[176:179], v187 offset:32768
	ds_read_b128 v[190:193], v187 offset:33792
	ds_read_b128 v[194:197], v187 offset:34816
	ds_read_b128 v[198:201], v187 offset:35840
	ds_read_b128 v[202:205], v187 offset:36864
	ds_read_b128 v[206:209], v187 offset:37888
	ds_read_b128 v[210:213], v187 offset:38912
	ds_read_b128 v[214:217], v187 offset:39936
	ds_read_b128 v[220:223], v187 offset:49152
	ds_read_b128 v[224:227], v187 offset:50176
	ds_read_b128 v[228:231], v187 offset:51200
	ds_read_b128 v[232:235], v187 offset:52224
	ds_read_b128 v[236:239], v187 offset:53248
	ds_read_b128 v[240:243], v187 offset:54272
	ds_read_b128 v[244:247], v187 offset:55296
	ds_read_b128 v[248:251], v187 offset:56320
	s_waitcnt lgkmcnt(0)
	s_barrier
	v_mfma_f32_16x16x32_bf16 v[72:75], v[144:147], v[176:179], v[72:75]
	v_mfma_f32_16x16x32_bf16 v[76:79], v[152:155], v[176:179], v[76:79]
	v_mfma_f32_16x16x32_bf16 v[96:99], v[144:147], v[194:197], v[96:99]
	v_mfma_f32_16x16x32_bf16 v[100:103], v[152:155], v[194:197], v[100:103]
	v_mfma_f32_16x16x32_bf16 v[120:123], v[144:147], v[202:205], v[120:123]
	v_mfma_f32_16x16x32_bf16 v[124:127], v[152:155], v[202:205], v[124:127]
	v_mfma_f32_16x16x32_bf16 v[92:95], v[144:147], v[210:213], v[92:95]
	v_mfma_f32_16x16x32_bf16 v[84:87], v[152:155], v[210:213], v[84:87]
	v_mfma_f32_16x16x32_bf16 v[72:75], v[148:151], v[190:193], v[72:75]
	v_mfma_f32_16x16x32_bf16 v[76:79], v[156:159], v[190:193], v[76:79]
	v_mfma_f32_16x16x32_bf16 v[96:99], v[148:151], v[198:201], v[96:99]
	v_mfma_f32_16x16x32_bf16 v[100:103], v[156:159], v[198:201], v[100:103]
	v_mfma_f32_16x16x32_bf16 v[120:123], v[148:151], v[206:209], v[120:123]
	v_mfma_f32_16x16x32_bf16 v[124:127], v[156:159], v[206:209], v[124:127]
	v_mfma_f32_16x16x32_bf16 v[92:95], v[148:151], v[214:217], v[92:95]
	v_mfma_f32_16x16x32_bf16 v[84:87], v[156:159], v[214:217], v[84:87]
	v_mfma_f32_16x16x32_bf16 v[80:83], v[160:163], v[176:179], v[80:83]
	v_mfma_f32_16x16x32_bf16 v[88:91], v[168:171], v[176:179], v[88:91]
	v_mfma_f32_16x16x32_bf16 v[108:111], v[160:163], v[194:197], v[108:111]
	v_mfma_f32_16x16x32_bf16 v[112:115], v[168:171], v[194:197], v[112:115]
	v_mfma_f32_16x16x32_bf16 v[116:119], v[160:163], v[202:205], v[116:119]
	v_mfma_f32_16x16x32_bf16 v[104:107], v[168:171], v[202:205], v[104:107]
	v_mfma_f32_16x16x32_bf16 v[68:71], v[160:163], v[210:213], v[68:71]
	v_mfma_f32_16x16x32_bf16 v[64:67], v[168:171], v[210:213], v[64:67]
	v_mfma_f32_16x16x32_bf16 v[80:83], v[164:167], v[190:193], v[80:83]
	v_mfma_f32_16x16x32_bf16 v[88:91], v[172:175], v[190:193], v[88:91]
	v_mfma_f32_16x16x32_bf16 v[108:111], v[164:167], v[198:201], v[108:111]
	v_mfma_f32_16x16x32_bf16 v[112:115], v[172:175], v[198:201], v[112:115]
	v_mfma_f32_16x16x32_bf16 v[116:119], v[164:167], v[206:209], v[116:119]
	v_mfma_f32_16x16x32_bf16 v[104:107], v[172:175], v[206:209], v[104:107]
	v_mfma_f32_16x16x32_bf16 v[68:71], v[164:167], v[214:217], v[68:71]
	v_mfma_f32_16x16x32_bf16 v[64:67], v[172:175], v[214:217], v[64:67]
	v_mfma_f32_16x16x32_bf16 v[60:63], v[144:147], v[220:223], v[60:63]
	v_mfma_f32_16x16x32_bf16 v[56:59], v[152:155], v[220:223], v[56:59]
	v_mfma_f32_16x16x32_bf16 v[44:47], v[144:147], v[228:231], v[44:47]
	v_mfma_f32_16x16x32_bf16 v[40:43], v[152:155], v[228:231], v[40:43]
	v_mfma_f32_16x16x32_bf16 v[28:31], v[144:147], v[236:239], v[28:31]
	v_mfma_f32_16x16x32_bf16 v[24:27], v[152:155], v[236:239], v[24:27]
	v_mfma_f32_16x16x32_bf16 v[12:15], v[144:147], v[244:247], v[12:15]
	v_mfma_f32_16x16x32_bf16 v[8:11], v[152:155], v[244:247], v[8:11]
	v_mfma_f32_16x16x32_bf16 v[60:63], v[148:151], v[224:227], v[60:63]
	v_mfma_f32_16x16x32_bf16 v[56:59], v[156:159], v[224:227], v[56:59]
	v_mfma_f32_16x16x32_bf16 v[44:47], v[148:151], v[232:235], v[44:47]
	v_mfma_f32_16x16x32_bf16 v[40:43], v[156:159], v[232:235], v[40:43]
	v_mfma_f32_16x16x32_bf16 v[28:31], v[148:151], v[240:243], v[28:31]
	v_mfma_f32_16x16x32_bf16 v[24:27], v[156:159], v[240:243], v[24:27]
	v_mfma_f32_16x16x32_bf16 v[12:15], v[148:151], v[248:251], v[12:15]
	v_mfma_f32_16x16x32_bf16 v[8:11], v[156:159], v[248:251], v[8:11]
	v_mfma_f32_16x16x32_bf16 v[52:55], v[160:163], v[220:223], v[52:55]
	v_mfma_f32_16x16x32_bf16 v[48:51], v[168:171], v[220:223], v[48:51]
	v_mfma_f32_16x16x32_bf16 v[36:39], v[160:163], v[228:231], v[36:39]
	v_mfma_f32_16x16x32_bf16 v[32:35], v[168:171], v[228:231], v[32:35]
	v_mfma_f32_16x16x32_bf16 v[20:23], v[160:163], v[236:239], v[20:23]
	v_mfma_f32_16x16x32_bf16 v[16:19], v[168:171], v[236:239], v[16:19]
	v_mfma_f32_16x16x32_bf16 v[4:7], v[160:163], v[244:247], v[4:7]
	v_mfma_f32_16x16x32_bf16 v[0:3], v[168:171], v[244:247], v[0:3]
	v_mfma_f32_16x16x32_bf16 v[52:55], v[164:167], v[224:227], v[52:55]
	v_mfma_f32_16x16x32_bf16 v[48:51], v[172:175], v[224:227], v[48:51]
	v_mfma_f32_16x16x32_bf16 v[36:39], v[164:167], v[232:235], v[36:39]
	v_mfma_f32_16x16x32_bf16 v[32:35], v[172:175], v[232:235], v[32:35]
	v_mfma_f32_16x16x32_bf16 v[20:23], v[164:167], v[240:243], v[20:23]
	v_mfma_f32_16x16x32_bf16 v[16:19], v[172:175], v[240:243], v[16:19]
	v_mfma_f32_16x16x32_bf16 v[4:7], v[164:167], v[248:251], v[4:7]
	v_mfma_f32_16x16x32_bf16 v[0:3], v[172:175], v[248:251], v[0:3]
	s_waitcnt vmcnt(0)
	s_barrier
	s_add_i32 s56, s56, 2
	s_add_u32 s46, s46, 0x100
	s_addc_u32 s47, s47, 0
	s_cmpk_gt_u32 s56, 0x55
	s_mov_b64 s[22:23], s[24:25]
	s_cbranch_scc0 .LBB0_940
	s_branch .Lk64_done_p7
.Lk64_trail_p7:
	s_add_u32 vcc_lo, s22, 0x80
	s_addc_u32 vcc_hi, s23, 0
	s_add_i32 m0, s30, 0xa000
	s_nop 0
	global_load_lds_dwordx4 v132, vcc
	s_add_u32 vcc_lo, vcc_lo, 0x58000
	s_addc_u32 vcc_hi, vcc_hi, 0
	s_add_i32 m0, s30, 0x9000
	s_nop 0
	global_load_lds_dwordx4 v128, vcc
	s_add_u32 vcc_lo, vcc_lo, 0x108000
	s_addc_u32 vcc_hi, vcc_hi, 0
	s_add_i32 m0, s30, 0xe000
	s_nop 0
	global_load_lds_dwordx4 v132, vcc
	s_add_u32 vcc_lo, vcc_lo, 0x58000
	s_addc_u32 vcc_hi, vcc_hi, 0
	s_add_i32 m0, s30, 0xd000
	s_nop 0
	global_load_lds_dwordx4 v128, vcc
	s_add_u32 vcc_lo, s28, 0x0
	s_addc_u32 vcc_hi, s29, 0
	s_mov_b32 m0, s30
	s_nop 0
	global_load_lds_dwordx4 v128, vcc
	s_sub_u32 vcc_lo, vcc_lo, 0x58000
	s_subb_u32 vcc_hi, vcc_hi, 0
	s_sub_i32 m0, s30, 0x1000
	s_nop 0
	global_load_lds_dwordx4 v128, vcc
	s_add_u32 vcc_lo, vcc_lo, 0x1b8000
	s_addc_u32 vcc_hi, vcc_hi, 0
	s_add_i32 m0, s30, 0x4000
	s_nop 0
	global_load_lds_dwordx4 v128, vcc
	s_sub_u32 vcc_lo, vcc_lo, 0x58000
	s_subb_u32 vcc_hi, vcc_hi, 0
	s_add_i32 m0, s30, 0x3000
	s_nop 0
	global_load_lds_dwordx4 v128, vcc
	ds_read_b128 v[144:147], v185 offset:0
	ds_read_b128 v[148:151], v185 offset:1024
	ds_read_b128 v[152:155], v185 offset:2048
	ds_read_b128 v[156:159], v185 offset:3072
	ds_read_b128 v[160:163], v186 offset:0
	ds_read_b128 v[164:167], v186 offset:1024
	ds_read_b128 v[168:171], v186 offset:2048
	ds_read_b128 v[172:175], v186 offset:3072
	ds_read_b128 v[176:179], v187 offset:0
	ds_read_b128 v[190:193], v187 offset:1024
	ds_read_b128 v[194:197], v187 offset:2048
	ds_read_b128 v[198:201], v187 offset:3072
	ds_read_b128 v[202:205], v187 offset:4096
	ds_read_b128 v[206:209], v187 offset:5120
	ds_read_b128 v[210:213], v187 offset:6144
	ds_read_b128 v[214:217], v187 offset:7168
	ds_read_b128 v[220:223], v187 offset:16384
	ds_read_b128 v[224:227], v187 offset:17408
	ds_read_b128 v[228:231], v187 offset:18432
	ds_read_b128 v[232:235], v187 offset:19456
	ds_read_b128 v[236:239], v187 offset:20480
	ds_read_b128 v[240:243], v187 offset:21504
	ds_read_b128 v[244:247], v187 offset:22528
	ds_read_b128 v[248:251], v187 offset:23552
	s_waitcnt lgkmcnt(0)
	s_barrier
	v_mfma_f32_16x16x32_bf16 v[72:75], v[144:147], v[176:179], v[72:75]
	v_mfma_f32_16x16x32_bf16 v[76:79], v[152:155], v[176:179], v[76:79]
	v_mfma_f32_16x16x32_bf16 v[96:99], v[144:147], v[194:197], v[96:99]
	v_mfma_f32_16x16x32_bf16 v[100:103], v[152:155], v[194:197], v[100:103]
	v_mfma_f32_16x16x32_bf16 v[120:123], v[144:147], v[202:205], v[120:123]
	v_mfma_f32_16x16x32_bf16 v[124:127], v[152:155], v[202:205], v[124:127]
	v_mfma_f32_16x16x32_bf16 v[92:95], v[144:147], v[210:213], v[92:95]
	v_mfma_f32_16x16x32_bf16 v[84:87], v[152:155], v[210:213], v[84:87]
	v_mfma_f32_16x16x32_bf16 v[72:75], v[148:151], v[190:193], v[72:75]
	v_mfma_f32_16x16x32_bf16 v[76:79], v[156:159], v[190:193], v[76:79]
	v_mfma_f32_16x16x32_bf16 v[96:99], v[148:151], v[198:201], v[96:99]
	v_mfma_f32_16x16x32_bf16 v[100:103], v[156:159], v[198:201], v[100:103]
	v_mfma_f32_16x16x32_bf16 v[120:123], v[148:151], v[206:209], v[120:123]
	v_mfma_f32_16x16x32_bf16 v[124:127], v[156:159], v[206:209], v[124:127]
	v_mfma_f32_16x16x32_bf16 v[92:95], v[148:151], v[214:217], v[92:95]
	v_mfma_f32_16x16x32_bf16 v[84:87], v[156:159], v[214:217], v[84:87]
	v_mfma_f32_16x16x32_bf16 v[80:83], v[160:163], v[176:179], v[80:83]
	v_mfma_f32_16x16x32_bf16 v[88:91], v[168:171], v[176:179], v[88:91]
	v_mfma_f32_16x16x32_bf16 v[108:111], v[160:163], v[194:197], v[108:111]
	v_mfma_f32_16x16x32_bf16 v[112:115], v[168:171], v[194:197], v[112:115]
	v_mfma_f32_16x16x32_bf16 v[116:119], v[160:163], v[202:205], v[116:119]
	v_mfma_f32_16x16x32_bf16 v[104:107], v[168:171], v[202:205], v[104:107]
	v_mfma_f32_16x16x32_bf16 v[68:71], v[160:163], v[210:213], v[68:71]
	v_mfma_f32_16x16x32_bf16 v[64:67], v[168:171], v[210:213], v[64:67]
	v_mfma_f32_16x16x32_bf16 v[80:83], v[164:167], v[190:193], v[80:83]
	v_mfma_f32_16x16x32_bf16 v[88:91], v[172:175], v[190:193], v[88:91]
	v_mfma_f32_16x16x32_bf16 v[108:111], v[164:167], v[198:201], v[108:111]
	v_mfma_f32_16x16x32_bf16 v[112:115], v[172:175], v[198:201], v[112:115]
	v_mfma_f32_16x16x32_bf16 v[116:119], v[164:167], v[206:209], v[116:119]
	v_mfma_f32_16x16x32_bf16 v[104:107], v[172:175], v[206:209], v[104:107]
	v_mfma_f32_16x16x32_bf16 v[68:71], v[164:167], v[214:217], v[68:71]
	v_mfma_f32_16x16x32_bf16 v[64:67], v[172:175], v[214:217], v[64:67]
	v_mfma_f32_16x16x32_bf16 v[60:63], v[144:147], v[220:223], v[60:63]
	v_mfma_f32_16x16x32_bf16 v[56:59], v[152:155], v[220:223], v[56:59]
	v_mfma_f32_16x16x32_bf16 v[44:47], v[144:147], v[228:231], v[44:47]
	v_mfma_f32_16x16x32_bf16 v[40:43], v[152:155], v[228:231], v[40:43]
	v_mfma_f32_16x16x32_bf16 v[28:31], v[144:147], v[236:239], v[28:31]
	v_mfma_f32_16x16x32_bf16 v[24:27], v[152:155], v[236:239], v[24:27]
	v_mfma_f32_16x16x32_bf16 v[12:15], v[144:147], v[244:247], v[12:15]
	v_mfma_f32_16x16x32_bf16 v[8:11], v[152:155], v[244:247], v[8:11]
	v_mfma_f32_16x16x32_bf16 v[60:63], v[148:151], v[224:227], v[60:63]
	v_mfma_f32_16x16x32_bf16 v[56:59], v[156:159], v[224:227], v[56:59]
	v_mfma_f32_16x16x32_bf16 v[44:47], v[148:151], v[232:235], v[44:47]
	v_mfma_f32_16x16x32_bf16 v[40:43], v[156:159], v[232:235], v[40:43]
	v_mfma_f32_16x16x32_bf16 v[28:31], v[148:151], v[240:243], v[28:31]
	v_mfma_f32_16x16x32_bf16 v[24:27], v[156:159], v[240:243], v[24:27]
	v_mfma_f32_16x16x32_bf16 v[12:15], v[148:151], v[248:251], v[12:15]
	v_mfma_f32_16x16x32_bf16 v[8:11], v[156:159], v[248:251], v[8:11]
	v_mfma_f32_16x16x32_bf16 v[52:55], v[160:163], v[220:223], v[52:55]
	v_mfma_f32_16x16x32_bf16 v[48:51], v[168:171], v[220:223], v[48:51]
	v_mfma_f32_16x16x32_bf16 v[36:39], v[160:163], v[228:231], v[36:39]
	v_mfma_f32_16x16x32_bf16 v[32:35], v[168:171], v[228:231], v[32:35]
	v_mfma_f32_16x16x32_bf16 v[20:23], v[160:163], v[236:239], v[20:23]
	v_mfma_f32_16x16x32_bf16 v[16:19], v[168:171], v[236:239], v[16:19]
	v_mfma_f32_16x16x32_bf16 v[4:7], v[160:163], v[244:247], v[4:7]
	v_mfma_f32_16x16x32_bf16 v[0:3], v[168:171], v[244:247], v[0:3]
	v_mfma_f32_16x16x32_bf16 v[52:55], v[164:167], v[224:227], v[52:55]
	v_mfma_f32_16x16x32_bf16 v[48:51], v[172:175], v[224:227], v[48:51]
	v_mfma_f32_16x16x32_bf16 v[36:39], v[164:167], v[232:235], v[36:39]
	v_mfma_f32_16x16x32_bf16 v[32:35], v[172:175], v[232:235], v[32:35]
	v_mfma_f32_16x16x32_bf16 v[20:23], v[164:167], v[240:243], v[20:23]
	v_mfma_f32_16x16x32_bf16 v[16:19], v[172:175], v[240:243], v[16:19]
	v_mfma_f32_16x16x32_bf16 v[4:7], v[164:167], v[248:251], v[4:7]
	v_mfma_f32_16x16x32_bf16 v[0:3], v[172:175], v[248:251], v[0:3]
	s_waitcnt vmcnt(0)
	s_barrier
	s_add_u32 vcc_lo, s28, 0x0
	s_addc_u32 vcc_hi, s29, 0
	s_add_i32 m0, s30, 0x2000
	s_nop 0
	global_load_lds_dwordx4 v132, vcc
	s_add_u32 vcc_lo, vcc_lo, 0x58000
	s_addc_u32 vcc_hi, vcc_hi, 0
	s_add_i32 m0, s30, 0x1000
	s_nop 0
	global_load_lds_dwordx4 v128, vcc
	s_add_u32 vcc_lo, vcc_lo, 0x108000
	s_addc_u32 vcc_hi, vcc_hi, 0
	s_add_i32 m0, s30, 0x6000
	s_nop 0
	global_load_lds_dwordx4 v132, vcc
	s_add_u32 vcc_lo, vcc_lo, 0x58000
	s_addc_u32 vcc_hi, vcc_hi, 0
	s_add_i32 m0, s30, 0x5000
	s_nop 0
	global_load_lds_dwordx4 v128, vcc
	s_add_u32 vcc_lo, s28, 0x80
	s_addc_u32 vcc_hi, s29, 0
	s_add_i32 m0, s30, 0x8000
	s_nop 0
	global_load_lds_dwordx4 v128, vcc
	s_sub_u32 vcc_lo, vcc_lo, 0x58000
	s_subb_u32 vcc_hi, vcc_hi, 0
	s_add_i32 m0, s30, 0x7000
	s_nop 0
	global_load_lds_dwordx4 v128, vcc
	s_add_u32 vcc_lo, vcc_lo, 0x1b8000
	s_addc_u32 vcc_hi, vcc_hi, 0
	s_add_i32 m0, s30, 0xc000
	s_nop 0
	global_load_lds_dwordx4 v128, vcc
	s_sub_u32 vcc_lo, vcc_lo, 0x58000
	s_subb_u32 vcc_hi, vcc_hi, 0
	s_add_i32 m0, s30, 0xb000
	s_nop 0
	global_load_lds_dwordx4 v128, vcc
	ds_read_b128 v[144:147], v185 offset:32768
	ds_read_b128 v[148:151], v185 offset:33792
	ds_read_b128 v[152:155], v185 offset:34816
	ds_read_b128 v[156:159], v185 offset:35840
	ds_read_b128 v[160:163], v186 offset:32768
	ds_read_b128 v[164:167], v186 offset:33792
	ds_read_b128 v[168:171], v186 offset:34816
	ds_read_b128 v[172:175], v186 offset:35840
	ds_read_b128 v[176:179], v187 offset:32768
	ds_read_b128 v[190:193], v187 offset:33792
	ds_read_b128 v[194:197], v187 offset:34816
	ds_read_b128 v[198:201], v187 offset:35840
	ds_read_b128 v[202:205], v187 offset:36864
	ds_read_b128 v[206:209], v187 offset:37888
	ds_read_b128 v[210:213], v187 offset:38912
	ds_read_b128 v[214:217], v187 offset:39936
	ds_read_b128 v[220:223], v187 offset:49152
	ds_read_b128 v[224:227], v187 offset:50176
	ds_read_b128 v[228:231], v187 offset:51200
	ds_read_b128 v[232:235], v187 offset:52224
	ds_read_b128 v[236:239], v187 offset:53248
	ds_read_b128 v[240:243], v187 offset:54272
	ds_read_b128 v[244:247], v187 offset:55296
	ds_read_b128 v[248:251], v187 offset:56320
	s_waitcnt lgkmcnt(0)
	s_barrier
	v_mfma_f32_16x16x32_bf16 v[72:75], v[144:147], v[176:179], v[72:75]
	v_mfma_f32_16x16x32_bf16 v[76:79], v[152:155], v[176:179], v[76:79]
	v_mfma_f32_16x16x32_bf16 v[96:99], v[144:147], v[194:197], v[96:99]
	v_mfma_f32_16x16x32_bf16 v[100:103], v[152:155], v[194:197], v[100:103]
	v_mfma_f32_16x16x32_bf16 v[120:123], v[144:147], v[202:205], v[120:123]
	v_mfma_f32_16x16x32_bf16 v[124:127], v[152:155], v[202:205], v[124:127]
	v_mfma_f32_16x16x32_bf16 v[92:95], v[144:147], v[210:213], v[92:95]
	v_mfma_f32_16x16x32_bf16 v[84:87], v[152:155], v[210:213], v[84:87]
	v_mfma_f32_16x16x32_bf16 v[72:75], v[148:151], v[190:193], v[72:75]
	v_mfma_f32_16x16x32_bf16 v[76:79], v[156:159], v[190:193], v[76:79]
	v_mfma_f32_16x16x32_bf16 v[96:99], v[148:151], v[198:201], v[96:99]
	v_mfma_f32_16x16x32_bf16 v[100:103], v[156:159], v[198:201], v[100:103]
	v_mfma_f32_16x16x32_bf16 v[120:123], v[148:151], v[206:209], v[120:123]
	v_mfma_f32_16x16x32_bf16 v[124:127], v[156:159], v[206:209], v[124:127]
	v_mfma_f32_16x16x32_bf16 v[92:95], v[148:151], v[214:217], v[92:95]
	v_mfma_f32_16x16x32_bf16 v[84:87], v[156:159], v[214:217], v[84:87]
	v_mfma_f32_16x16x32_bf16 v[80:83], v[160:163], v[176:179], v[80:83]
	v_mfma_f32_16x16x32_bf16 v[88:91], v[168:171], v[176:179], v[88:91]
	v_mfma_f32_16x16x32_bf16 v[108:111], v[160:163], v[194:197], v[108:111]
	v_mfma_f32_16x16x32_bf16 v[112:115], v[168:171], v[194:197], v[112:115]
	v_mfma_f32_16x16x32_bf16 v[116:119], v[160:163], v[202:205], v[116:119]
	v_mfma_f32_16x16x32_bf16 v[104:107], v[168:171], v[202:205], v[104:107]
	v_mfma_f32_16x16x32_bf16 v[68:71], v[160:163], v[210:213], v[68:71]
	v_mfma_f32_16x16x32_bf16 v[64:67], v[168:171], v[210:213], v[64:67]
	v_mfma_f32_16x16x32_bf16 v[80:83], v[164:167], v[190:193], v[80:83]
	v_mfma_f32_16x16x32_bf16 v[88:91], v[172:175], v[190:193], v[88:91]
	v_mfma_f32_16x16x32_bf16 v[108:111], v[164:167], v[198:201], v[108:111]
	v_mfma_f32_16x16x32_bf16 v[112:115], v[172:175], v[198:201], v[112:115]
	v_mfma_f32_16x16x32_bf16 v[116:119], v[164:167], v[206:209], v[116:119]
	v_mfma_f32_16x16x32_bf16 v[104:107], v[172:175], v[206:209], v[104:107]
	v_mfma_f32_16x16x32_bf16 v[68:71], v[164:167], v[214:217], v[68:71]
	v_mfma_f32_16x16x32_bf16 v[64:67], v[172:175], v[214:217], v[64:67]
	v_mfma_f32_16x16x32_bf16 v[60:63], v[144:147], v[220:223], v[60:63]
	v_mfma_f32_16x16x32_bf16 v[56:59], v[152:155], v[220:223], v[56:59]
	v_mfma_f32_16x16x32_bf16 v[44:47], v[144:147], v[228:231], v[44:47]
	v_mfma_f32_16x16x32_bf16 v[40:43], v[152:155], v[228:231], v[40:43]
	v_mfma_f32_16x16x32_bf16 v[28:31], v[144:147], v[236:239], v[28:31]
	v_mfma_f32_16x16x32_bf16 v[24:27], v[152:155], v[236:239], v[24:27]
	v_mfma_f32_16x16x32_bf16 v[12:15], v[144:147], v[244:247], v[12:15]
	v_mfma_f32_16x16x32_bf16 v[8:11], v[152:155], v[244:247], v[8:11]
	v_mfma_f32_16x16x32_bf16 v[60:63], v[148:151], v[224:227], v[60:63]
	v_mfma_f32_16x16x32_bf16 v[56:59], v[156:159], v[224:227], v[56:59]
	v_mfma_f32_16x16x32_bf16 v[44:47], v[148:151], v[232:235], v[44:47]
	v_mfma_f32_16x16x32_bf16 v[40:43], v[156:159], v[232:235], v[40:43]
	v_mfma_f32_16x16x32_bf16 v[28:31], v[148:151], v[240:243], v[28:31]
	v_mfma_f32_16x16x32_bf16 v[24:27], v[156:159], v[240:243], v[24:27]
	v_mfma_f32_16x16x32_bf16 v[12:15], v[148:151], v[248:251], v[12:15]
	v_mfma_f32_16x16x32_bf16 v[8:11], v[156:159], v[248:251], v[8:11]
	v_mfma_f32_16x16x32_bf16 v[52:55], v[160:163], v[220:223], v[52:55]
	v_mfma_f32_16x16x32_bf16 v[48:51], v[168:171], v[220:223], v[48:51]
	v_mfma_f32_16x16x32_bf16 v[36:39], v[160:163], v[228:231], v[36:39]
	v_mfma_f32_16x16x32_bf16 v[32:35], v[168:171], v[228:231], v[32:35]
	v_mfma_f32_16x16x32_bf16 v[20:23], v[160:163], v[236:239], v[20:23]
	v_mfma_f32_16x16x32_bf16 v[16:19], v[168:171], v[236:239], v[16:19]
	v_mfma_f32_16x16x32_bf16 v[4:7], v[160:163], v[244:247], v[4:7]
	v_mfma_f32_16x16x32_bf16 v[0:3], v[168:171], v[244:247], v[0:3]
	v_mfma_f32_16x16x32_bf16 v[52:55], v[164:167], v[224:227], v[52:55]
	v_mfma_f32_16x16x32_bf16 v[48:51], v[172:175], v[224:227], v[48:51]
	v_mfma_f32_16x16x32_bf16 v[36:39], v[164:167], v[232:235], v[36:39]
	v_mfma_f32_16x16x32_bf16 v[32:35], v[172:175], v[232:235], v[32:35]
	v_mfma_f32_16x16x32_bf16 v[20:23], v[164:167], v[240:243], v[20:23]
	v_mfma_f32_16x16x32_bf16 v[16:19], v[172:175], v[240:243], v[16:19]
	v_mfma_f32_16x16x32_bf16 v[4:7], v[164:167], v[248:251], v[4:7]
	v_mfma_f32_16x16x32_bf16 v[0:3], v[172:175], v[248:251], v[0:3]
	s_waitcnt vmcnt(0)
	s_barrier
	s_add_i32 s56, s56, 2
	s_add_u32 s46, s46, 0x100
	s_addc_u32 s47, s47, 0
	s_cmpk_gt_u32 s56, 0x55
	s_mov_b64 s[22:23], s[24:25]
	s_cbranch_scc0 .LBB0_940
